# RWKV: first two blocks peeled (no startup checks in the steady loop), needed-landed value kept incrementally as the loop counter
# speedup vs baseline: 1.0214x; 1.0014x over previous
; template <int DIR>
; DEVINL void rwkv_scan_dir(const Params& p, int task, int lane, int wave) {
;   const int b = (task >> 8) & 1, head = (task >> 4) & 15, rg = task & 15;
;   const int seg = lane & 15, rl = lane >> 4, row = rg * 4 + rl;
;   constexpr int DIST = 24;
;   constexpr int WOFS = DIR ? 8 : 0;
;   const char* recbase = p.ws + O_REC + ((long)(b * 16 + head) * 4096) * 1024 + lane * 16;
;   const unsigned ring_lds = (unsigned)(unsigned long)(__attribute__((address_space(3))) char*)(dynsmem + wave * 32768);
;   const unsigned ring_u = __builtin_amdgcn_readfirstlane(ring_lds);
;   const unsigned a_seg = ring_lds + seg * 64;
;   const unsigned a_v = ring_lds + (row >> 2) * 64 + 48 + (row & 3) * 2;
;   u16* yo = (u16*)(p.ws + (DIR ? O_YB : O_YSUM)) + ((long)b * 4096) * 1024 + head * 64 + row;
;   float s0 = 0.f, s1 = 0.f, s2 = 0.f, s3 = 0.f;
;   float ykeep = 0.f;
;   const char* recdir = recbase + (DIR ? (long)4095 * 1024 : 0);
.Lrw_task:
	s_cmp_ge_u32 s7, 0x400
	s_cbranch_scc1 .Lrw_done
	s_and_b32 s24, s7, 15
	s_bfe_u32 s26, s7, 0x40004
	s_bfe_u32 s32, s7, 0x10008
	s_lshr_b32 s36, s7, 9
	s_lshl_b32 s3, s32, 4
	s_add_u32 s3, s3, s26
	s_lshl_b32 s3, s3, 22
	s_add_u32 s10, s92, s3
	s_addc_u32 s11, s93, 0
	s_add_u32 s10, s10, 0xf400000
	s_addc_u32 s11, s11, 0
	s_lshl_b32 s3, s32, 23
	s_lshl_b32 s37, s26, 7
	s_add_u32 s3, s3, s37
	s_add_u32 s12, s92, s3
	s_addc_u32 s13, s93, 0
	s_lshl_b32 s3, s24, 3
	v_lshl_add_u32 v8, v4, 1, s3
	s_lshl_b32 s37, s24, 4
	s_lshl_b32 s39, s6, 12
	s_cmp_lg_u32 s36, 0
	s_cbranch_scc1 .Lrw_bwd
	s_add_u32 s12, s12, 0x2000000
	s_addc_u32 s13, s13, 0
	v_lshl_add_u32 v8, v3, 11, v8
	s_add_u32 s10, s10, s39
	s_addc_u32 s11, s11, 0
	s_mov_b32 s40, s39
	s_mov_b32 s41, 0
	v_lshlrev_b32_e32 v6, 4, v3
	s_add_u32 s3, s37, 0x300
	v_lshl_add_u32 v7, v4, 1, s3
	s_add_u32 s41, s40, s41
	s_and_b32 s41, s41, 0x1ffff
	s_add_u32 m0, s41, 16
	s_nop 0
	global_load_lds_dwordx4 v5, s[10:11] offset:0
	global_load_lds_dwordx4 v5, s[10:11] offset:1024
	global_load_lds_dwordx4 v5, s[10:11] offset:2048
	global_load_lds_dwordx4 v5, s[10:11] offset:3072
	s_add_u32 s10, s10, 0x4000
	s_addc_u32 s11, s11, 0
	s_add_u32 s41, s41, 0x4000
	s_and_b32 s41, s41, 0x1ffff
	s_add_u32 m0, s41, 16
	s_nop 0
	global_load_lds_dwordx4 v5, s[10:11] offset:0
	global_load_lds_dwordx4 v5, s[10:11] offset:1024
	global_load_lds_dwordx4 v5, s[10:11] offset:2048
	global_load_lds_dwordx4 v5, s[10:11] offset:3072
	s_add_u32 s10, s10, 0x4000
	s_addc_u32 s11, s11, 0
	s_add_u32 s41, s41, 0x4000
	s_and_b32 s41, s41, 0x1ffff
	s_add_u32 m0, s41, 16
	s_nop 0
	global_load_lds_dwordx4 v5, s[10:11] offset:0
	global_load_lds_dwordx4 v5, s[10:11] offset:1024
	global_load_lds_dwordx4 v5, s[10:11] offset:2048
	global_load_lds_dwordx4 v5, s[10:11] offset:3072
	s_add_u32 s10, s10, 0x4000
	s_addc_u32 s11, s11, 0
	s_add_u32 s41, s41, 0x4000
	s_and_b32 s41, s41, 0x1ffff
	s_waitcnt vmcnt(0)
	v_mov_b32_e32 v10, 0
	v_mov_b32_e32 v11, 0
	v_mov_b32_e32 v12, 0
	v_mov_b32_e32 v13, 0
	s_add_u32 s43, s15, 2
	s_add_u32 s45, s43, 0x100
	s_add_u32 s3, s15, 2
	v_mov_b32_e32 v69, s3
	ds_write_b32 v23, v69
	ds_read_b128 v[100:103], v9
	s_waitcnt lgkmcnt(0)
	v_min3_u32 v100, v100, v101, v102
	v_min_u32_e32 v100, v100, v103
	s_nop 0
	v_readfirstlane_b32 s24, v100
	s_nop 0
	s_cmp_ge_u32 s24, s43
	s_cbranch_scc0 .Lrw_slow_d0p
.Lrw_ready_d0p:
	ds_read_b64 v[24:25], v6 offset:16
	ds_read_b128 v[26:29], v6 offset:272
	ds_read_b128 v[30:33], v6 offset:528
	ds_read_u16 v34, v7 offset:16
	ds_read_b64 v[36:37], v6 offset:1040
	ds_read_b128 v[38:41], v6 offset:1296
	ds_read_b128 v[42:45], v6 offset:1552
	ds_read_u16 v46, v7 offset:1040
	s_waitcnt lgkmcnt(0)
	s_waitcnt vmcnt(0)
	v_add_u32_e32 v69, 1, v69
	ds_write_b32 v23, v69
	v_min3_u32 v100, v100, v101, v102
	v_min_u32_e32 v100, v100, v103
	s_nop 0
	v_readfirstlane_b32 s24, v100
	s_nop 0
	s_cmp_ge_u32 s24, s43
	s_cbranch_scc0 .Lrw_slow_d0b0
.Lrw_ready_d0b0:
	s_add_u32 m0, s41, 16
	s_nop 0
	global_load_lds_dwordx4 v5, s[10:11] offset:0
	global_load_lds_dwordx4 v5, s[10:11] offset:1024
	global_load_lds_dwordx4 v5, s[10:11] offset:2048
	global_load_lds_dwordx4 v5, s[10:11] offset:3072
	s_add_u32 s10, s10, 0x4000
	s_addc_u32 s11, s11, 0
	s_add_u32 s41, s41, 0x4000
	s_and_b32 s41, s41, 0x1ffff
	ds_read_b64 v[72:73], v6 offset:2064
	ds_read_b128 v[74:77], v6 offset:2320
	ds_read_b128 v[78:81], v6 offset:2576
	ds_read_u16 v82, v7 offset:2064
	v_fma_mix_f32 v14, v10, v26, 0 op_sel:[0,0,0] op_sel_hi:[0,1,0]
	v_fma_mix_f32 v63, v10, v92, 0 op_sel:[0,0,0] op_sel_hi:[0,1,0]
	v_fma_mix_f32 v14, v11, v26, v14 op_sel:[0,1,0] op_sel_hi:[0,1,0]
	v_fma_mix_f32 v63, v11, v92, v63 op_sel:[0,1,0] op_sel_hi:[0,1,0]
	v_fma_mix_f32 v14, v12, v27, v14 op_sel:[0,0,0] op_sel_hi:[0,1,0]
	v_fma_mix_f32 v63, v12, v93, v63 op_sel:[0,0,0] op_sel_hi:[0,1,0]
	v_fma_mix_f32 v14, v13, v27, v14 op_sel:[0,1,0] op_sel_hi:[0,1,0]
	v_fma_mix_f32 v16, v10, v24, 0 op_sel:[0,0,0] op_sel_hi:[0,1,0]
	v_fma_mix_f32 v17, v11, v24, 0 op_sel:[0,1,0] op_sel_hi:[0,1,0]
	v_add_f32_dpp v20, v14, v14 quad_perm:[1,0,3,2] row_mask:0xf bank_mask:0xf bound_ctrl:1
	v_fma_mix_f32 v63, v13, v93, v63 op_sel:[0,1,0] op_sel_hi:[0,1,0]
	v_fma_mix_f32 v18, v12, v25, 0 op_sel:[0,0,0] op_sel_hi:[0,1,0]
	v_add_f32_dpp v20, v20, v20 quad_perm:[2,3,0,1] row_mask:0xf bank_mask:0xf bound_ctrl:1
	v_fma_mix_f32 v19, v13, v25, 0 op_sel:[0,1,0] op_sel_hi:[0,1,0]
	v_fma_mix_f32 v16, v34, v30, v16 op_sel:[0,0,0] op_sel_hi:[1,1,0]
	v_add_f32_dpp v20, v20, v20 row_half_mirror row_mask:0xf bank_mask:0xf bound_ctrl:1
	v_fma_mix_f32 v17, v34, v30, v17 op_sel:[0,1,0] op_sel_hi:[1,1,0]
	v_fma_mix_f32 v18, v34, v31, v18 op_sel:[0,0,0] op_sel_hi:[1,1,0]
	v_add_f32_dpp v20, v20, v20 row_mirror row_mask:0xf bank_mask:0xf bound_ctrl:1
	v_fma_mix_f32 v19, v34, v31, v19 op_sel:[0,1,0] op_sel_hi:[1,1,0]
	v_fma_mix_f32 v10, v20, v28, v16 op_sel:[0,0,0] op_sel_hi:[0,1,0]
	v_fma_mix_f32 v11, v20, v28, v17 op_sel:[0,1,0] op_sel_hi:[0,1,0]
	v_fma_mix_f32 v12, v20, v29, v18 op_sel:[0,0,0] op_sel_hi:[0,1,0]
	v_fma_mix_f32 v13, v20, v29, v19 op_sel:[0,1,0] op_sel_hi:[0,1,0]
	s_waitcnt lgkmcnt(4)
	ds_read_b64 v[84:85], v6 offset:3088
	ds_read_b128 v[86:89], v6 offset:3344
	ds_read_b128 v[90:93], v6 offset:3600
	ds_read_u16 v94, v7 offset:3088
	v_fma_mix_f32 v14, v10, v38, 0 op_sel:[0,0,0] op_sel_hi:[0,1,0]
	v_fma_mix_f32 v48, v10, v32, 0 op_sel:[0,0,0] op_sel_hi:[0,1,0]
	v_fma_mix_f32 v14, v11, v38, v14 op_sel:[0,1,0] op_sel_hi:[0,1,0]
	v_fma_mix_f32 v48, v11, v32, v48 op_sel:[0,1,0] op_sel_hi:[0,1,0]
	v_fma_mix_f32 v14, v12, v39, v14 op_sel:[0,0,0] op_sel_hi:[0,1,0]
	v_fma_mix_f32 v48, v12, v33, v48 op_sel:[0,0,0] op_sel_hi:[0,1,0]
	v_fma_mix_f32 v14, v13, v39, v14 op_sel:[0,1,0] op_sel_hi:[0,1,0]
	v_fma_mix_f32 v16, v10, v36, 0 op_sel:[0,0,0] op_sel_hi:[0,1,0]
	v_fma_mix_f32 v17, v11, v36, 0 op_sel:[0,1,0] op_sel_hi:[0,1,0]
	v_add_f32_dpp v20, v14, v14 quad_perm:[1,0,3,2] row_mask:0xf bank_mask:0xf bound_ctrl:1
	v_fma_mix_f32 v48, v13, v33, v48 op_sel:[0,1,0] op_sel_hi:[0,1,0]
	v_fma_mix_f32 v18, v12, v37, 0 op_sel:[0,0,0] op_sel_hi:[0,1,0]
	v_add_f32_dpp v20, v20, v20 quad_perm:[2,3,0,1] row_mask:0xf bank_mask:0xf bound_ctrl:1
	v_fma_mix_f32 v19, v13, v37, 0 op_sel:[0,1,0] op_sel_hi:[0,1,0]
	v_fma_mix_f32 v16, v46, v42, v16 op_sel:[0,0,0] op_sel_hi:[1,1,0]
	v_add_f32_dpp v20, v20, v20 row_half_mirror row_mask:0xf bank_mask:0xf bound_ctrl:1
	v_fma_mix_f32 v17, v46, v42, v17 op_sel:[0,1,0] op_sel_hi:[1,1,0]
	v_fma_mix_f32 v18, v46, v43, v18 op_sel:[0,0,0] op_sel_hi:[1,1,0]
	v_add_f32_dpp v20, v20, v20 row_mirror row_mask:0xf bank_mask:0xf bound_ctrl:1
	v_fma_mix_f32 v19, v46, v43, v19 op_sel:[0,1,0] op_sel_hi:[1,1,0]
	v_fma_mix_f32 v10, v20, v40, v16 op_sel:[0,0,0] op_sel_hi:[0,1,0]
	v_fma_mix_f32 v11, v20, v40, v17 op_sel:[0,1,0] op_sel_hi:[0,1,0]
	v_fma_mix_f32 v12, v20, v41, v18 op_sel:[0,0,0] op_sel_hi:[0,1,0]
	v_fma_mix_f32 v13, v20, v41, v19 op_sel:[0,1,0] op_sel_hi:[0,1,0]
	s_waitcnt lgkmcnt(4)
	ds_read_b64 v[24:25], v6 offset:4112
	ds_read_b128 v[26:29], v6 offset:4368
	ds_read_b128 v[30:33], v6 offset:4624
	ds_read_u16 v34, v7 offset:4112
	v_fma_mix_f32 v14, v10, v74, 0 op_sel:[0,0,0] op_sel_hi:[0,1,0]
	v_fma_mix_f32 v49, v10, v44, 0 op_sel:[0,0,0] op_sel_hi:[0,1,0]
	v_fma_mix_f32 v14, v11, v74, v14 op_sel:[0,1,0] op_sel_hi:[0,1,0]
	v_fma_mix_f32 v49, v11, v44, v49 op_sel:[0,1,0] op_sel_hi:[0,1,0]
	v_fma_mix_f32 v14, v12, v75, v14 op_sel:[0,0,0] op_sel_hi:[0,1,0]
	v_fma_mix_f32 v49, v12, v45, v49 op_sel:[0,0,0] op_sel_hi:[0,1,0]
	v_fma_mix_f32 v14, v13, v75, v14 op_sel:[0,1,0] op_sel_hi:[0,1,0]
	v_fma_mix_f32 v16, v10, v72, 0 op_sel:[0,0,0] op_sel_hi:[0,1,0]
	v_fma_mix_f32 v17, v11, v72, 0 op_sel:[0,1,0] op_sel_hi:[0,1,0]
	v_add_f32_dpp v20, v14, v14 quad_perm:[1,0,3,2] row_mask:0xf bank_mask:0xf bound_ctrl:1
	v_fma_mix_f32 v49, v13, v45, v49 op_sel:[0,1,0] op_sel_hi:[0,1,0]
	v_fma_mix_f32 v18, v12, v73, 0 op_sel:[0,0,0] op_sel_hi:[0,1,0]
	v_add_f32_dpp v20, v20, v20 quad_perm:[2,3,0,1] row_mask:0xf bank_mask:0xf bound_ctrl:1
	v_fma_mix_f32 v19, v13, v73, 0 op_sel:[0,1,0] op_sel_hi:[0,1,0]
	v_fma_mix_f32 v16, v82, v78, v16 op_sel:[0,0,0] op_sel_hi:[1,1,0]
	v_add_f32_dpp v20, v20, v20 row_half_mirror row_mask:0xf bank_mask:0xf bound_ctrl:1
	v_fma_mix_f32 v17, v82, v78, v17 op_sel:[0,1,0] op_sel_hi:[1,1,0]
	v_fma_mix_f32 v18, v82, v79, v18 op_sel:[0,0,0] op_sel_hi:[1,1,0]
	v_add_f32_dpp v20, v20, v20 row_mirror row_mask:0xf bank_mask:0xf bound_ctrl:1
	v_fma_mix_f32 v19, v82, v79, v19 op_sel:[0,1,0] op_sel_hi:[1,1,0]
	v_fma_mix_f32 v10, v20, v76, v16 op_sel:[0,0,0] op_sel_hi:[0,1,0]
	v_fma_mix_f32 v11, v20, v76, v17 op_sel:[0,1,0] op_sel_hi:[0,1,0]
	v_fma_mix_f32 v12, v20, v77, v18 op_sel:[0,0,0] op_sel_hi:[0,1,0]
	v_fma_mix_f32 v13, v20, v77, v19 op_sel:[0,1,0] op_sel_hi:[0,1,0]
	s_waitcnt lgkmcnt(4)
	ds_read_b64 v[36:37], v6 offset:5136
	ds_read_b128 v[38:41], v6 offset:5392
	ds_read_b128 v[42:45], v6 offset:5648
	ds_read_u16 v46, v7 offset:5136
	v_fma_mix_f32 v14, v10, v86, 0 op_sel:[0,0,0] op_sel_hi:[0,1,0]
	v_fma_mix_f32 v50, v10, v80, 0 op_sel:[0,0,0] op_sel_hi:[0,1,0]
	v_fma_mix_f32 v14, v11, v86, v14 op_sel:[0,1,0] op_sel_hi:[0,1,0]
	v_fma_mix_f32 v50, v11, v80, v50 op_sel:[0,1,0] op_sel_hi:[0,1,0]
	v_fma_mix_f32 v14, v12, v87, v14 op_sel:[0,0,0] op_sel_hi:[0,1,0]
	v_fma_mix_f32 v50, v12, v81, v50 op_sel:[0,0,0] op_sel_hi:[0,1,0]
	v_fma_mix_f32 v14, v13, v87, v14 op_sel:[0,1,0] op_sel_hi:[0,1,0]
	v_fma_mix_f32 v16, v10, v84, 0 op_sel:[0,0,0] op_sel_hi:[0,1,0]
	v_fma_mix_f32 v17, v11, v84, 0 op_sel:[0,1,0] op_sel_hi:[0,1,0]
	v_add_f32_dpp v20, v14, v14 quad_perm:[1,0,3,2] row_mask:0xf bank_mask:0xf bound_ctrl:1
	v_fma_mix_f32 v50, v13, v81, v50 op_sel:[0,1,0] op_sel_hi:[0,1,0]
	v_fma_mix_f32 v18, v12, v85, 0 op_sel:[0,0,0] op_sel_hi:[0,1,0]
	v_add_f32_dpp v20, v20, v20 quad_perm:[2,3,0,1] row_mask:0xf bank_mask:0xf bound_ctrl:1
	v_fma_mix_f32 v19, v13, v85, 0 op_sel:[0,1,0] op_sel_hi:[0,1,0]
	v_fma_mix_f32 v16, v94, v90, v16 op_sel:[0,0,0] op_sel_hi:[1,1,0]
	v_add_f32_dpp v20, v20, v20 row_half_mirror row_mask:0xf bank_mask:0xf bound_ctrl:1
	v_fma_mix_f32 v17, v94, v90, v17 op_sel:[0,1,0] op_sel_hi:[1,1,0]
	v_fma_mix_f32 v18, v94, v91, v18 op_sel:[0,0,0] op_sel_hi:[1,1,0]
	v_add_f32_dpp v20, v20, v20 row_mirror row_mask:0xf bank_mask:0xf bound_ctrl:1
	v_fma_mix_f32 v19, v94, v91, v19 op_sel:[0,1,0] op_sel_hi:[1,1,0]
	v_fma_mix_f32 v10, v20, v88, v16 op_sel:[0,0,0] op_sel_hi:[0,1,0]
	v_fma_mix_f32 v11, v20, v88, v17 op_sel:[0,1,0] op_sel_hi:[0,1,0]
	v_fma_mix_f32 v12, v20, v89, v18 op_sel:[0,0,0] op_sel_hi:[0,1,0]
	v_fma_mix_f32 v13, v20, v89, v19 op_sel:[0,1,0] op_sel_hi:[0,1,0]
	s_waitcnt lgkmcnt(4)
	ds_read_b64 v[72:73], v6 offset:6160
	ds_read_b128 v[74:77], v6 offset:6416
	ds_read_b128 v[78:81], v6 offset:6672
	ds_read_u16 v82, v7 offset:6160
	v_fma_mix_f32 v14, v10, v26, 0 op_sel:[0,0,0] op_sel_hi:[0,1,0]
	v_fma_mix_f32 v51, v10, v92, 0 op_sel:[0,0,0] op_sel_hi:[0,1,0]
	v_fma_mix_f32 v14, v11, v26, v14 op_sel:[0,1,0] op_sel_hi:[0,1,0]
	v_fma_mix_f32 v51, v11, v92, v51 op_sel:[0,1,0] op_sel_hi:[0,1,0]
	v_fma_mix_f32 v14, v12, v27, v14 op_sel:[0,0,0] op_sel_hi:[0,1,0]
	v_fma_mix_f32 v51, v12, v93, v51 op_sel:[0,0,0] op_sel_hi:[0,1,0]
	v_fma_mix_f32 v14, v13, v27, v14 op_sel:[0,1,0] op_sel_hi:[0,1,0]
	v_fma_mix_f32 v16, v10, v24, 0 op_sel:[0,0,0] op_sel_hi:[0,1,0]
	v_fma_mix_f32 v17, v11, v24, 0 op_sel:[0,1,0] op_sel_hi:[0,1,0]
	v_add_f32_dpp v20, v14, v14 quad_perm:[1,0,3,2] row_mask:0xf bank_mask:0xf bound_ctrl:1
	v_fma_mix_f32 v51, v13, v93, v51 op_sel:[0,1,0] op_sel_hi:[0,1,0]
	v_fma_mix_f32 v18, v12, v25, 0 op_sel:[0,0,0] op_sel_hi:[0,1,0]
	v_add_f32_dpp v20, v20, v20 quad_perm:[2,3,0,1] row_mask:0xf bank_mask:0xf bound_ctrl:1
	v_fma_mix_f32 v19, v13, v25, 0 op_sel:[0,1,0] op_sel_hi:[0,1,0]
	v_fma_mix_f32 v16, v34, v30, v16 op_sel:[0,0,0] op_sel_hi:[1,1,0]
	v_add_f32_dpp v20, v20, v20 row_half_mirror row_mask:0xf bank_mask:0xf bound_ctrl:1
	v_fma_mix_f32 v17, v34, v30, v17 op_sel:[0,1,0] op_sel_hi:[1,1,0]
	v_fma_mix_f32 v18, v34, v31, v18 op_sel:[0,0,0] op_sel_hi:[1,1,0]
	v_add_f32_dpp v20, v20, v20 row_mirror row_mask:0xf bank_mask:0xf bound_ctrl:1
	v_fma_mix_f32 v19, v34, v31, v19 op_sel:[0,1,0] op_sel_hi:[1,1,0]
	v_fma_mix_f32 v10, v20, v28, v16 op_sel:[0,0,0] op_sel_hi:[0,1,0]
	v_fma_mix_f32 v11, v20, v28, v17 op_sel:[0,1,0] op_sel_hi:[0,1,0]
	v_fma_mix_f32 v12, v20, v29, v18 op_sel:[0,0,0] op_sel_hi:[0,1,0]
	v_fma_mix_f32 v13, v20, v29, v19 op_sel:[0,1,0] op_sel_hi:[0,1,0]
	s_waitcnt lgkmcnt(4)
	ds_read_b64 v[84:85], v6 offset:7184
	ds_read_b128 v[86:89], v6 offset:7440
	ds_read_b128 v[90:93], v6 offset:7696
	ds_read_u16 v94, v7 offset:7184
	v_fma_mix_f32 v14, v10, v38, 0 op_sel:[0,0,0] op_sel_hi:[0,1,0]
	v_fma_mix_f32 v52, v10, v32, 0 op_sel:[0,0,0] op_sel_hi:[0,1,0]
	v_fma_mix_f32 v14, v11, v38, v14 op_sel:[0,1,0] op_sel_hi:[0,1,0]
	v_fma_mix_f32 v52, v11, v32, v52 op_sel:[0,1,0] op_sel_hi:[0,1,0]
	v_fma_mix_f32 v14, v12, v39, v14 op_sel:[0,0,0] op_sel_hi:[0,1,0]
	v_fma_mix_f32 v52, v12, v33, v52 op_sel:[0,0,0] op_sel_hi:[0,1,0]
	v_fma_mix_f32 v14, v13, v39, v14 op_sel:[0,1,0] op_sel_hi:[0,1,0]
	v_fma_mix_f32 v16, v10, v36, 0 op_sel:[0,0,0] op_sel_hi:[0,1,0]
	v_fma_mix_f32 v17, v11, v36, 0 op_sel:[0,1,0] op_sel_hi:[0,1,0]
	v_add_f32_dpp v20, v14, v14 quad_perm:[1,0,3,2] row_mask:0xf bank_mask:0xf bound_ctrl:1
	v_fma_mix_f32 v52, v13, v33, v52 op_sel:[0,1,0] op_sel_hi:[0,1,0]
	v_fma_mix_f32 v18, v12, v37, 0 op_sel:[0,0,0] op_sel_hi:[0,1,0]
	v_add_f32_dpp v20, v20, v20 quad_perm:[2,3,0,1] row_mask:0xf bank_mask:0xf bound_ctrl:1
	v_fma_mix_f32 v19, v13, v37, 0 op_sel:[0,1,0] op_sel_hi:[0,1,0]
	v_fma_mix_f32 v16, v46, v42, v16 op_sel:[0,0,0] op_sel_hi:[1,1,0]
	v_add_f32_dpp v20, v20, v20 row_half_mirror row_mask:0xf bank_mask:0xf bound_ctrl:1
	v_fma_mix_f32 v17, v46, v42, v17 op_sel:[0,1,0] op_sel_hi:[1,1,0]
	v_fma_mix_f32 v18, v46, v43, v18 op_sel:[0,0,0] op_sel_hi:[1,1,0]
	v_add_f32_dpp v20, v20, v20 row_mirror row_mask:0xf bank_mask:0xf bound_ctrl:1
	v_fma_mix_f32 v19, v46, v43, v19 op_sel:[0,1,0] op_sel_hi:[1,1,0]
	v_fma_mix_f32 v10, v20, v40, v16 op_sel:[0,0,0] op_sel_hi:[0,1,0]
	v_fma_mix_f32 v11, v20, v40, v17 op_sel:[0,1,0] op_sel_hi:[0,1,0]
	v_fma_mix_f32 v12, v20, v41, v18 op_sel:[0,0,0] op_sel_hi:[0,1,0]
	v_fma_mix_f32 v13, v20, v41, v19 op_sel:[0,1,0] op_sel_hi:[0,1,0]
	s_waitcnt lgkmcnt(4)
	ds_read_b64 v[24:25], v6 offset:8208
	ds_read_b128 v[26:29], v6 offset:8464
	ds_read_b128 v[30:33], v6 offset:8720
	ds_read_u16 v34, v7 offset:8208
	v_fma_mix_f32 v14, v10, v74, 0 op_sel:[0,0,0] op_sel_hi:[0,1,0]
	v_fma_mix_f32 v53, v10, v44, 0 op_sel:[0,0,0] op_sel_hi:[0,1,0]
	v_fma_mix_f32 v14, v11, v74, v14 op_sel:[0,1,0] op_sel_hi:[0,1,0]
	v_fma_mix_f32 v53, v11, v44, v53 op_sel:[0,1,0] op_sel_hi:[0,1,0]
	v_fma_mix_f32 v14, v12, v75, v14 op_sel:[0,0,0] op_sel_hi:[0,1,0]
	v_fma_mix_f32 v53, v12, v45, v53 op_sel:[0,0,0] op_sel_hi:[0,1,0]
	v_fma_mix_f32 v14, v13, v75, v14 op_sel:[0,1,0] op_sel_hi:[0,1,0]
	v_fma_mix_f32 v16, v10, v72, 0 op_sel:[0,0,0] op_sel_hi:[0,1,0]
	v_fma_mix_f32 v17, v11, v72, 0 op_sel:[0,1,0] op_sel_hi:[0,1,0]
	v_add_f32_dpp v20, v14, v14 quad_perm:[1,0,3,2] row_mask:0xf bank_mask:0xf bound_ctrl:1
	v_fma_mix_f32 v53, v13, v45, v53 op_sel:[0,1,0] op_sel_hi:[0,1,0]
	v_fma_mix_f32 v18, v12, v73, 0 op_sel:[0,0,0] op_sel_hi:[0,1,0]
	v_add_f32_dpp v20, v20, v20 quad_perm:[2,3,0,1] row_mask:0xf bank_mask:0xf bound_ctrl:1
	v_fma_mix_f32 v19, v13, v73, 0 op_sel:[0,1,0] op_sel_hi:[0,1,0]
	v_fma_mix_f32 v16, v82, v78, v16 op_sel:[0,0,0] op_sel_hi:[1,1,0]
	v_add_f32_dpp v20, v20, v20 row_half_mirror row_mask:0xf bank_mask:0xf bound_ctrl:1
	v_fma_mix_f32 v17, v82, v78, v17 op_sel:[0,1,0] op_sel_hi:[1,1,0]
	v_fma_mix_f32 v18, v82, v79, v18 op_sel:[0,0,0] op_sel_hi:[1,1,0]
	v_add_f32_dpp v20, v20, v20 row_mirror row_mask:0xf bank_mask:0xf bound_ctrl:1
	v_fma_mix_f32 v19, v82, v79, v19 op_sel:[0,1,0] op_sel_hi:[1,1,0]
	v_fma_mix_f32 v10, v20, v76, v16 op_sel:[0,0,0] op_sel_hi:[0,1,0]
	v_fma_mix_f32 v11, v20, v76, v17 op_sel:[0,1,0] op_sel_hi:[0,1,0]
	v_fma_mix_f32 v12, v20, v77, v18 op_sel:[0,0,0] op_sel_hi:[0,1,0]
	v_fma_mix_f32 v13, v20, v77, v19 op_sel:[0,1,0] op_sel_hi:[0,1,0]
	s_waitcnt lgkmcnt(4)
	ds_read_b64 v[36:37], v6 offset:9232
	ds_read_b128 v[38:41], v6 offset:9488
	ds_read_b128 v[42:45], v6 offset:9744
	ds_read_u16 v46, v7 offset:9232
	v_fma_mix_f32 v14, v10, v86, 0 op_sel:[0,0,0] op_sel_hi:[0,1,0]
	v_fma_mix_f32 v54, v10, v80, 0 op_sel:[0,0,0] op_sel_hi:[0,1,0]
	v_fma_mix_f32 v14, v11, v86, v14 op_sel:[0,1,0] op_sel_hi:[0,1,0]
	v_fma_mix_f32 v54, v11, v80, v54 op_sel:[0,1,0] op_sel_hi:[0,1,0]
	v_fma_mix_f32 v14, v12, v87, v14 op_sel:[0,0,0] op_sel_hi:[0,1,0]
	v_fma_mix_f32 v54, v12, v81, v54 op_sel:[0,0,0] op_sel_hi:[0,1,0]
	v_fma_mix_f32 v14, v13, v87, v14 op_sel:[0,1,0] op_sel_hi:[0,1,0]
	v_fma_mix_f32 v16, v10, v84, 0 op_sel:[0,0,0] op_sel_hi:[0,1,0]
	v_fma_mix_f32 v17, v11, v84, 0 op_sel:[0,1,0] op_sel_hi:[0,1,0]
	v_add_f32_dpp v20, v14, v14 quad_perm:[1,0,3,2] row_mask:0xf bank_mask:0xf bound_ctrl:1
	v_fma_mix_f32 v54, v13, v81, v54 op_sel:[0,1,0] op_sel_hi:[0,1,0]
	v_fma_mix_f32 v18, v12, v85, 0 op_sel:[0,0,0] op_sel_hi:[0,1,0]
	v_add_f32_dpp v20, v20, v20 quad_perm:[2,3,0,1] row_mask:0xf bank_mask:0xf bound_ctrl:1
	v_fma_mix_f32 v19, v13, v85, 0 op_sel:[0,1,0] op_sel_hi:[0,1,0]
	v_fma_mix_f32 v16, v94, v90, v16 op_sel:[0,0,0] op_sel_hi:[1,1,0]
	v_add_f32_dpp v20, v20, v20 row_half_mirror row_mask:0xf bank_mask:0xf bound_ctrl:1
	v_fma_mix_f32 v17, v94, v90, v17 op_sel:[0,1,0] op_sel_hi:[1,1,0]
	v_fma_mix_f32 v18, v94, v91, v18 op_sel:[0,0,0] op_sel_hi:[1,1,0]
	v_add_f32_dpp v20, v20, v20 row_mirror row_mask:0xf bank_mask:0xf bound_ctrl:1
	v_fma_mix_f32 v19, v94, v91, v19 op_sel:[0,1,0] op_sel_hi:[1,1,0]
	v_fma_mix_f32 v10, v20, v88, v16 op_sel:[0,0,0] op_sel_hi:[0,1,0]
	v_fma_mix_f32 v11, v20, v88, v17 op_sel:[0,1,0] op_sel_hi:[0,1,0]
	v_fma_mix_f32 v12, v20, v89, v18 op_sel:[0,0,0] op_sel_hi:[0,1,0]
	v_fma_mix_f32 v13, v20, v89, v19 op_sel:[0,1,0] op_sel_hi:[0,1,0]
	s_waitcnt lgkmcnt(4)
	ds_read_b64 v[72:73], v6 offset:10256
	ds_read_b128 v[74:77], v6 offset:10512
	ds_read_b128 v[78:81], v6 offset:10768
	ds_read_u16 v82, v7 offset:10256
	v_fma_mix_f32 v14, v10, v26, 0 op_sel:[0,0,0] op_sel_hi:[0,1,0]
	v_fma_mix_f32 v55, v10, v92, 0 op_sel:[0,0,0] op_sel_hi:[0,1,0]
	v_fma_mix_f32 v14, v11, v26, v14 op_sel:[0,1,0] op_sel_hi:[0,1,0]
	v_fma_mix_f32 v55, v11, v92, v55 op_sel:[0,1,0] op_sel_hi:[0,1,0]
	v_fma_mix_f32 v14, v12, v27, v14 op_sel:[0,0,0] op_sel_hi:[0,1,0]
	v_fma_mix_f32 v55, v12, v93, v55 op_sel:[0,0,0] op_sel_hi:[0,1,0]
	v_fma_mix_f32 v14, v13, v27, v14 op_sel:[0,1,0] op_sel_hi:[0,1,0]
	v_fma_mix_f32 v16, v10, v24, 0 op_sel:[0,0,0] op_sel_hi:[0,1,0]
	v_fma_mix_f32 v17, v11, v24, 0 op_sel:[0,1,0] op_sel_hi:[0,1,0]
	v_add_f32_dpp v20, v14, v14 quad_perm:[1,0,3,2] row_mask:0xf bank_mask:0xf bound_ctrl:1
	v_fma_mix_f32 v55, v13, v93, v55 op_sel:[0,1,0] op_sel_hi:[0,1,0]
	v_fma_mix_f32 v18, v12, v25, 0 op_sel:[0,0,0] op_sel_hi:[0,1,0]
	v_add_f32_dpp v20, v20, v20 quad_perm:[2,3,0,1] row_mask:0xf bank_mask:0xf bound_ctrl:1
	v_fma_mix_f32 v19, v13, v25, 0 op_sel:[0,1,0] op_sel_hi:[0,1,0]
	v_fma_mix_f32 v16, v34, v30, v16 op_sel:[0,0,0] op_sel_hi:[1,1,0]
	v_add_f32_dpp v20, v20, v20 row_half_mirror row_mask:0xf bank_mask:0xf bound_ctrl:1
	v_fma_mix_f32 v17, v34, v30, v17 op_sel:[0,1,0] op_sel_hi:[1,1,0]
	v_fma_mix_f32 v18, v34, v31, v18 op_sel:[0,0,0] op_sel_hi:[1,1,0]
	v_add_f32_dpp v20, v20, v20 row_mirror row_mask:0xf bank_mask:0xf bound_ctrl:1
	v_fma_mix_f32 v19, v34, v31, v19 op_sel:[0,1,0] op_sel_hi:[1,1,0]
	v_fma_mix_f32 v10, v20, v28, v16 op_sel:[0,0,0] op_sel_hi:[0,1,0]
	v_fma_mix_f32 v11, v20, v28, v17 op_sel:[0,1,0] op_sel_hi:[0,1,0]
	v_fma_mix_f32 v12, v20, v29, v18 op_sel:[0,0,0] op_sel_hi:[0,1,0]
	v_fma_mix_f32 v13, v20, v29, v19 op_sel:[0,1,0] op_sel_hi:[0,1,0]
	s_waitcnt lgkmcnt(4)
	ds_read_b64 v[84:85], v6 offset:11280
	ds_read_b128 v[86:89], v6 offset:11536
	ds_read_b128 v[90:93], v6 offset:11792
	ds_read_u16 v94, v7 offset:11280
	v_fma_mix_f32 v14, v10, v38, 0 op_sel:[0,0,0] op_sel_hi:[0,1,0]
	v_fma_mix_f32 v56, v10, v32, 0 op_sel:[0,0,0] op_sel_hi:[0,1,0]
	v_fma_mix_f32 v14, v11, v38, v14 op_sel:[0,1,0] op_sel_hi:[0,1,0]
	v_fma_mix_f32 v56, v11, v32, v56 op_sel:[0,1,0] op_sel_hi:[0,1,0]
	v_fma_mix_f32 v14, v12, v39, v14 op_sel:[0,0,0] op_sel_hi:[0,1,0]
	v_fma_mix_f32 v56, v12, v33, v56 op_sel:[0,0,0] op_sel_hi:[0,1,0]
	v_fma_mix_f32 v14, v13, v39, v14 op_sel:[0,1,0] op_sel_hi:[0,1,0]
	v_fma_mix_f32 v16, v10, v36, 0 op_sel:[0,0,0] op_sel_hi:[0,1,0]
	v_fma_mix_f32 v17, v11, v36, 0 op_sel:[0,1,0] op_sel_hi:[0,1,0]
	v_add_f32_dpp v20, v14, v14 quad_perm:[1,0,3,2] row_mask:0xf bank_mask:0xf bound_ctrl:1
	v_fma_mix_f32 v56, v13, v33, v56 op_sel:[0,1,0] op_sel_hi:[0,1,0]
	v_fma_mix_f32 v18, v12, v37, 0 op_sel:[0,0,0] op_sel_hi:[0,1,0]
	v_add_f32_dpp v20, v20, v20 quad_perm:[2,3,0,1] row_mask:0xf bank_mask:0xf bound_ctrl:1
	v_fma_mix_f32 v19, v13, v37, 0 op_sel:[0,1,0] op_sel_hi:[0,1,0]
	v_fma_mix_f32 v16, v46, v42, v16 op_sel:[0,0,0] op_sel_hi:[1,1,0]
	v_add_f32_dpp v20, v20, v20 row_half_mirror row_mask:0xf bank_mask:0xf bound_ctrl:1
	v_fma_mix_f32 v17, v46, v42, v17 op_sel:[0,1,0] op_sel_hi:[1,1,0]
	v_fma_mix_f32 v18, v46, v43, v18 op_sel:[0,0,0] op_sel_hi:[1,1,0]
	v_add_f32_dpp v20, v20, v20 row_mirror row_mask:0xf bank_mask:0xf bound_ctrl:1
	v_fma_mix_f32 v19, v46, v43, v19 op_sel:[0,1,0] op_sel_hi:[1,1,0]
	v_fma_mix_f32 v10, v20, v40, v16 op_sel:[0,0,0] op_sel_hi:[0,1,0]
	v_fma_mix_f32 v11, v20, v40, v17 op_sel:[0,1,0] op_sel_hi:[0,1,0]
	v_fma_mix_f32 v12, v20, v41, v18 op_sel:[0,0,0] op_sel_hi:[0,1,0]
	v_fma_mix_f32 v13, v20, v41, v19 op_sel:[0,1,0] op_sel_hi:[0,1,0]
	s_waitcnt lgkmcnt(4)
	ds_read_b64 v[24:25], v6 offset:12304
	ds_read_b128 v[26:29], v6 offset:12560
	ds_read_b128 v[30:33], v6 offset:12816
	ds_read_u16 v34, v7 offset:12304
	v_fma_mix_f32 v14, v10, v74, 0 op_sel:[0,0,0] op_sel_hi:[0,1,0]
	v_fma_mix_f32 v57, v10, v44, 0 op_sel:[0,0,0] op_sel_hi:[0,1,0]
	v_fma_mix_f32 v14, v11, v74, v14 op_sel:[0,1,0] op_sel_hi:[0,1,0]
	v_fma_mix_f32 v57, v11, v44, v57 op_sel:[0,1,0] op_sel_hi:[0,1,0]
	v_fma_mix_f32 v14, v12, v75, v14 op_sel:[0,0,0] op_sel_hi:[0,1,0]
	v_fma_mix_f32 v57, v12, v45, v57 op_sel:[0,0,0] op_sel_hi:[0,1,0]
	v_fma_mix_f32 v14, v13, v75, v14 op_sel:[0,1,0] op_sel_hi:[0,1,0]
	v_fma_mix_f32 v16, v10, v72, 0 op_sel:[0,0,0] op_sel_hi:[0,1,0]
	v_fma_mix_f32 v17, v11, v72, 0 op_sel:[0,1,0] op_sel_hi:[0,1,0]
	v_add_f32_dpp v20, v14, v14 quad_perm:[1,0,3,2] row_mask:0xf bank_mask:0xf bound_ctrl:1
	v_fma_mix_f32 v57, v13, v45, v57 op_sel:[0,1,0] op_sel_hi:[0,1,0]
	v_fma_mix_f32 v18, v12, v73, 0 op_sel:[0,0,0] op_sel_hi:[0,1,0]
	v_add_f32_dpp v20, v20, v20 quad_perm:[2,3,0,1] row_mask:0xf bank_mask:0xf bound_ctrl:1
	v_fma_mix_f32 v19, v13, v73, 0 op_sel:[0,1,0] op_sel_hi:[0,1,0]
	v_fma_mix_f32 v16, v82, v78, v16 op_sel:[0,0,0] op_sel_hi:[1,1,0]
	v_add_f32_dpp v20, v20, v20 row_half_mirror row_mask:0xf bank_mask:0xf bound_ctrl:1
	v_fma_mix_f32 v17, v82, v78, v17 op_sel:[0,1,0] op_sel_hi:[1,1,0]
	v_fma_mix_f32 v18, v82, v79, v18 op_sel:[0,0,0] op_sel_hi:[1,1,0]
	v_add_f32_dpp v20, v20, v20 row_mirror row_mask:0xf bank_mask:0xf bound_ctrl:1
	v_fma_mix_f32 v19, v82, v79, v19 op_sel:[0,1,0] op_sel_hi:[1,1,0]
	v_fma_mix_f32 v10, v20, v76, v16 op_sel:[0,0,0] op_sel_hi:[0,1,0]
	v_fma_mix_f32 v11, v20, v76, v17 op_sel:[0,1,0] op_sel_hi:[0,1,0]
	v_fma_mix_f32 v12, v20, v77, v18 op_sel:[0,0,0] op_sel_hi:[0,1,0]
	v_fma_mix_f32 v13, v20, v77, v19 op_sel:[0,1,0] op_sel_hi:[0,1,0]
	s_waitcnt lgkmcnt(4)
	ds_read_b64 v[36:37], v6 offset:13328
	ds_read_b128 v[38:41], v6 offset:13584
	ds_read_b128 v[42:45], v6 offset:13840
	ds_read_u16 v46, v7 offset:13328
	v_fma_mix_f32 v14, v10, v86, 0 op_sel:[0,0,0] op_sel_hi:[0,1,0]
	v_fma_mix_f32 v58, v10, v80, 0 op_sel:[0,0,0] op_sel_hi:[0,1,0]
	v_fma_mix_f32 v14, v11, v86, v14 op_sel:[0,1,0] op_sel_hi:[0,1,0]
	v_fma_mix_f32 v58, v11, v80, v58 op_sel:[0,1,0] op_sel_hi:[0,1,0]
	v_fma_mix_f32 v14, v12, v87, v14 op_sel:[0,0,0] op_sel_hi:[0,1,0]
	v_fma_mix_f32 v58, v12, v81, v58 op_sel:[0,0,0] op_sel_hi:[0,1,0]
	v_fma_mix_f32 v14, v13, v87, v14 op_sel:[0,1,0] op_sel_hi:[0,1,0]
	v_fma_mix_f32 v16, v10, v84, 0 op_sel:[0,0,0] op_sel_hi:[0,1,0]
	v_fma_mix_f32 v17, v11, v84, 0 op_sel:[0,1,0] op_sel_hi:[0,1,0]
	v_add_f32_dpp v20, v14, v14 quad_perm:[1,0,3,2] row_mask:0xf bank_mask:0xf bound_ctrl:1
	v_fma_mix_f32 v58, v13, v81, v58 op_sel:[0,1,0] op_sel_hi:[0,1,0]
	v_fma_mix_f32 v18, v12, v85, 0 op_sel:[0,0,0] op_sel_hi:[0,1,0]
	v_add_f32_dpp v20, v20, v20 quad_perm:[2,3,0,1] row_mask:0xf bank_mask:0xf bound_ctrl:1
	v_fma_mix_f32 v19, v13, v85, 0 op_sel:[0,1,0] op_sel_hi:[0,1,0]
	v_fma_mix_f32 v16, v94, v90, v16 op_sel:[0,0,0] op_sel_hi:[1,1,0]
	v_add_f32_dpp v20, v20, v20 row_half_mirror row_mask:0xf bank_mask:0xf bound_ctrl:1
	v_fma_mix_f32 v17, v94, v90, v17 op_sel:[0,1,0] op_sel_hi:[1,1,0]
	v_fma_mix_f32 v18, v94, v91, v18 op_sel:[0,0,0] op_sel_hi:[1,1,0]
	v_add_f32_dpp v20, v20, v20 row_mirror row_mask:0xf bank_mask:0xf bound_ctrl:1
	v_fma_mix_f32 v19, v94, v91, v19 op_sel:[0,1,0] op_sel_hi:[1,1,0]
	v_fma_mix_f32 v10, v20, v88, v16 op_sel:[0,0,0] op_sel_hi:[0,1,0]
	v_fma_mix_f32 v11, v20, v88, v17 op_sel:[0,1,0] op_sel_hi:[0,1,0]
	v_fma_mix_f32 v12, v20, v89, v18 op_sel:[0,0,0] op_sel_hi:[0,1,0]
	v_fma_mix_f32 v13, v20, v89, v19 op_sel:[0,1,0] op_sel_hi:[0,1,0]
	s_waitcnt lgkmcnt(4)
	ds_read_b64 v[72:73], v6 offset:14352
	ds_read_b128 v[74:77], v6 offset:14608
	ds_read_b128 v[78:81], v6 offset:14864
	ds_read_u16 v82, v7 offset:14352
	v_fma_mix_f32 v14, v10, v26, 0 op_sel:[0,0,0] op_sel_hi:[0,1,0]
	v_fma_mix_f32 v59, v10, v92, 0 op_sel:[0,0,0] op_sel_hi:[0,1,0]
	v_fma_mix_f32 v14, v11, v26, v14 op_sel:[0,1,0] op_sel_hi:[0,1,0]
	v_fma_mix_f32 v59, v11, v92, v59 op_sel:[0,1,0] op_sel_hi:[0,1,0]
	v_fma_mix_f32 v14, v12, v27, v14 op_sel:[0,0,0] op_sel_hi:[0,1,0]
	v_fma_mix_f32 v59, v12, v93, v59 op_sel:[0,0,0] op_sel_hi:[0,1,0]
	v_fma_mix_f32 v14, v13, v27, v14 op_sel:[0,1,0] op_sel_hi:[0,1,0]
	v_fma_mix_f32 v16, v10, v24, 0 op_sel:[0,0,0] op_sel_hi:[0,1,0]
	v_fma_mix_f32 v17, v11, v24, 0 op_sel:[0,1,0] op_sel_hi:[0,1,0]
	v_add_f32_dpp v20, v14, v14 quad_perm:[1,0,3,2] row_mask:0xf bank_mask:0xf bound_ctrl:1
	v_fma_mix_f32 v59, v13, v93, v59 op_sel:[0,1,0] op_sel_hi:[0,1,0]
	v_fma_mix_f32 v18, v12, v25, 0 op_sel:[0,0,0] op_sel_hi:[0,1,0]
	v_add_f32_dpp v20, v20, v20 quad_perm:[2,3,0,1] row_mask:0xf bank_mask:0xf bound_ctrl:1
	v_fma_mix_f32 v19, v13, v25, 0 op_sel:[0,1,0] op_sel_hi:[0,1,0]
	v_fma_mix_f32 v16, v34, v30, v16 op_sel:[0,0,0] op_sel_hi:[1,1,0]
	v_add_f32_dpp v20, v20, v20 row_half_mirror row_mask:0xf bank_mask:0xf bound_ctrl:1
	v_fma_mix_f32 v17, v34, v30, v17 op_sel:[0,1,0] op_sel_hi:[1,1,0]
	v_fma_mix_f32 v18, v34, v31, v18 op_sel:[0,0,0] op_sel_hi:[1,1,0]
	v_add_f32_dpp v20, v20, v20 row_mirror row_mask:0xf bank_mask:0xf bound_ctrl:1
	v_fma_mix_f32 v19, v34, v31, v19 op_sel:[0,1,0] op_sel_hi:[1,1,0]
	v_fma_mix_f32 v10, v20, v28, v16 op_sel:[0,0,0] op_sel_hi:[0,1,0]
	v_fma_mix_f32 v11, v20, v28, v17 op_sel:[0,1,0] op_sel_hi:[0,1,0]
	v_fma_mix_f32 v12, v20, v29, v18 op_sel:[0,0,0] op_sel_hi:[0,1,0]
	v_fma_mix_f32 v13, v20, v29, v19 op_sel:[0,1,0] op_sel_hi:[0,1,0]
	s_waitcnt lgkmcnt(4)
; DEVINL u16 f2bf(float a) { return (u16)(pk2(a, 0.f) & 0xffffu); }
; #define RW_STEP2(B) RW_STEP(B, WvA, XA, KrA, vhA, WvB, XB, KrB, vhB); RW_STEP((B) + 1, WvB, XB, KrB, vhB, WvA, XA, KrA, vhA)
; #define RW_STEP4(B) RW_STEP2(B); RW_STEP2((B) + 2)
; template <int DIR>
; DEVINL void rwkv_scan_dir(const Params& p, int task, int lane, int wave) {
;     ...
;   for (int st = 0; st < 4096; st += 32) {
;     RW_STEP(0, WvA, XA, KrA, vhA, WvB, XB, KrB, vhB);
;     if (st > 0) { const int q0 = st - 16 + seg; yo[(long)(DIR ? (4095 - q0) : q0) * 1024] = f2bf(ykeep); }
;     RW_STEP(1, WvB, XB, KrB, vhB, WvA, XA, KrA, vhA);
;     RW_STEP2(2); RW_STEP4(4); RW_STEP4(8); RW_STEP4(12);
	ds_read_b128 v[100:103], v9
	ds_read_b64 v[84:85], v6 offset:15376
	ds_read_b128 v[86:89], v6 offset:15632
	ds_read_b128 v[90:93], v6 offset:15888
	ds_read_u16 v94, v7 offset:15376
	v_fma_mix_f32 v14, v10, v38, 0 op_sel:[0,0,0] op_sel_hi:[0,1,0]
	v_fma_mix_f32 v60, v10, v32, 0 op_sel:[0,0,0] op_sel_hi:[0,1,0]
	v_fma_mix_f32 v14, v11, v38, v14 op_sel:[0,1,0] op_sel_hi:[0,1,0]
	v_fma_mix_f32 v60, v11, v32, v60 op_sel:[0,1,0] op_sel_hi:[0,1,0]
	v_fma_mix_f32 v14, v12, v39, v14 op_sel:[0,0,0] op_sel_hi:[0,1,0]
	v_fma_mix_f32 v60, v12, v33, v60 op_sel:[0,0,0] op_sel_hi:[0,1,0]
	v_fma_mix_f32 v14, v13, v39, v14 op_sel:[0,1,0] op_sel_hi:[0,1,0]
	v_fma_mix_f32 v16, v10, v36, 0 op_sel:[0,0,0] op_sel_hi:[0,1,0]
	v_fma_mix_f32 v17, v11, v36, 0 op_sel:[0,1,0] op_sel_hi:[0,1,0]
	v_add_f32_dpp v20, v14, v14 quad_perm:[1,0,3,2] row_mask:0xf bank_mask:0xf bound_ctrl:1
	v_fma_mix_f32 v60, v13, v33, v60 op_sel:[0,1,0] op_sel_hi:[0,1,0]
	v_fma_mix_f32 v18, v12, v37, 0 op_sel:[0,0,0] op_sel_hi:[0,1,0]
	v_add_f32_dpp v20, v20, v20 quad_perm:[2,3,0,1] row_mask:0xf bank_mask:0xf bound_ctrl:1
	v_fma_mix_f32 v19, v13, v37, 0 op_sel:[0,1,0] op_sel_hi:[0,1,0]
	v_fma_mix_f32 v16, v46, v42, v16 op_sel:[0,0,0] op_sel_hi:[1,1,0]
	v_add_f32_dpp v20, v20, v20 row_half_mirror row_mask:0xf bank_mask:0xf bound_ctrl:1
	v_fma_mix_f32 v17, v46, v42, v17 op_sel:[0,1,0] op_sel_hi:[1,1,0]
	v_fma_mix_f32 v18, v46, v43, v18 op_sel:[0,0,0] op_sel_hi:[1,1,0]
	v_add_f32_dpp v20, v20, v20 row_mirror row_mask:0xf bank_mask:0xf bound_ctrl:1
	v_fma_mix_f32 v19, v46, v43, v19 op_sel:[0,1,0] op_sel_hi:[1,1,0]
	v_fma_mix_f32 v10, v20, v40, v16 op_sel:[0,0,0] op_sel_hi:[0,1,0]
	v_fma_mix_f32 v11, v20, v40, v17 op_sel:[0,1,0] op_sel_hi:[0,1,0]
	v_fma_mix_f32 v12, v20, v41, v18 op_sel:[0,0,0] op_sel_hi:[0,1,0]
	v_fma_mix_f32 v13, v20, v41, v19 op_sel:[0,1,0] op_sel_hi:[0,1,0]
	s_waitcnt lgkmcnt(4)
	v_add_u32_e32 v6, 0x4000, v6
	v_add_u32_e32 v7, 0x4000, v7
	v_and_b32_e32 v6, 0x1ffff, v6
	v_and_b32_e32 v7, 0x1ffff, v7
	ds_read_b64 v[24:25], v6 offset:16
	ds_read_b128 v[26:29], v6 offset:272
	ds_read_b128 v[30:33], v6 offset:528
	ds_read_u16 v34, v7 offset:16
	v_fma_mix_f32 v14, v10, v74, 0 op_sel:[0,0,0] op_sel_hi:[0,1,0]
	v_fma_mix_f32 v61, v10, v44, 0 op_sel:[0,0,0] op_sel_hi:[0,1,0]
	v_fma_mix_f32 v14, v11, v74, v14 op_sel:[0,1,0] op_sel_hi:[0,1,0]
	v_fma_mix_f32 v61, v11, v44, v61 op_sel:[0,1,0] op_sel_hi:[0,1,0]
	v_fma_mix_f32 v14, v12, v75, v14 op_sel:[0,0,0] op_sel_hi:[0,1,0]
	v_fma_mix_f32 v61, v12, v45, v61 op_sel:[0,0,0] op_sel_hi:[0,1,0]
	v_fma_mix_f32 v14, v13, v75, v14 op_sel:[0,1,0] op_sel_hi:[0,1,0]
	v_fma_mix_f32 v16, v10, v72, 0 op_sel:[0,0,0] op_sel_hi:[0,1,0]
	v_fma_mix_f32 v17, v11, v72, 0 op_sel:[0,1,0] op_sel_hi:[0,1,0]
	v_add_f32_dpp v20, v14, v14 quad_perm:[1,0,3,2] row_mask:0xf bank_mask:0xf bound_ctrl:1
	v_fma_mix_f32 v61, v13, v45, v61 op_sel:[0,1,0] op_sel_hi:[0,1,0]
	v_fma_mix_f32 v18, v12, v73, 0 op_sel:[0,0,0] op_sel_hi:[0,1,0]
	v_add_f32_dpp v20, v20, v20 quad_perm:[2,3,0,1] row_mask:0xf bank_mask:0xf bound_ctrl:1
	v_fma_mix_f32 v19, v13, v73, 0 op_sel:[0,1,0] op_sel_hi:[0,1,0]
	v_fma_mix_f32 v16, v82, v78, v16 op_sel:[0,0,0] op_sel_hi:[1,1,0]
	v_add_f32_dpp v20, v20, v20 row_half_mirror row_mask:0xf bank_mask:0xf bound_ctrl:1
	v_fma_mix_f32 v17, v82, v78, v17 op_sel:[0,1,0] op_sel_hi:[1,1,0]
	v_fma_mix_f32 v18, v82, v79, v18 op_sel:[0,0,0] op_sel_hi:[1,1,0]
	v_add_f32_dpp v20, v20, v20 row_mirror row_mask:0xf bank_mask:0xf bound_ctrl:1
	v_fma_mix_f32 v19, v82, v79, v19 op_sel:[0,1,0] op_sel_hi:[1,1,0]
	v_fma_mix_f32 v10, v20, v76, v16 op_sel:[0,0,0] op_sel_hi:[0,1,0]
	v_fma_mix_f32 v11, v20, v76, v17 op_sel:[0,1,0] op_sel_hi:[0,1,0]
	v_fma_mix_f32 v12, v20, v77, v18 op_sel:[0,0,0] op_sel_hi:[0,1,0]
	v_fma_mix_f32 v13, v20, v77, v19 op_sel:[0,1,0] op_sel_hi:[0,1,0]
	s_waitcnt lgkmcnt(4)
	ds_read_b64 v[36:37], v6 offset:1040
	ds_read_b128 v[38:41], v6 offset:1296
	ds_read_b128 v[42:45], v6 offset:1552
	ds_read_u16 v46, v7 offset:1040
	v_fma_mix_f32 v14, v10, v86, 0 op_sel:[0,0,0] op_sel_hi:[0,1,0]
	v_fma_mix_f32 v62, v10, v80, 0 op_sel:[0,0,0] op_sel_hi:[0,1,0]
	v_fma_mix_f32 v14, v11, v86, v14 op_sel:[0,1,0] op_sel_hi:[0,1,0]
	v_fma_mix_f32 v62, v11, v80, v62 op_sel:[0,1,0] op_sel_hi:[0,1,0]
	v_fma_mix_f32 v14, v12, v87, v14 op_sel:[0,0,0] op_sel_hi:[0,1,0]
	v_fma_mix_f32 v62, v12, v81, v62 op_sel:[0,0,0] op_sel_hi:[0,1,0]
	v_fma_mix_f32 v14, v13, v87, v14 op_sel:[0,1,0] op_sel_hi:[0,1,0]
	v_fma_mix_f32 v16, v10, v84, 0 op_sel:[0,0,0] op_sel_hi:[0,1,0]
	v_fma_mix_f32 v17, v11, v84, 0 op_sel:[0,1,0] op_sel_hi:[0,1,0]
	v_add_f32_dpp v20, v14, v14 quad_perm:[1,0,3,2] row_mask:0xf bank_mask:0xf bound_ctrl:1
	v_fma_mix_f32 v62, v13, v81, v62 op_sel:[0,1,0] op_sel_hi:[0,1,0]
	v_fma_mix_f32 v18, v12, v85, 0 op_sel:[0,0,0] op_sel_hi:[0,1,0]
	v_add_f32_dpp v20, v20, v20 quad_perm:[2,3,0,1] row_mask:0xf bank_mask:0xf bound_ctrl:1
	v_fma_mix_f32 v19, v13, v85, 0 op_sel:[0,1,0] op_sel_hi:[0,1,0]
	v_fma_mix_f32 v16, v94, v90, v16 op_sel:[0,0,0] op_sel_hi:[1,1,0]
	v_add_f32_dpp v20, v20, v20 row_half_mirror row_mask:0xf bank_mask:0xf bound_ctrl:1
	v_fma_mix_f32 v17, v94, v90, v17 op_sel:[0,1,0] op_sel_hi:[1,1,0]
	v_fma_mix_f32 v18, v94, v91, v18 op_sel:[0,0,0] op_sel_hi:[1,1,0]
	v_add_f32_dpp v20, v20, v20 row_mirror row_mask:0xf bank_mask:0xf bound_ctrl:1
	v_fma_mix_f32 v19, v94, v91, v19 op_sel:[0,1,0] op_sel_hi:[1,1,0]
	v_fma_mix_f32 v10, v20, v88, v16 op_sel:[0,0,0] op_sel_hi:[0,1,0]
	v_fma_mix_f32 v11, v20, v88, v17 op_sel:[0,1,0] op_sel_hi:[0,1,0]
	v_fma_mix_f32 v12, v20, v89, v18 op_sel:[0,0,0] op_sel_hi:[0,1,0]
	v_fma_mix_f32 v13, v20, v89, v19 op_sel:[0,1,0] op_sel_hi:[0,1,0]
	s_waitcnt lgkmcnt(4)
	s_add_u32 s43, s43, 1
	s_waitcnt vmcnt(0)
	v_add_u32_e32 v69, 1, v69
	ds_write_b32 v23, v69
	v_min3_u32 v100, v100, v101, v102
	v_min_u32_e32 v100, v100, v103
	s_nop 0
	v_readfirstlane_b32 s24, v100
	s_nop 0
	s_cmp_ge_u32 s24, s43
	s_cbranch_scc0 .Lrw_slow_d0b1
; DEVINL u16 f2bf(float a) { return (u16)(pk2(a, 0.f) & 0xffffu); }
; #define RW_STEP2(B) RW_STEP(B, WvA, XA, KrA, vhA, WvB, XB, KrB, vhB); RW_STEP((B) + 1, WvB, XB, KrB, vhB, WvA, XA, KrA, vhA)
; #define RW_STEP4(B) RW_STEP2(B); RW_STEP2((B) + 2)
; template <int DIR>
; DEVINL void rwkv_scan_dir(const Params& p, int task, int lane, int wave) {
;     ...
;     if (st > 0) { const int q0 = st - 16 + seg; yo[(long)(DIR ? (4095 - q0) : q0) * 1024] = f2bf(ykeep); }
;     RW_STEP(1, WvB, XB, KrB, vhB, WvA, XA, KrA, vhA);
;     RW_STEP2(2); RW_STEP4(4); RW_STEP4(8); RW_STEP4(12);
;     RW_STEP(16, WvA, XA, KrA, vhA, WvB, XB, KrB, vhB);
;     { const int q0 = st + seg; yo[(long)(DIR ? (4095 - q0) : q0) * 1024] = f2bf(ykeep); }
.Lrw_ready_d0b1:
	s_add_u32 m0, s41, 16
	s_nop 0
	global_load_lds_dwordx4 v5, s[10:11] offset:0
	global_load_lds_dwordx4 v5, s[10:11] offset:1024
	global_load_lds_dwordx4 v5, s[10:11] offset:2048
	global_load_lds_dwordx4 v5, s[10:11] offset:3072
	s_add_u32 s10, s10, 0x4000
	s_addc_u32 s11, s11, 0
	s_add_u32 s41, s41, 0x4000
	s_and_b32 s41, s41, 0x1ffff
	ds_read_b64 v[72:73], v6 offset:2064
	ds_read_b128 v[74:77], v6 offset:2320
	ds_read_b128 v[78:81], v6 offset:2576
	ds_read_u16 v82, v7 offset:2064
	v_fma_mix_f32 v14, v10, v26, 0 op_sel:[0,0,0] op_sel_hi:[0,1,0]
	v_fma_mix_f32 v63, v10, v92, 0 op_sel:[0,0,0] op_sel_hi:[0,1,0]
	v_fma_mix_f32 v14, v11, v26, v14 op_sel:[0,1,0] op_sel_hi:[0,1,0]
	v_fma_mix_f32 v63, v11, v92, v63 op_sel:[0,1,0] op_sel_hi:[0,1,0]
	v_fma_mix_f32 v14, v12, v27, v14 op_sel:[0,0,0] op_sel_hi:[0,1,0]
	v_fma_mix_f32 v63, v12, v93, v63 op_sel:[0,0,0] op_sel_hi:[0,1,0]
	v_fma_mix_f32 v14, v13, v27, v14 op_sel:[0,1,0] op_sel_hi:[0,1,0]
	v_fma_mix_f32 v16, v10, v24, 0 op_sel:[0,0,0] op_sel_hi:[0,1,0]
	v_fma_mix_f32 v17, v11, v24, 0 op_sel:[0,1,0] op_sel_hi:[0,1,0]
	v_add_f32_dpp v20, v14, v14 quad_perm:[1,0,3,2] row_mask:0xf bank_mask:0xf bound_ctrl:1
	v_fma_mix_f32 v63, v13, v93, v63 op_sel:[0,1,0] op_sel_hi:[0,1,0]
	v_fma_mix_f32 v18, v12, v25, 0 op_sel:[0,0,0] op_sel_hi:[0,1,0]
	v_add_f32_dpp v20, v20, v20 quad_perm:[2,3,0,1] row_mask:0xf bank_mask:0xf bound_ctrl:1
	v_fma_mix_f32 v19, v13, v25, 0 op_sel:[0,1,0] op_sel_hi:[0,1,0]
	v_fma_mix_f32 v16, v34, v30, v16 op_sel:[0,0,0] op_sel_hi:[1,1,0]
	v_add_f32_dpp v20, v20, v20 row_half_mirror row_mask:0xf bank_mask:0xf bound_ctrl:1
	v_fma_mix_f32 v17, v34, v30, v17 op_sel:[0,1,0] op_sel_hi:[1,1,0]
	v_fma_mix_f32 v18, v34, v31, v18 op_sel:[0,0,0] op_sel_hi:[1,1,0]
	v_add_f32_dpp v20, v20, v20 row_mirror row_mask:0xf bank_mask:0xf bound_ctrl:1
	v_fma_mix_f32 v19, v34, v31, v19 op_sel:[0,1,0] op_sel_hi:[1,1,0]
	v_fma_mix_f32 v10, v20, v28, v16 op_sel:[0,0,0] op_sel_hi:[0,1,0]
	v_fma_mix_f32 v11, v20, v28, v17 op_sel:[0,1,0] op_sel_hi:[0,1,0]
	v_fma_mix_f32 v12, v20, v29, v18 op_sel:[0,0,0] op_sel_hi:[0,1,0]
	v_fma_mix_f32 v13, v20, v29, v19 op_sel:[0,1,0] op_sel_hi:[0,1,0]
	s_waitcnt lgkmcnt(4)
	v_add_f32_dpp v48, v48, v48 row_ror:8 row_mask:0xf bank_mask:0x3
	v_add_f32_dpp v49, v49, v49 row_ror:8 row_mask:0xf bank_mask:0x3
	v_add_f32_dpp v50, v50, v50 row_ror:8 row_mask:0xf bank_mask:0x3
	v_add_f32_dpp v51, v51, v51 row_ror:8 row_mask:0xf bank_mask:0x3
	v_add_f32_dpp v52, v52, v52 row_ror:8 row_mask:0xf bank_mask:0x3
	v_add_f32_dpp v53, v53, v53 row_ror:8 row_mask:0xf bank_mask:0x3
	v_add_f32_dpp v54, v54, v54 row_ror:8 row_mask:0xf bank_mask:0x3
	v_add_f32_dpp v55, v55, v55 row_ror:8 row_mask:0xf bank_mask:0x3
	v_add_f32_dpp v48, v56, v56 row_ror:8 row_mask:0xf bank_mask:0xc
	v_add_f32_dpp v49, v57, v57 row_ror:8 row_mask:0xf bank_mask:0xc
	v_add_f32_dpp v50, v58, v58 row_ror:8 row_mask:0xf bank_mask:0xc
	v_add_f32_dpp v51, v59, v59 row_ror:8 row_mask:0xf bank_mask:0xc
	v_add_f32_dpp v52, v60, v60 row_ror:8 row_mask:0xf bank_mask:0xc
	v_add_f32_dpp v53, v61, v61 row_ror:8 row_mask:0xf bank_mask:0xc
	v_add_f32_dpp v54, v62, v62 row_ror:8 row_mask:0xf bank_mask:0xc
	v_add_f32_dpp v55, v63, v63 row_ror:8 row_mask:0xf bank_mask:0xc
	v_add_f32_dpp v48, v48, v48 row_ror:12 row_mask:0xf bank_mask:0x5
	v_add_f32_dpp v49, v49, v49 row_ror:12 row_mask:0xf bank_mask:0x5
	v_add_f32_dpp v50, v50, v50 row_ror:12 row_mask:0xf bank_mask:0x5
	v_add_f32_dpp v51, v51, v51 row_ror:12 row_mask:0xf bank_mask:0x5
	v_add_f32_dpp v48, v52, v52 row_ror:4 row_mask:0xf bank_mask:0xa
	v_add_f32_dpp v49, v53, v53 row_ror:4 row_mask:0xf bank_mask:0xa
	v_add_f32_dpp v50, v54, v54 row_ror:4 row_mask:0xf bank_mask:0xa
	v_add_f32_dpp v51, v55, v55 row_ror:4 row_mask:0xf bank_mask:0xa
	v_add_f32_dpp v64, v48, v48 quad_perm:[2,3,0,1] row_mask:0xf bank_mask:0xf bound_ctrl:1
	v_add_f32_dpp v65, v50, v50 quad_perm:[2,3,0,1] row_mask:0xf bank_mask:0xf bound_ctrl:1
	v_cndmask_b32_e64 v56, v64, v65, s[50:51]
	v_add_f32_dpp v64, v49, v49 quad_perm:[2,3,0,1] row_mask:0xf bank_mask:0xf bound_ctrl:1
	v_add_f32_dpp v65, v51, v51 quad_perm:[2,3,0,1] row_mask:0xf bank_mask:0xf bound_ctrl:1
	v_cndmask_b32_e64 v57, v64, v65, s[50:51]
	v_add_f32_dpp v64, v56, v56 quad_perm:[1,0,3,2] row_mask:0xf bank_mask:0xf bound_ctrl:1
	s_nop 0
	v_add_f32_dpp v65, v57, v57 quad_perm:[1,0,3,2] row_mask:0xf bank_mask:0xf bound_ctrl:1
	v_cndmask_b32_e64 v66, v64, v65, s[48:49]
	v_cvt_pk_bf16_f32 v66, v66, v66
	global_store_short v8, v66, s[12:13]
	s_add_u32 s12, s12, 0x8000
	s_addc_u32 s13, s13, 0
	ds_read_b64 v[84:85], v6 offset:3088
	ds_read_b128 v[86:89], v6 offset:3344
	ds_read_b128 v[90:93], v6 offset:3600
	ds_read_u16 v94, v7 offset:3088
	v_fma_mix_f32 v14, v10, v38, 0 op_sel:[0,0,0] op_sel_hi:[0,1,0]
	v_fma_mix_f32 v48, v10, v32, 0 op_sel:[0,0,0] op_sel_hi:[0,1,0]
	v_fma_mix_f32 v14, v11, v38, v14 op_sel:[0,1,0] op_sel_hi:[0,1,0]
	v_fma_mix_f32 v48, v11, v32, v48 op_sel:[0,1,0] op_sel_hi:[0,1,0]
	v_fma_mix_f32 v14, v12, v39, v14 op_sel:[0,0,0] op_sel_hi:[0,1,0]
	v_fma_mix_f32 v48, v12, v33, v48 op_sel:[0,0,0] op_sel_hi:[0,1,0]
	v_fma_mix_f32 v14, v13, v39, v14 op_sel:[0,1,0] op_sel_hi:[0,1,0]
	v_fma_mix_f32 v16, v10, v36, 0 op_sel:[0,0,0] op_sel_hi:[0,1,0]
	v_fma_mix_f32 v17, v11, v36, 0 op_sel:[0,1,0] op_sel_hi:[0,1,0]
	v_add_f32_dpp v20, v14, v14 quad_perm:[1,0,3,2] row_mask:0xf bank_mask:0xf bound_ctrl:1
	v_fma_mix_f32 v48, v13, v33, v48 op_sel:[0,1,0] op_sel_hi:[0,1,0]
	v_fma_mix_f32 v18, v12, v37, 0 op_sel:[0,0,0] op_sel_hi:[0,1,0]
	v_add_f32_dpp v20, v20, v20 quad_perm:[2,3,0,1] row_mask:0xf bank_mask:0xf bound_ctrl:1
	v_fma_mix_f32 v19, v13, v37, 0 op_sel:[0,1,0] op_sel_hi:[0,1,0]
	v_fma_mix_f32 v16, v46, v42, v16 op_sel:[0,0,0] op_sel_hi:[1,1,0]
	v_add_f32_dpp v20, v20, v20 row_half_mirror row_mask:0xf bank_mask:0xf bound_ctrl:1
	v_fma_mix_f32 v17, v46, v42, v17 op_sel:[0,1,0] op_sel_hi:[1,1,0]
	v_fma_mix_f32 v18, v46, v43, v18 op_sel:[0,0,0] op_sel_hi:[1,1,0]
	v_add_f32_dpp v20, v20, v20 row_mirror row_mask:0xf bank_mask:0xf bound_ctrl:1
	v_fma_mix_f32 v19, v46, v43, v19 op_sel:[0,1,0] op_sel_hi:[1,1,0]
	v_fma_mix_f32 v10, v20, v40, v16 op_sel:[0,0,0] op_sel_hi:[0,1,0]
	v_fma_mix_f32 v11, v20, v40, v17 op_sel:[0,1,0] op_sel_hi:[0,1,0]
	v_fma_mix_f32 v12, v20, v41, v18 op_sel:[0,0,0] op_sel_hi:[0,1,0]
	v_fma_mix_f32 v13, v20, v41, v19 op_sel:[0,1,0] op_sel_hi:[0,1,0]
	s_waitcnt lgkmcnt(4)
	ds_read_b64 v[24:25], v6 offset:4112
	ds_read_b128 v[26:29], v6 offset:4368
	ds_read_b128 v[30:33], v6 offset:4624
	ds_read_u16 v34, v7 offset:4112
	v_fma_mix_f32 v14, v10, v74, 0 op_sel:[0,0,0] op_sel_hi:[0,1,0]
	v_fma_mix_f32 v49, v10, v44, 0 op_sel:[0,0,0] op_sel_hi:[0,1,0]
	v_fma_mix_f32 v14, v11, v74, v14 op_sel:[0,1,0] op_sel_hi:[0,1,0]
	v_fma_mix_f32 v49, v11, v44, v49 op_sel:[0,1,0] op_sel_hi:[0,1,0]
	v_fma_mix_f32 v14, v12, v75, v14 op_sel:[0,0,0] op_sel_hi:[0,1,0]
	v_fma_mix_f32 v49, v12, v45, v49 op_sel:[0,0,0] op_sel_hi:[0,1,0]
	v_fma_mix_f32 v14, v13, v75, v14 op_sel:[0,1,0] op_sel_hi:[0,1,0]
	v_fma_mix_f32 v16, v10, v72, 0 op_sel:[0,0,0] op_sel_hi:[0,1,0]
	v_fma_mix_f32 v17, v11, v72, 0 op_sel:[0,1,0] op_sel_hi:[0,1,0]
	v_add_f32_dpp v20, v14, v14 quad_perm:[1,0,3,2] row_mask:0xf bank_mask:0xf bound_ctrl:1
	v_fma_mix_f32 v49, v13, v45, v49 op_sel:[0,1,0] op_sel_hi:[0,1,0]
	v_fma_mix_f32 v18, v12, v73, 0 op_sel:[0,0,0] op_sel_hi:[0,1,0]
	v_add_f32_dpp v20, v20, v20 quad_perm:[2,3,0,1] row_mask:0xf bank_mask:0xf bound_ctrl:1
	v_fma_mix_f32 v19, v13, v73, 0 op_sel:[0,1,0] op_sel_hi:[0,1,0]
	v_fma_mix_f32 v16, v82, v78, v16 op_sel:[0,0,0] op_sel_hi:[1,1,0]
	v_add_f32_dpp v20, v20, v20 row_half_mirror row_mask:0xf bank_mask:0xf bound_ctrl:1
	v_fma_mix_f32 v17, v82, v78, v17 op_sel:[0,1,0] op_sel_hi:[1,1,0]
	v_fma_mix_f32 v18, v82, v79, v18 op_sel:[0,0,0] op_sel_hi:[1,1,0]
	v_add_f32_dpp v20, v20, v20 row_mirror row_mask:0xf bank_mask:0xf bound_ctrl:1
	v_fma_mix_f32 v19, v82, v79, v19 op_sel:[0,1,0] op_sel_hi:[1,1,0]
	v_fma_mix_f32 v10, v20, v76, v16 op_sel:[0,0,0] op_sel_hi:[0,1,0]
	v_fma_mix_f32 v11, v20, v76, v17 op_sel:[0,1,0] op_sel_hi:[0,1,0]
	v_fma_mix_f32 v12, v20, v77, v18 op_sel:[0,0,0] op_sel_hi:[0,1,0]
	v_fma_mix_f32 v13, v20, v77, v19 op_sel:[0,1,0] op_sel_hi:[0,1,0]
	s_waitcnt lgkmcnt(4)
	ds_read_b64 v[36:37], v6 offset:5136
	ds_read_b128 v[38:41], v6 offset:5392
	ds_read_b128 v[42:45], v6 offset:5648
	ds_read_u16 v46, v7 offset:5136
	v_fma_mix_f32 v14, v10, v86, 0 op_sel:[0,0,0] op_sel_hi:[0,1,0]
	v_fma_mix_f32 v50, v10, v80, 0 op_sel:[0,0,0] op_sel_hi:[0,1,0]
	v_fma_mix_f32 v14, v11, v86, v14 op_sel:[0,1,0] op_sel_hi:[0,1,0]
	v_fma_mix_f32 v50, v11, v80, v50 op_sel:[0,1,0] op_sel_hi:[0,1,0]
	v_fma_mix_f32 v14, v12, v87, v14 op_sel:[0,0,0] op_sel_hi:[0,1,0]
	v_fma_mix_f32 v50, v12, v81, v50 op_sel:[0,0,0] op_sel_hi:[0,1,0]
	v_fma_mix_f32 v14, v13, v87, v14 op_sel:[0,1,0] op_sel_hi:[0,1,0]
	v_fma_mix_f32 v16, v10, v84, 0 op_sel:[0,0,0] op_sel_hi:[0,1,0]
	v_fma_mix_f32 v17, v11, v84, 0 op_sel:[0,1,0] op_sel_hi:[0,1,0]
	v_add_f32_dpp v20, v14, v14 quad_perm:[1,0,3,2] row_mask:0xf bank_mask:0xf bound_ctrl:1
	v_fma_mix_f32 v50, v13, v81, v50 op_sel:[0,1,0] op_sel_hi:[0,1,0]
	v_fma_mix_f32 v18, v12, v85, 0 op_sel:[0,0,0] op_sel_hi:[0,1,0]
	v_add_f32_dpp v20, v20, v20 quad_perm:[2,3,0,1] row_mask:0xf bank_mask:0xf bound_ctrl:1
	v_fma_mix_f32 v19, v13, v85, 0 op_sel:[0,1,0] op_sel_hi:[0,1,0]
	v_fma_mix_f32 v16, v94, v90, v16 op_sel:[0,0,0] op_sel_hi:[1,1,0]
	v_add_f32_dpp v20, v20, v20 row_half_mirror row_mask:0xf bank_mask:0xf bound_ctrl:1
	v_fma_mix_f32 v17, v94, v90, v17 op_sel:[0,1,0] op_sel_hi:[1,1,0]
	v_fma_mix_f32 v18, v94, v91, v18 op_sel:[0,0,0] op_sel_hi:[1,1,0]
	v_add_f32_dpp v20, v20, v20 row_mirror row_mask:0xf bank_mask:0xf bound_ctrl:1
	v_fma_mix_f32 v19, v94, v91, v19 op_sel:[0,1,0] op_sel_hi:[1,1,0]
	v_fma_mix_f32 v10, v20, v88, v16 op_sel:[0,0,0] op_sel_hi:[0,1,0]
	v_fma_mix_f32 v11, v20, v88, v17 op_sel:[0,1,0] op_sel_hi:[0,1,0]
	v_fma_mix_f32 v12, v20, v89, v18 op_sel:[0,0,0] op_sel_hi:[0,1,0]
	v_fma_mix_f32 v13, v20, v89, v19 op_sel:[0,1,0] op_sel_hi:[0,1,0]
	s_waitcnt lgkmcnt(4)
	ds_read_b64 v[72:73], v6 offset:6160
	ds_read_b128 v[74:77], v6 offset:6416
	ds_read_b128 v[78:81], v6 offset:6672
	ds_read_u16 v82, v7 offset:6160
	v_fma_mix_f32 v14, v10, v26, 0 op_sel:[0,0,0] op_sel_hi:[0,1,0]
	v_fma_mix_f32 v51, v10, v92, 0 op_sel:[0,0,0] op_sel_hi:[0,1,0]
	v_fma_mix_f32 v14, v11, v26, v14 op_sel:[0,1,0] op_sel_hi:[0,1,0]
	v_fma_mix_f32 v51, v11, v92, v51 op_sel:[0,1,0] op_sel_hi:[0,1,0]
	v_fma_mix_f32 v14, v12, v27, v14 op_sel:[0,0,0] op_sel_hi:[0,1,0]
	v_fma_mix_f32 v51, v12, v93, v51 op_sel:[0,0,0] op_sel_hi:[0,1,0]
	v_fma_mix_f32 v14, v13, v27, v14 op_sel:[0,1,0] op_sel_hi:[0,1,0]
	v_fma_mix_f32 v16, v10, v24, 0 op_sel:[0,0,0] op_sel_hi:[0,1,0]
	v_fma_mix_f32 v17, v11, v24, 0 op_sel:[0,1,0] op_sel_hi:[0,1,0]
	v_add_f32_dpp v20, v14, v14 quad_perm:[1,0,3,2] row_mask:0xf bank_mask:0xf bound_ctrl:1
	v_fma_mix_f32 v51, v13, v93, v51 op_sel:[0,1,0] op_sel_hi:[0,1,0]
	v_fma_mix_f32 v18, v12, v25, 0 op_sel:[0,0,0] op_sel_hi:[0,1,0]
	v_add_f32_dpp v20, v20, v20 quad_perm:[2,3,0,1] row_mask:0xf bank_mask:0xf bound_ctrl:1
	v_fma_mix_f32 v19, v13, v25, 0 op_sel:[0,1,0] op_sel_hi:[0,1,0]
	v_fma_mix_f32 v16, v34, v30, v16 op_sel:[0,0,0] op_sel_hi:[1,1,0]
	v_add_f32_dpp v20, v20, v20 row_half_mirror row_mask:0xf bank_mask:0xf bound_ctrl:1
	v_fma_mix_f32 v17, v34, v30, v17 op_sel:[0,1,0] op_sel_hi:[1,1,0]
	v_fma_mix_f32 v18, v34, v31, v18 op_sel:[0,0,0] op_sel_hi:[1,1,0]
	v_add_f32_dpp v20, v20, v20 row_mirror row_mask:0xf bank_mask:0xf bound_ctrl:1
	v_fma_mix_f32 v19, v34, v31, v19 op_sel:[0,1,0] op_sel_hi:[1,1,0]
	v_fma_mix_f32 v10, v20, v28, v16 op_sel:[0,0,0] op_sel_hi:[0,1,0]
	v_fma_mix_f32 v11, v20, v28, v17 op_sel:[0,1,0] op_sel_hi:[0,1,0]
	v_fma_mix_f32 v12, v20, v29, v18 op_sel:[0,0,0] op_sel_hi:[0,1,0]
	v_fma_mix_f32 v13, v20, v29, v19 op_sel:[0,1,0] op_sel_hi:[0,1,0]
	s_waitcnt lgkmcnt(4)
	ds_read_b64 v[84:85], v6 offset:7184
	ds_read_b128 v[86:89], v6 offset:7440
	ds_read_b128 v[90:93], v6 offset:7696
	ds_read_u16 v94, v7 offset:7184
	v_fma_mix_f32 v14, v10, v38, 0 op_sel:[0,0,0] op_sel_hi:[0,1,0]
	v_fma_mix_f32 v52, v10, v32, 0 op_sel:[0,0,0] op_sel_hi:[0,1,0]
	v_fma_mix_f32 v14, v11, v38, v14 op_sel:[0,1,0] op_sel_hi:[0,1,0]
	v_fma_mix_f32 v52, v11, v32, v52 op_sel:[0,1,0] op_sel_hi:[0,1,0]
	v_fma_mix_f32 v14, v12, v39, v14 op_sel:[0,0,0] op_sel_hi:[0,1,0]
	v_fma_mix_f32 v52, v12, v33, v52 op_sel:[0,0,0] op_sel_hi:[0,1,0]
	v_fma_mix_f32 v14, v13, v39, v14 op_sel:[0,1,0] op_sel_hi:[0,1,0]
	v_fma_mix_f32 v16, v10, v36, 0 op_sel:[0,0,0] op_sel_hi:[0,1,0]
	v_fma_mix_f32 v17, v11, v36, 0 op_sel:[0,1,0] op_sel_hi:[0,1,0]
	v_add_f32_dpp v20, v14, v14 quad_perm:[1,0,3,2] row_mask:0xf bank_mask:0xf bound_ctrl:1
	v_fma_mix_f32 v52, v13, v33, v52 op_sel:[0,1,0] op_sel_hi:[0,1,0]
	v_fma_mix_f32 v18, v12, v37, 0 op_sel:[0,0,0] op_sel_hi:[0,1,0]
	v_add_f32_dpp v20, v20, v20 quad_perm:[2,3,0,1] row_mask:0xf bank_mask:0xf bound_ctrl:1
	v_fma_mix_f32 v19, v13, v37, 0 op_sel:[0,1,0] op_sel_hi:[0,1,0]
	v_fma_mix_f32 v16, v46, v42, v16 op_sel:[0,0,0] op_sel_hi:[1,1,0]
	v_add_f32_dpp v20, v20, v20 row_half_mirror row_mask:0xf bank_mask:0xf bound_ctrl:1
	v_fma_mix_f32 v17, v46, v42, v17 op_sel:[0,1,0] op_sel_hi:[1,1,0]
	v_fma_mix_f32 v18, v46, v43, v18 op_sel:[0,0,0] op_sel_hi:[1,1,0]
	v_add_f32_dpp v20, v20, v20 row_mirror row_mask:0xf bank_mask:0xf bound_ctrl:1
	v_fma_mix_f32 v19, v46, v43, v19 op_sel:[0,1,0] op_sel_hi:[1,1,0]
	v_fma_mix_f32 v10, v20, v40, v16 op_sel:[0,0,0] op_sel_hi:[0,1,0]
	v_fma_mix_f32 v11, v20, v40, v17 op_sel:[0,1,0] op_sel_hi:[0,1,0]
	v_fma_mix_f32 v12, v20, v41, v18 op_sel:[0,0,0] op_sel_hi:[0,1,0]
	v_fma_mix_f32 v13, v20, v41, v19 op_sel:[0,1,0] op_sel_hi:[0,1,0]
	s_waitcnt lgkmcnt(4)
	ds_read_b64 v[24:25], v6 offset:8208
	ds_read_b128 v[26:29], v6 offset:8464
	ds_read_b128 v[30:33], v6 offset:8720
	ds_read_u16 v34, v7 offset:8208
	v_fma_mix_f32 v14, v10, v74, 0 op_sel:[0,0,0] op_sel_hi:[0,1,0]
	v_fma_mix_f32 v53, v10, v44, 0 op_sel:[0,0,0] op_sel_hi:[0,1,0]
	v_fma_mix_f32 v14, v11, v74, v14 op_sel:[0,1,0] op_sel_hi:[0,1,0]
	v_fma_mix_f32 v53, v11, v44, v53 op_sel:[0,1,0] op_sel_hi:[0,1,0]
	v_fma_mix_f32 v14, v12, v75, v14 op_sel:[0,0,0] op_sel_hi:[0,1,0]
	v_fma_mix_f32 v53, v12, v45, v53 op_sel:[0,0,0] op_sel_hi:[0,1,0]
	v_fma_mix_f32 v14, v13, v75, v14 op_sel:[0,1,0] op_sel_hi:[0,1,0]
	v_fma_mix_f32 v16, v10, v72, 0 op_sel:[0,0,0] op_sel_hi:[0,1,0]
	v_fma_mix_f32 v17, v11, v72, 0 op_sel:[0,1,0] op_sel_hi:[0,1,0]
	v_add_f32_dpp v20, v14, v14 quad_perm:[1,0,3,2] row_mask:0xf bank_mask:0xf bound_ctrl:1
	v_fma_mix_f32 v53, v13, v45, v53 op_sel:[0,1,0] op_sel_hi:[0,1,0]
	v_fma_mix_f32 v18, v12, v73, 0 op_sel:[0,0,0] op_sel_hi:[0,1,0]
	v_add_f32_dpp v20, v20, v20 quad_perm:[2,3,0,1] row_mask:0xf bank_mask:0xf bound_ctrl:1
	v_fma_mix_f32 v19, v13, v73, 0 op_sel:[0,1,0] op_sel_hi:[0,1,0]
	v_fma_mix_f32 v16, v82, v78, v16 op_sel:[0,0,0] op_sel_hi:[1,1,0]
	v_add_f32_dpp v20, v20, v20 row_half_mirror row_mask:0xf bank_mask:0xf bound_ctrl:1
	v_fma_mix_f32 v17, v82, v78, v17 op_sel:[0,1,0] op_sel_hi:[1,1,0]
	v_fma_mix_f32 v18, v82, v79, v18 op_sel:[0,0,0] op_sel_hi:[1,1,0]
	v_add_f32_dpp v20, v20, v20 row_mirror row_mask:0xf bank_mask:0xf bound_ctrl:1
	v_fma_mix_f32 v19, v82, v79, v19 op_sel:[0,1,0] op_sel_hi:[1,1,0]
	v_fma_mix_f32 v10, v20, v76, v16 op_sel:[0,0,0] op_sel_hi:[0,1,0]
	v_fma_mix_f32 v11, v20, v76, v17 op_sel:[0,1,0] op_sel_hi:[0,1,0]
	v_fma_mix_f32 v12, v20, v77, v18 op_sel:[0,0,0] op_sel_hi:[0,1,0]
	v_fma_mix_f32 v13, v20, v77, v19 op_sel:[0,1,0] op_sel_hi:[0,1,0]
	s_waitcnt lgkmcnt(4)
	ds_read_b64 v[36:37], v6 offset:9232
	ds_read_b128 v[38:41], v6 offset:9488
	ds_read_b128 v[42:45], v6 offset:9744
	ds_read_u16 v46, v7 offset:9232
	v_fma_mix_f32 v14, v10, v86, 0 op_sel:[0,0,0] op_sel_hi:[0,1,0]
	v_fma_mix_f32 v54, v10, v80, 0 op_sel:[0,0,0] op_sel_hi:[0,1,0]
	v_fma_mix_f32 v14, v11, v86, v14 op_sel:[0,1,0] op_sel_hi:[0,1,0]
	v_fma_mix_f32 v54, v11, v80, v54 op_sel:[0,1,0] op_sel_hi:[0,1,0]
	v_fma_mix_f32 v14, v12, v87, v14 op_sel:[0,0,0] op_sel_hi:[0,1,0]
	v_fma_mix_f32 v54, v12, v81, v54 op_sel:[0,0,0] op_sel_hi:[0,1,0]
	v_fma_mix_f32 v14, v13, v87, v14 op_sel:[0,1,0] op_sel_hi:[0,1,0]
	v_fma_mix_f32 v16, v10, v84, 0 op_sel:[0,0,0] op_sel_hi:[0,1,0]
	v_fma_mix_f32 v17, v11, v84, 0 op_sel:[0,1,0] op_sel_hi:[0,1,0]
	v_add_f32_dpp v20, v14, v14 quad_perm:[1,0,3,2] row_mask:0xf bank_mask:0xf bound_ctrl:1
	v_fma_mix_f32 v54, v13, v81, v54 op_sel:[0,1,0] op_sel_hi:[0,1,0]
	v_fma_mix_f32 v18, v12, v85, 0 op_sel:[0,0,0] op_sel_hi:[0,1,0]
	v_add_f32_dpp v20, v20, v20 quad_perm:[2,3,0,1] row_mask:0xf bank_mask:0xf bound_ctrl:1
	v_fma_mix_f32 v19, v13, v85, 0 op_sel:[0,1,0] op_sel_hi:[0,1,0]
	v_fma_mix_f32 v16, v94, v90, v16 op_sel:[0,0,0] op_sel_hi:[1,1,0]
	v_add_f32_dpp v20, v20, v20 row_half_mirror row_mask:0xf bank_mask:0xf bound_ctrl:1
	v_fma_mix_f32 v17, v94, v90, v17 op_sel:[0,1,0] op_sel_hi:[1,1,0]
	v_fma_mix_f32 v18, v94, v91, v18 op_sel:[0,0,0] op_sel_hi:[1,1,0]
	v_add_f32_dpp v20, v20, v20 row_mirror row_mask:0xf bank_mask:0xf bound_ctrl:1
	v_fma_mix_f32 v19, v94, v91, v19 op_sel:[0,1,0] op_sel_hi:[1,1,0]
	v_fma_mix_f32 v10, v20, v88, v16 op_sel:[0,0,0] op_sel_hi:[0,1,0]
	v_fma_mix_f32 v11, v20, v88, v17 op_sel:[0,1,0] op_sel_hi:[0,1,0]
	v_fma_mix_f32 v12, v20, v89, v18 op_sel:[0,0,0] op_sel_hi:[0,1,0]
	v_fma_mix_f32 v13, v20, v89, v19 op_sel:[0,1,0] op_sel_hi:[0,1,0]
	s_waitcnt lgkmcnt(4)
	ds_read_b64 v[72:73], v6 offset:10256
	ds_read_b128 v[74:77], v6 offset:10512
	ds_read_b128 v[78:81], v6 offset:10768
	ds_read_u16 v82, v7 offset:10256
	v_fma_mix_f32 v14, v10, v26, 0 op_sel:[0,0,0] op_sel_hi:[0,1,0]
	v_fma_mix_f32 v55, v10, v92, 0 op_sel:[0,0,0] op_sel_hi:[0,1,0]
	v_fma_mix_f32 v14, v11, v26, v14 op_sel:[0,1,0] op_sel_hi:[0,1,0]
	v_fma_mix_f32 v55, v11, v92, v55 op_sel:[0,1,0] op_sel_hi:[0,1,0]
	v_fma_mix_f32 v14, v12, v27, v14 op_sel:[0,0,0] op_sel_hi:[0,1,0]
	v_fma_mix_f32 v55, v12, v93, v55 op_sel:[0,0,0] op_sel_hi:[0,1,0]
	v_fma_mix_f32 v14, v13, v27, v14 op_sel:[0,1,0] op_sel_hi:[0,1,0]
	v_fma_mix_f32 v16, v10, v24, 0 op_sel:[0,0,0] op_sel_hi:[0,1,0]
	v_fma_mix_f32 v17, v11, v24, 0 op_sel:[0,1,0] op_sel_hi:[0,1,0]
	v_add_f32_dpp v20, v14, v14 quad_perm:[1,0,3,2] row_mask:0xf bank_mask:0xf bound_ctrl:1
	v_fma_mix_f32 v55, v13, v93, v55 op_sel:[0,1,0] op_sel_hi:[0,1,0]
	v_fma_mix_f32 v18, v12, v25, 0 op_sel:[0,0,0] op_sel_hi:[0,1,0]
	v_add_f32_dpp v20, v20, v20 quad_perm:[2,3,0,1] row_mask:0xf bank_mask:0xf bound_ctrl:1
	v_fma_mix_f32 v19, v13, v25, 0 op_sel:[0,1,0] op_sel_hi:[0,1,0]
	v_fma_mix_f32 v16, v34, v30, v16 op_sel:[0,0,0] op_sel_hi:[1,1,0]
	v_add_f32_dpp v20, v20, v20 row_half_mirror row_mask:0xf bank_mask:0xf bound_ctrl:1
	v_fma_mix_f32 v17, v34, v30, v17 op_sel:[0,1,0] op_sel_hi:[1,1,0]
	v_fma_mix_f32 v18, v34, v31, v18 op_sel:[0,0,0] op_sel_hi:[1,1,0]
	v_add_f32_dpp v20, v20, v20 row_mirror row_mask:0xf bank_mask:0xf bound_ctrl:1
	v_fma_mix_f32 v19, v34, v31, v19 op_sel:[0,1,0] op_sel_hi:[1,1,0]
	v_fma_mix_f32 v10, v20, v28, v16 op_sel:[0,0,0] op_sel_hi:[0,1,0]
	v_fma_mix_f32 v11, v20, v28, v17 op_sel:[0,1,0] op_sel_hi:[0,1,0]
	v_fma_mix_f32 v12, v20, v29, v18 op_sel:[0,0,0] op_sel_hi:[0,1,0]
	v_fma_mix_f32 v13, v20, v29, v19 op_sel:[0,1,0] op_sel_hi:[0,1,0]
	s_waitcnt lgkmcnt(4)
	ds_read_b64 v[84:85], v6 offset:11280
	ds_read_b128 v[86:89], v6 offset:11536
	ds_read_b128 v[90:93], v6 offset:11792
	ds_read_u16 v94, v7 offset:11280
	v_fma_mix_f32 v14, v10, v38, 0 op_sel:[0,0,0] op_sel_hi:[0,1,0]
	v_fma_mix_f32 v56, v10, v32, 0 op_sel:[0,0,0] op_sel_hi:[0,1,0]
	v_fma_mix_f32 v14, v11, v38, v14 op_sel:[0,1,0] op_sel_hi:[0,1,0]
	v_fma_mix_f32 v56, v11, v32, v56 op_sel:[0,1,0] op_sel_hi:[0,1,0]
	v_fma_mix_f32 v14, v12, v39, v14 op_sel:[0,0,0] op_sel_hi:[0,1,0]
	v_fma_mix_f32 v56, v12, v33, v56 op_sel:[0,0,0] op_sel_hi:[0,1,0]
	v_fma_mix_f32 v14, v13, v39, v14 op_sel:[0,1,0] op_sel_hi:[0,1,0]
	v_fma_mix_f32 v16, v10, v36, 0 op_sel:[0,0,0] op_sel_hi:[0,1,0]
	v_fma_mix_f32 v17, v11, v36, 0 op_sel:[0,1,0] op_sel_hi:[0,1,0]
	v_add_f32_dpp v20, v14, v14 quad_perm:[1,0,3,2] row_mask:0xf bank_mask:0xf bound_ctrl:1
	v_fma_mix_f32 v56, v13, v33, v56 op_sel:[0,1,0] op_sel_hi:[0,1,0]
	v_fma_mix_f32 v18, v12, v37, 0 op_sel:[0,0,0] op_sel_hi:[0,1,0]
	v_add_f32_dpp v20, v20, v20 quad_perm:[2,3,0,1] row_mask:0xf bank_mask:0xf bound_ctrl:1
	v_fma_mix_f32 v19, v13, v37, 0 op_sel:[0,1,0] op_sel_hi:[0,1,0]
	v_fma_mix_f32 v16, v46, v42, v16 op_sel:[0,0,0] op_sel_hi:[1,1,0]
	v_add_f32_dpp v20, v20, v20 row_half_mirror row_mask:0xf bank_mask:0xf bound_ctrl:1
	v_fma_mix_f32 v17, v46, v42, v17 op_sel:[0,1,0] op_sel_hi:[1,1,0]
	v_fma_mix_f32 v18, v46, v43, v18 op_sel:[0,0,0] op_sel_hi:[1,1,0]
	v_add_f32_dpp v20, v20, v20 row_mirror row_mask:0xf bank_mask:0xf bound_ctrl:1
	v_fma_mix_f32 v19, v46, v43, v19 op_sel:[0,1,0] op_sel_hi:[1,1,0]
	v_fma_mix_f32 v10, v20, v40, v16 op_sel:[0,0,0] op_sel_hi:[0,1,0]
	v_fma_mix_f32 v11, v20, v40, v17 op_sel:[0,1,0] op_sel_hi:[0,1,0]
	v_fma_mix_f32 v12, v20, v41, v18 op_sel:[0,0,0] op_sel_hi:[0,1,0]
	v_fma_mix_f32 v13, v20, v41, v19 op_sel:[0,1,0] op_sel_hi:[0,1,0]
	s_waitcnt lgkmcnt(4)
	ds_read_b64 v[24:25], v6 offset:12304
	ds_read_b128 v[26:29], v6 offset:12560
	ds_read_b128 v[30:33], v6 offset:12816
	ds_read_u16 v34, v7 offset:12304
	v_fma_mix_f32 v14, v10, v74, 0 op_sel:[0,0,0] op_sel_hi:[0,1,0]
	v_fma_mix_f32 v57, v10, v44, 0 op_sel:[0,0,0] op_sel_hi:[0,1,0]
	v_fma_mix_f32 v14, v11, v74, v14 op_sel:[0,1,0] op_sel_hi:[0,1,0]
	v_fma_mix_f32 v57, v11, v44, v57 op_sel:[0,1,0] op_sel_hi:[0,1,0]
	v_fma_mix_f32 v14, v12, v75, v14 op_sel:[0,0,0] op_sel_hi:[0,1,0]
	v_fma_mix_f32 v57, v12, v45, v57 op_sel:[0,0,0] op_sel_hi:[0,1,0]
	v_fma_mix_f32 v14, v13, v75, v14 op_sel:[0,1,0] op_sel_hi:[0,1,0]
	v_fma_mix_f32 v16, v10, v72, 0 op_sel:[0,0,0] op_sel_hi:[0,1,0]
	v_fma_mix_f32 v17, v11, v72, 0 op_sel:[0,1,0] op_sel_hi:[0,1,0]
	v_add_f32_dpp v20, v14, v14 quad_perm:[1,0,3,2] row_mask:0xf bank_mask:0xf bound_ctrl:1
	v_fma_mix_f32 v57, v13, v45, v57 op_sel:[0,1,0] op_sel_hi:[0,1,0]
	v_fma_mix_f32 v18, v12, v73, 0 op_sel:[0,0,0] op_sel_hi:[0,1,0]
	v_add_f32_dpp v20, v20, v20 quad_perm:[2,3,0,1] row_mask:0xf bank_mask:0xf bound_ctrl:1
	v_fma_mix_f32 v19, v13, v73, 0 op_sel:[0,1,0] op_sel_hi:[0,1,0]
	v_fma_mix_f32 v16, v82, v78, v16 op_sel:[0,0,0] op_sel_hi:[1,1,0]
	v_add_f32_dpp v20, v20, v20 row_half_mirror row_mask:0xf bank_mask:0xf bound_ctrl:1
	v_fma_mix_f32 v17, v82, v78, v17 op_sel:[0,1,0] op_sel_hi:[1,1,0]
	v_fma_mix_f32 v18, v82, v79, v18 op_sel:[0,0,0] op_sel_hi:[1,1,0]
	v_add_f32_dpp v20, v20, v20 row_mirror row_mask:0xf bank_mask:0xf bound_ctrl:1
	v_fma_mix_f32 v19, v82, v79, v19 op_sel:[0,1,0] op_sel_hi:[1,1,0]
	v_fma_mix_f32 v10, v20, v76, v16 op_sel:[0,0,0] op_sel_hi:[0,1,0]
	v_fma_mix_f32 v11, v20, v76, v17 op_sel:[0,1,0] op_sel_hi:[0,1,0]
	v_fma_mix_f32 v12, v20, v77, v18 op_sel:[0,0,0] op_sel_hi:[0,1,0]
	v_fma_mix_f32 v13, v20, v77, v19 op_sel:[0,1,0] op_sel_hi:[0,1,0]
	s_waitcnt lgkmcnt(4)
	ds_read_b64 v[36:37], v6 offset:13328
	ds_read_b128 v[38:41], v6 offset:13584
	ds_read_b128 v[42:45], v6 offset:13840
	ds_read_u16 v46, v7 offset:13328
	v_fma_mix_f32 v14, v10, v86, 0 op_sel:[0,0,0] op_sel_hi:[0,1,0]
	v_fma_mix_f32 v58, v10, v80, 0 op_sel:[0,0,0] op_sel_hi:[0,1,0]
	v_fma_mix_f32 v14, v11, v86, v14 op_sel:[0,1,0] op_sel_hi:[0,1,0]
	v_fma_mix_f32 v58, v11, v80, v58 op_sel:[0,1,0] op_sel_hi:[0,1,0]
	v_fma_mix_f32 v14, v12, v87, v14 op_sel:[0,0,0] op_sel_hi:[0,1,0]
	v_fma_mix_f32 v58, v12, v81, v58 op_sel:[0,0,0] op_sel_hi:[0,1,0]
	v_fma_mix_f32 v14, v13, v87, v14 op_sel:[0,1,0] op_sel_hi:[0,1,0]
	v_fma_mix_f32 v16, v10, v84, 0 op_sel:[0,0,0] op_sel_hi:[0,1,0]
	v_fma_mix_f32 v17, v11, v84, 0 op_sel:[0,1,0] op_sel_hi:[0,1,0]
	v_add_f32_dpp v20, v14, v14 quad_perm:[1,0,3,2] row_mask:0xf bank_mask:0xf bound_ctrl:1
	v_fma_mix_f32 v58, v13, v81, v58 op_sel:[0,1,0] op_sel_hi:[0,1,0]
	v_fma_mix_f32 v18, v12, v85, 0 op_sel:[0,0,0] op_sel_hi:[0,1,0]
	v_add_f32_dpp v20, v20, v20 quad_perm:[2,3,0,1] row_mask:0xf bank_mask:0xf bound_ctrl:1
	v_fma_mix_f32 v19, v13, v85, 0 op_sel:[0,1,0] op_sel_hi:[0,1,0]
	v_fma_mix_f32 v16, v94, v90, v16 op_sel:[0,0,0] op_sel_hi:[1,1,0]
	v_add_f32_dpp v20, v20, v20 row_half_mirror row_mask:0xf bank_mask:0xf bound_ctrl:1
	v_fma_mix_f32 v17, v94, v90, v17 op_sel:[0,1,0] op_sel_hi:[1,1,0]
	v_fma_mix_f32 v18, v94, v91, v18 op_sel:[0,0,0] op_sel_hi:[1,1,0]
	v_add_f32_dpp v20, v20, v20 row_mirror row_mask:0xf bank_mask:0xf bound_ctrl:1
	v_fma_mix_f32 v19, v94, v91, v19 op_sel:[0,1,0] op_sel_hi:[1,1,0]
	v_fma_mix_f32 v10, v20, v88, v16 op_sel:[0,0,0] op_sel_hi:[0,1,0]
	v_fma_mix_f32 v11, v20, v88, v17 op_sel:[0,1,0] op_sel_hi:[0,1,0]
	v_fma_mix_f32 v12, v20, v89, v18 op_sel:[0,0,0] op_sel_hi:[0,1,0]
	v_fma_mix_f32 v13, v20, v89, v19 op_sel:[0,1,0] op_sel_hi:[0,1,0]
	s_waitcnt lgkmcnt(4)
	ds_read_b64 v[72:73], v6 offset:14352
	ds_read_b128 v[74:77], v6 offset:14608
	ds_read_b128 v[78:81], v6 offset:14864
	ds_read_u16 v82, v7 offset:14352
	v_fma_mix_f32 v14, v10, v26, 0 op_sel:[0,0,0] op_sel_hi:[0,1,0]
	v_fma_mix_f32 v59, v10, v92, 0 op_sel:[0,0,0] op_sel_hi:[0,1,0]
	v_fma_mix_f32 v14, v11, v26, v14 op_sel:[0,1,0] op_sel_hi:[0,1,0]
	v_fma_mix_f32 v59, v11, v92, v59 op_sel:[0,1,0] op_sel_hi:[0,1,0]
	v_fma_mix_f32 v14, v12, v27, v14 op_sel:[0,0,0] op_sel_hi:[0,1,0]
	v_fma_mix_f32 v59, v12, v93, v59 op_sel:[0,0,0] op_sel_hi:[0,1,0]
	v_fma_mix_f32 v14, v13, v27, v14 op_sel:[0,1,0] op_sel_hi:[0,1,0]
	v_fma_mix_f32 v16, v10, v24, 0 op_sel:[0,0,0] op_sel_hi:[0,1,0]
	v_fma_mix_f32 v17, v11, v24, 0 op_sel:[0,1,0] op_sel_hi:[0,1,0]
	v_add_f32_dpp v20, v14, v14 quad_perm:[1,0,3,2] row_mask:0xf bank_mask:0xf bound_ctrl:1
	v_fma_mix_f32 v59, v13, v93, v59 op_sel:[0,1,0] op_sel_hi:[0,1,0]
	v_fma_mix_f32 v18, v12, v25, 0 op_sel:[0,0,0] op_sel_hi:[0,1,0]
	v_add_f32_dpp v20, v20, v20 quad_perm:[2,3,0,1] row_mask:0xf bank_mask:0xf bound_ctrl:1
	v_fma_mix_f32 v19, v13, v25, 0 op_sel:[0,1,0] op_sel_hi:[0,1,0]
	v_fma_mix_f32 v16, v34, v30, v16 op_sel:[0,0,0] op_sel_hi:[1,1,0]
	v_add_f32_dpp v20, v20, v20 row_half_mirror row_mask:0xf bank_mask:0xf bound_ctrl:1
	v_fma_mix_f32 v17, v34, v30, v17 op_sel:[0,1,0] op_sel_hi:[1,1,0]
	v_fma_mix_f32 v18, v34, v31, v18 op_sel:[0,0,0] op_sel_hi:[1,1,0]
	v_add_f32_dpp v20, v20, v20 row_mirror row_mask:0xf bank_mask:0xf bound_ctrl:1
	v_fma_mix_f32 v19, v34, v31, v19 op_sel:[0,1,0] op_sel_hi:[1,1,0]
	v_fma_mix_f32 v10, v20, v28, v16 op_sel:[0,0,0] op_sel_hi:[0,1,0]
	v_fma_mix_f32 v11, v20, v28, v17 op_sel:[0,1,0] op_sel_hi:[0,1,0]
	v_fma_mix_f32 v12, v20, v29, v18 op_sel:[0,0,0] op_sel_hi:[0,1,0]
	v_fma_mix_f32 v13, v20, v29, v19 op_sel:[0,1,0] op_sel_hi:[0,1,0]
	s_waitcnt lgkmcnt(4)
	ds_read_b128 v[100:103], v9
	ds_read_b64 v[84:85], v6 offset:15376
	ds_read_b128 v[86:89], v6 offset:15632
	ds_read_b128 v[90:93], v6 offset:15888
	ds_read_u16 v94, v7 offset:15376
	v_fma_mix_f32 v14, v10, v38, 0 op_sel:[0,0,0] op_sel_hi:[0,1,0]
	v_fma_mix_f32 v60, v10, v32, 0 op_sel:[0,0,0] op_sel_hi:[0,1,0]
	v_fma_mix_f32 v14, v11, v38, v14 op_sel:[0,1,0] op_sel_hi:[0,1,0]
	v_fma_mix_f32 v60, v11, v32, v60 op_sel:[0,1,0] op_sel_hi:[0,1,0]
	v_fma_mix_f32 v14, v12, v39, v14 op_sel:[0,0,0] op_sel_hi:[0,1,0]
	v_fma_mix_f32 v60, v12, v33, v60 op_sel:[0,0,0] op_sel_hi:[0,1,0]
	v_fma_mix_f32 v14, v13, v39, v14 op_sel:[0,1,0] op_sel_hi:[0,1,0]
	v_fma_mix_f32 v16, v10, v36, 0 op_sel:[0,0,0] op_sel_hi:[0,1,0]
	v_fma_mix_f32 v17, v11, v36, 0 op_sel:[0,1,0] op_sel_hi:[0,1,0]
	v_add_f32_dpp v20, v14, v14 quad_perm:[1,0,3,2] row_mask:0xf bank_mask:0xf bound_ctrl:1
	v_fma_mix_f32 v60, v13, v33, v60 op_sel:[0,1,0] op_sel_hi:[0,1,0]
	v_fma_mix_f32 v18, v12, v37, 0 op_sel:[0,0,0] op_sel_hi:[0,1,0]
	v_add_f32_dpp v20, v20, v20 quad_perm:[2,3,0,1] row_mask:0xf bank_mask:0xf bound_ctrl:1
	v_fma_mix_f32 v19, v13, v37, 0 op_sel:[0,1,0] op_sel_hi:[0,1,0]
	v_fma_mix_f32 v16, v46, v42, v16 op_sel:[0,0,0] op_sel_hi:[1,1,0]
	v_add_f32_dpp v20, v20, v20 row_half_mirror row_mask:0xf bank_mask:0xf bound_ctrl:1
	v_fma_mix_f32 v17, v46, v42, v17 op_sel:[0,1,0] op_sel_hi:[1,1,0]
	v_fma_mix_f32 v18, v46, v43, v18 op_sel:[0,0,0] op_sel_hi:[1,1,0]
	v_add_f32_dpp v20, v20, v20 row_mirror row_mask:0xf bank_mask:0xf bound_ctrl:1
	v_fma_mix_f32 v19, v46, v43, v19 op_sel:[0,1,0] op_sel_hi:[1,1,0]
	v_fma_mix_f32 v10, v20, v40, v16 op_sel:[0,0,0] op_sel_hi:[0,1,0]
	v_fma_mix_f32 v11, v20, v40, v17 op_sel:[0,1,0] op_sel_hi:[0,1,0]
	v_fma_mix_f32 v12, v20, v41, v18 op_sel:[0,0,0] op_sel_hi:[0,1,0]
	v_fma_mix_f32 v13, v20, v41, v19 op_sel:[0,1,0] op_sel_hi:[0,1,0]
	s_waitcnt lgkmcnt(4)
; DEVINL u16 f2bf(float a) { return (u16)(pk2(a, 0.f) & 0xffffu); }
; #define RW_STEP2(B) RW_STEP(B, WvA, XA, KrA, vhA, WvB, XB, KrB, vhB); RW_STEP((B) + 1, WvB, XB, KrB, vhB, WvA, XA, KrA, vhA)
; #define RW_STEP4(B) RW_STEP2(B); RW_STEP2((B) + 2)
; template <int DIR>
; DEVINL void rwkv_scan_dir(const Params& p, int task, int lane, int wave) {
;     ...
;   for (int st = 0; st < 4096; st += 32) {
;     RW_STEP(0, WvA, XA, KrA, vhA, WvB, XB, KrB, vhB);
;     if (st > 0) { const int q0 = st - 16 + seg; yo[(long)(DIR ? (4095 - q0) : q0) * 1024] = f2bf(ykeep); }
;     RW_STEP(1, WvB, XB, KrB, vhB, WvA, XA, KrA, vhA);
;     RW_STEP2(2); RW_STEP4(4); RW_STEP4(8); RW_STEP4(12);
	v_add_u32_e32 v6, 0x4000, v6
	v_add_u32_e32 v7, 0x4000, v7
	v_and_b32_e32 v6, 0x1ffff, v6
	v_and_b32_e32 v7, 0x1ffff, v7
	ds_read_b64 v[24:25], v6 offset:16
	ds_read_b128 v[26:29], v6 offset:272
	ds_read_b128 v[30:33], v6 offset:528
	ds_read_u16 v34, v7 offset:16
	v_fma_mix_f32 v14, v10, v74, 0 op_sel:[0,0,0] op_sel_hi:[0,1,0]
	v_fma_mix_f32 v61, v10, v44, 0 op_sel:[0,0,0] op_sel_hi:[0,1,0]
	v_fma_mix_f32 v14, v11, v74, v14 op_sel:[0,1,0] op_sel_hi:[0,1,0]
	v_fma_mix_f32 v61, v11, v44, v61 op_sel:[0,1,0] op_sel_hi:[0,1,0]
	v_fma_mix_f32 v14, v12, v75, v14 op_sel:[0,0,0] op_sel_hi:[0,1,0]
	v_fma_mix_f32 v61, v12, v45, v61 op_sel:[0,0,0] op_sel_hi:[0,1,0]
	v_fma_mix_f32 v14, v13, v75, v14 op_sel:[0,1,0] op_sel_hi:[0,1,0]
	v_fma_mix_f32 v16, v10, v72, 0 op_sel:[0,0,0] op_sel_hi:[0,1,0]
	v_fma_mix_f32 v17, v11, v72, 0 op_sel:[0,1,0] op_sel_hi:[0,1,0]
	v_add_f32_dpp v20, v14, v14 quad_perm:[1,0,3,2] row_mask:0xf bank_mask:0xf bound_ctrl:1
	v_fma_mix_f32 v61, v13, v45, v61 op_sel:[0,1,0] op_sel_hi:[0,1,0]
	v_fma_mix_f32 v18, v12, v73, 0 op_sel:[0,0,0] op_sel_hi:[0,1,0]
	v_add_f32_dpp v20, v20, v20 quad_perm:[2,3,0,1] row_mask:0xf bank_mask:0xf bound_ctrl:1
	v_fma_mix_f32 v19, v13, v73, 0 op_sel:[0,1,0] op_sel_hi:[0,1,0]
	v_fma_mix_f32 v16, v82, v78, v16 op_sel:[0,0,0] op_sel_hi:[1,1,0]
	v_add_f32_dpp v20, v20, v20 row_half_mirror row_mask:0xf bank_mask:0xf bound_ctrl:1
	v_fma_mix_f32 v17, v82, v78, v17 op_sel:[0,1,0] op_sel_hi:[1,1,0]
	v_fma_mix_f32 v18, v82, v79, v18 op_sel:[0,0,0] op_sel_hi:[1,1,0]
	v_add_f32_dpp v20, v20, v20 row_mirror row_mask:0xf bank_mask:0xf bound_ctrl:1
	v_fma_mix_f32 v19, v82, v79, v19 op_sel:[0,1,0] op_sel_hi:[1,1,0]
	v_fma_mix_f32 v10, v20, v76, v16 op_sel:[0,0,0] op_sel_hi:[0,1,0]
	v_fma_mix_f32 v11, v20, v76, v17 op_sel:[0,1,0] op_sel_hi:[0,1,0]
	v_fma_mix_f32 v12, v20, v77, v18 op_sel:[0,0,0] op_sel_hi:[0,1,0]
	v_fma_mix_f32 v13, v20, v77, v19 op_sel:[0,1,0] op_sel_hi:[0,1,0]
	s_waitcnt lgkmcnt(4)
	ds_read_b64 v[36:37], v6 offset:1040
	ds_read_b128 v[38:41], v6 offset:1296
	ds_read_b128 v[42:45], v6 offset:1552
	ds_read_u16 v46, v7 offset:1040
	v_fma_mix_f32 v14, v10, v86, 0 op_sel:[0,0,0] op_sel_hi:[0,1,0]
	v_fma_mix_f32 v62, v10, v80, 0 op_sel:[0,0,0] op_sel_hi:[0,1,0]
	v_fma_mix_f32 v14, v11, v86, v14 op_sel:[0,1,0] op_sel_hi:[0,1,0]
	v_fma_mix_f32 v62, v11, v80, v62 op_sel:[0,1,0] op_sel_hi:[0,1,0]
	v_fma_mix_f32 v14, v12, v87, v14 op_sel:[0,0,0] op_sel_hi:[0,1,0]
	v_fma_mix_f32 v62, v12, v81, v62 op_sel:[0,0,0] op_sel_hi:[0,1,0]
	v_fma_mix_f32 v14, v13, v87, v14 op_sel:[0,1,0] op_sel_hi:[0,1,0]
	v_fma_mix_f32 v16, v10, v84, 0 op_sel:[0,0,0] op_sel_hi:[0,1,0]
	v_fma_mix_f32 v17, v11, v84, 0 op_sel:[0,1,0] op_sel_hi:[0,1,0]
	v_add_f32_dpp v20, v14, v14 quad_perm:[1,0,3,2] row_mask:0xf bank_mask:0xf bound_ctrl:1
	v_fma_mix_f32 v62, v13, v81, v62 op_sel:[0,1,0] op_sel_hi:[0,1,0]
	v_fma_mix_f32 v18, v12, v85, 0 op_sel:[0,0,0] op_sel_hi:[0,1,0]
	v_add_f32_dpp v20, v20, v20 quad_perm:[2,3,0,1] row_mask:0xf bank_mask:0xf bound_ctrl:1
	v_fma_mix_f32 v19, v13, v85, 0 op_sel:[0,1,0] op_sel_hi:[0,1,0]
	v_fma_mix_f32 v16, v94, v90, v16 op_sel:[0,0,0] op_sel_hi:[1,1,0]
	v_add_f32_dpp v20, v20, v20 row_half_mirror row_mask:0xf bank_mask:0xf bound_ctrl:1
	v_fma_mix_f32 v17, v94, v90, v17 op_sel:[0,1,0] op_sel_hi:[1,1,0]
	v_fma_mix_f32 v18, v94, v91, v18 op_sel:[0,0,0] op_sel_hi:[1,1,0]
	v_add_f32_dpp v20, v20, v20 row_mirror row_mask:0xf bank_mask:0xf bound_ctrl:1
	v_fma_mix_f32 v19, v94, v91, v19 op_sel:[0,1,0] op_sel_hi:[1,1,0]
	v_fma_mix_f32 v10, v20, v88, v16 op_sel:[0,0,0] op_sel_hi:[0,1,0]
	v_fma_mix_f32 v11, v20, v88, v17 op_sel:[0,1,0] op_sel_hi:[0,1,0]
	v_fma_mix_f32 v12, v20, v89, v18 op_sel:[0,0,0] op_sel_hi:[0,1,0]
	v_fma_mix_f32 v13, v20, v89, v19 op_sel:[0,1,0] op_sel_hi:[0,1,0]
	s_waitcnt lgkmcnt(4)
	s_add_u32 s43, s43, 1
.Lrw_blk_d0:
	s_waitcnt vmcnt(1)
	v_add_u32_e32 v69, 1, v69
	ds_write_b32 v23, v69
	v_min3_u32 v100, v100, v101, v102
	v_min_u32_e32 v100, v100, v103
	s_nop 0
	v_readfirstlane_b32 s24, v100
	s_nop 0
	s_cmp_ge_u32 s24, s43
	s_cbranch_scc0 .Lrw_slow_d0
.Lrw_ready_d0:
	s_add_u32 m0, s41, 16
	s_nop 0
	global_load_lds_dwordx4 v5, s[10:11] offset:0
	global_load_lds_dwordx4 v5, s[10:11] offset:1024
	global_load_lds_dwordx4 v5, s[10:11] offset:2048
	global_load_lds_dwordx4 v5, s[10:11] offset:3072
	s_add_u32 s10, s10, 0x4000
	s_addc_u32 s11, s11, 0
	s_add_u32 s41, s41, 0x4000
	s_and_b32 s41, s41, 0x1ffff
	ds_read_b64 v[72:73], v6 offset:2064
	ds_read_b128 v[74:77], v6 offset:2320
	ds_read_b128 v[78:81], v6 offset:2576
	ds_read_u16 v82, v7 offset:2064
	v_fma_mix_f32 v14, v10, v26, 0 op_sel:[0,0,0] op_sel_hi:[0,1,0]
	v_fma_mix_f32 v63, v10, v92, 0 op_sel:[0,0,0] op_sel_hi:[0,1,0]
	v_fma_mix_f32 v14, v11, v26, v14 op_sel:[0,1,0] op_sel_hi:[0,1,0]
	v_fma_mix_f32 v63, v11, v92, v63 op_sel:[0,1,0] op_sel_hi:[0,1,0]
	v_fma_mix_f32 v14, v12, v27, v14 op_sel:[0,0,0] op_sel_hi:[0,1,0]
	v_fma_mix_f32 v63, v12, v93, v63 op_sel:[0,0,0] op_sel_hi:[0,1,0]
	v_fma_mix_f32 v14, v13, v27, v14 op_sel:[0,1,0] op_sel_hi:[0,1,0]
	v_fma_mix_f32 v16, v10, v24, 0 op_sel:[0,0,0] op_sel_hi:[0,1,0]
	v_fma_mix_f32 v17, v11, v24, 0 op_sel:[0,1,0] op_sel_hi:[0,1,0]
	v_add_f32_dpp v20, v14, v14 quad_perm:[1,0,3,2] row_mask:0xf bank_mask:0xf bound_ctrl:1
	v_fma_mix_f32 v63, v13, v93, v63 op_sel:[0,1,0] op_sel_hi:[0,1,0]
	v_fma_mix_f32 v18, v12, v25, 0 op_sel:[0,0,0] op_sel_hi:[0,1,0]
	v_add_f32_dpp v20, v20, v20 quad_perm:[2,3,0,1] row_mask:0xf bank_mask:0xf bound_ctrl:1
	v_fma_mix_f32 v19, v13, v25, 0 op_sel:[0,1,0] op_sel_hi:[0,1,0]
	v_fma_mix_f32 v16, v34, v30, v16 op_sel:[0,0,0] op_sel_hi:[1,1,0]
	v_add_f32_dpp v20, v20, v20 row_half_mirror row_mask:0xf bank_mask:0xf bound_ctrl:1
	v_fma_mix_f32 v17, v34, v30, v17 op_sel:[0,1,0] op_sel_hi:[1,1,0]
	v_fma_mix_f32 v18, v34, v31, v18 op_sel:[0,0,0] op_sel_hi:[1,1,0]
	v_add_f32_dpp v20, v20, v20 row_mirror row_mask:0xf bank_mask:0xf bound_ctrl:1
	v_fma_mix_f32 v19, v34, v31, v19 op_sel:[0,1,0] op_sel_hi:[1,1,0]
	v_fma_mix_f32 v10, v20, v28, v16 op_sel:[0,0,0] op_sel_hi:[0,1,0]
	v_fma_mix_f32 v11, v20, v28, v17 op_sel:[0,1,0] op_sel_hi:[0,1,0]
	v_fma_mix_f32 v12, v20, v29, v18 op_sel:[0,0,0] op_sel_hi:[0,1,0]
	v_fma_mix_f32 v13, v20, v29, v19 op_sel:[0,1,0] op_sel_hi:[0,1,0]
	s_waitcnt lgkmcnt(4)
; DEVINL u16 f2bf(float a) { return (u16)(pk2(a, 0.f) & 0xffffu); }
; #define RW_STEP2(B) RW_STEP(B, WvA, XA, KrA, vhA, WvB, XB, KrB, vhB); RW_STEP((B) + 1, WvB, XB, KrB, vhB, WvA, XA, KrA, vhA)
; #define RW_STEP4(B) RW_STEP2(B); RW_STEP2((B) + 2)
; template <int DIR>
; DEVINL void rwkv_scan_dir(const Params& p, int task, int lane, int wave) {
;     ...
;     if (st > 0) { const int q0 = st - 16 + seg; yo[(long)(DIR ? (4095 - q0) : q0) * 1024] = f2bf(ykeep); }
;     RW_STEP(1, WvB, XB, KrB, vhB, WvA, XA, KrA, vhA);
;     RW_STEP2(2); RW_STEP4(4); RW_STEP4(8); RW_STEP4(12);
;     RW_STEP(16, WvA, XA, KrA, vhA, WvB, XB, KrB, vhB);
;     { const int q0 = st + seg; yo[(long)(DIR ? (4095 - q0) : q0) * 1024] = f2bf(ykeep); }
	v_add_f32_dpp v48, v48, v48 row_ror:8 row_mask:0xf bank_mask:0x3
	v_add_f32_dpp v49, v49, v49 row_ror:8 row_mask:0xf bank_mask:0x3
	v_add_f32_dpp v50, v50, v50 row_ror:8 row_mask:0xf bank_mask:0x3
	v_add_f32_dpp v51, v51, v51 row_ror:8 row_mask:0xf bank_mask:0x3
	v_add_f32_dpp v52, v52, v52 row_ror:8 row_mask:0xf bank_mask:0x3
	v_add_f32_dpp v53, v53, v53 row_ror:8 row_mask:0xf bank_mask:0x3
	v_add_f32_dpp v54, v54, v54 row_ror:8 row_mask:0xf bank_mask:0x3
	v_add_f32_dpp v55, v55, v55 row_ror:8 row_mask:0xf bank_mask:0x3
	v_add_f32_dpp v48, v56, v56 row_ror:8 row_mask:0xf bank_mask:0xc
	v_add_f32_dpp v49, v57, v57 row_ror:8 row_mask:0xf bank_mask:0xc
	v_add_f32_dpp v50, v58, v58 row_ror:8 row_mask:0xf bank_mask:0xc
	v_add_f32_dpp v51, v59, v59 row_ror:8 row_mask:0xf bank_mask:0xc
	v_add_f32_dpp v52, v60, v60 row_ror:8 row_mask:0xf bank_mask:0xc
	v_add_f32_dpp v53, v61, v61 row_ror:8 row_mask:0xf bank_mask:0xc
	v_add_f32_dpp v54, v62, v62 row_ror:8 row_mask:0xf bank_mask:0xc
	v_add_f32_dpp v55, v63, v63 row_ror:8 row_mask:0xf bank_mask:0xc
	v_add_f32_dpp v48, v48, v48 row_ror:12 row_mask:0xf bank_mask:0x5
	v_add_f32_dpp v49, v49, v49 row_ror:12 row_mask:0xf bank_mask:0x5
	v_add_f32_dpp v50, v50, v50 row_ror:12 row_mask:0xf bank_mask:0x5
	v_add_f32_dpp v51, v51, v51 row_ror:12 row_mask:0xf bank_mask:0x5
	v_add_f32_dpp v48, v52, v52 row_ror:4 row_mask:0xf bank_mask:0xa
	v_add_f32_dpp v49, v53, v53 row_ror:4 row_mask:0xf bank_mask:0xa
	v_add_f32_dpp v50, v54, v54 row_ror:4 row_mask:0xf bank_mask:0xa
	v_add_f32_dpp v51, v55, v55 row_ror:4 row_mask:0xf bank_mask:0xa
	v_add_f32_dpp v64, v48, v48 quad_perm:[2,3,0,1] row_mask:0xf bank_mask:0xf bound_ctrl:1
	v_add_f32_dpp v65, v50, v50 quad_perm:[2,3,0,1] row_mask:0xf bank_mask:0xf bound_ctrl:1
	v_cndmask_b32_e64 v56, v64, v65, s[50:51]
	v_add_f32_dpp v64, v49, v49 quad_perm:[2,3,0,1] row_mask:0xf bank_mask:0xf bound_ctrl:1
	v_add_f32_dpp v65, v51, v51 quad_perm:[2,3,0,1] row_mask:0xf bank_mask:0xf bound_ctrl:1
	v_cndmask_b32_e64 v57, v64, v65, s[50:51]
	v_add_f32_dpp v64, v56, v56 quad_perm:[1,0,3,2] row_mask:0xf bank_mask:0xf bound_ctrl:1
	s_nop 0
	v_add_f32_dpp v65, v57, v57 quad_perm:[1,0,3,2] row_mask:0xf bank_mask:0xf bound_ctrl:1
	v_cndmask_b32_e64 v66, v64, v65, s[48:49]
	v_cvt_pk_bf16_f32 v66, v66, v66
	global_store_short v8, v66, s[12:13]
	s_add_u32 s12, s12, 0x8000
	s_addc_u32 s13, s13, 0
	ds_read_b64 v[84:85], v6 offset:3088
	ds_read_b128 v[86:89], v6 offset:3344
	ds_read_b128 v[90:93], v6 offset:3600
	ds_read_u16 v94, v7 offset:3088
	v_fma_mix_f32 v14, v10, v38, 0 op_sel:[0,0,0] op_sel_hi:[0,1,0]
	v_fma_mix_f32 v48, v10, v32, 0 op_sel:[0,0,0] op_sel_hi:[0,1,0]
	v_fma_mix_f32 v14, v11, v38, v14 op_sel:[0,1,0] op_sel_hi:[0,1,0]
	v_fma_mix_f32 v48, v11, v32, v48 op_sel:[0,1,0] op_sel_hi:[0,1,0]
	v_fma_mix_f32 v14, v12, v39, v14 op_sel:[0,0,0] op_sel_hi:[0,1,0]
	v_fma_mix_f32 v48, v12, v33, v48 op_sel:[0,0,0] op_sel_hi:[0,1,0]
	v_fma_mix_f32 v14, v13, v39, v14 op_sel:[0,1,0] op_sel_hi:[0,1,0]
	v_fma_mix_f32 v16, v10, v36, 0 op_sel:[0,0,0] op_sel_hi:[0,1,0]
	v_fma_mix_f32 v17, v11, v36, 0 op_sel:[0,1,0] op_sel_hi:[0,1,0]
	v_add_f32_dpp v20, v14, v14 quad_perm:[1,0,3,2] row_mask:0xf bank_mask:0xf bound_ctrl:1
	v_fma_mix_f32 v48, v13, v33, v48 op_sel:[0,1,0] op_sel_hi:[0,1,0]
	v_fma_mix_f32 v18, v12, v37, 0 op_sel:[0,0,0] op_sel_hi:[0,1,0]
	v_add_f32_dpp v20, v20, v20 quad_perm:[2,3,0,1] row_mask:0xf bank_mask:0xf bound_ctrl:1
	v_fma_mix_f32 v19, v13, v37, 0 op_sel:[0,1,0] op_sel_hi:[0,1,0]
	v_fma_mix_f32 v16, v46, v42, v16 op_sel:[0,0,0] op_sel_hi:[1,1,0]
	v_add_f32_dpp v20, v20, v20 row_half_mirror row_mask:0xf bank_mask:0xf bound_ctrl:1
	v_fma_mix_f32 v17, v46, v42, v17 op_sel:[0,1,0] op_sel_hi:[1,1,0]
	v_fma_mix_f32 v18, v46, v43, v18 op_sel:[0,0,0] op_sel_hi:[1,1,0]
	v_add_f32_dpp v20, v20, v20 row_mirror row_mask:0xf bank_mask:0xf bound_ctrl:1
	v_fma_mix_f32 v19, v46, v43, v19 op_sel:[0,1,0] op_sel_hi:[1,1,0]
	v_fma_mix_f32 v10, v20, v40, v16 op_sel:[0,0,0] op_sel_hi:[0,1,0]
	v_fma_mix_f32 v11, v20, v40, v17 op_sel:[0,1,0] op_sel_hi:[0,1,0]
	v_fma_mix_f32 v12, v20, v41, v18 op_sel:[0,0,0] op_sel_hi:[0,1,0]
	v_fma_mix_f32 v13, v20, v41, v19 op_sel:[0,1,0] op_sel_hi:[0,1,0]
	s_waitcnt lgkmcnt(4)
	ds_read_b64 v[24:25], v6 offset:4112
	ds_read_b128 v[26:29], v6 offset:4368
	ds_read_b128 v[30:33], v6 offset:4624
	ds_read_u16 v34, v7 offset:4112
	v_fma_mix_f32 v14, v10, v74, 0 op_sel:[0,0,0] op_sel_hi:[0,1,0]
	v_fma_mix_f32 v49, v10, v44, 0 op_sel:[0,0,0] op_sel_hi:[0,1,0]
	v_fma_mix_f32 v14, v11, v74, v14 op_sel:[0,1,0] op_sel_hi:[0,1,0]
	v_fma_mix_f32 v49, v11, v44, v49 op_sel:[0,1,0] op_sel_hi:[0,1,0]
	v_fma_mix_f32 v14, v12, v75, v14 op_sel:[0,0,0] op_sel_hi:[0,1,0]
	v_fma_mix_f32 v49, v12, v45, v49 op_sel:[0,0,0] op_sel_hi:[0,1,0]
	v_fma_mix_f32 v14, v13, v75, v14 op_sel:[0,1,0] op_sel_hi:[0,1,0]
	v_fma_mix_f32 v16, v10, v72, 0 op_sel:[0,0,0] op_sel_hi:[0,1,0]
	v_fma_mix_f32 v17, v11, v72, 0 op_sel:[0,1,0] op_sel_hi:[0,1,0]
	v_add_f32_dpp v20, v14, v14 quad_perm:[1,0,3,2] row_mask:0xf bank_mask:0xf bound_ctrl:1
	v_fma_mix_f32 v49, v13, v45, v49 op_sel:[0,1,0] op_sel_hi:[0,1,0]
	v_fma_mix_f32 v18, v12, v73, 0 op_sel:[0,0,0] op_sel_hi:[0,1,0]
	v_add_f32_dpp v20, v20, v20 quad_perm:[2,3,0,1] row_mask:0xf bank_mask:0xf bound_ctrl:1
	v_fma_mix_f32 v19, v13, v73, 0 op_sel:[0,1,0] op_sel_hi:[0,1,0]
	v_fma_mix_f32 v16, v82, v78, v16 op_sel:[0,0,0] op_sel_hi:[1,1,0]
	v_add_f32_dpp v20, v20, v20 row_half_mirror row_mask:0xf bank_mask:0xf bound_ctrl:1
	v_fma_mix_f32 v17, v82, v78, v17 op_sel:[0,1,0] op_sel_hi:[1,1,0]
	v_fma_mix_f32 v18, v82, v79, v18 op_sel:[0,0,0] op_sel_hi:[1,1,0]
	v_add_f32_dpp v20, v20, v20 row_mirror row_mask:0xf bank_mask:0xf bound_ctrl:1
	v_fma_mix_f32 v19, v82, v79, v19 op_sel:[0,1,0] op_sel_hi:[1,1,0]
	v_fma_mix_f32 v10, v20, v76, v16 op_sel:[0,0,0] op_sel_hi:[0,1,0]
	v_fma_mix_f32 v11, v20, v76, v17 op_sel:[0,1,0] op_sel_hi:[0,1,0]
	v_fma_mix_f32 v12, v20, v77, v18 op_sel:[0,0,0] op_sel_hi:[0,1,0]
	v_fma_mix_f32 v13, v20, v77, v19 op_sel:[0,1,0] op_sel_hi:[0,1,0]
	s_waitcnt lgkmcnt(4)
	ds_read_b64 v[36:37], v6 offset:5136
	ds_read_b128 v[38:41], v6 offset:5392
	ds_read_b128 v[42:45], v6 offset:5648
	ds_read_u16 v46, v7 offset:5136
	v_fma_mix_f32 v14, v10, v86, 0 op_sel:[0,0,0] op_sel_hi:[0,1,0]
	v_fma_mix_f32 v50, v10, v80, 0 op_sel:[0,0,0] op_sel_hi:[0,1,0]
	v_fma_mix_f32 v14, v11, v86, v14 op_sel:[0,1,0] op_sel_hi:[0,1,0]
	v_fma_mix_f32 v50, v11, v80, v50 op_sel:[0,1,0] op_sel_hi:[0,1,0]
	v_fma_mix_f32 v14, v12, v87, v14 op_sel:[0,0,0] op_sel_hi:[0,1,0]
	v_fma_mix_f32 v50, v12, v81, v50 op_sel:[0,0,0] op_sel_hi:[0,1,0]
	v_fma_mix_f32 v14, v13, v87, v14 op_sel:[0,1,0] op_sel_hi:[0,1,0]
	v_fma_mix_f32 v16, v10, v84, 0 op_sel:[0,0,0] op_sel_hi:[0,1,0]
	v_fma_mix_f32 v17, v11, v84, 0 op_sel:[0,1,0] op_sel_hi:[0,1,0]
	v_add_f32_dpp v20, v14, v14 quad_perm:[1,0,3,2] row_mask:0xf bank_mask:0xf bound_ctrl:1
	v_fma_mix_f32 v50, v13, v81, v50 op_sel:[0,1,0] op_sel_hi:[0,1,0]
	v_fma_mix_f32 v18, v12, v85, 0 op_sel:[0,0,0] op_sel_hi:[0,1,0]
	v_add_f32_dpp v20, v20, v20 quad_perm:[2,3,0,1] row_mask:0xf bank_mask:0xf bound_ctrl:1
	v_fma_mix_f32 v19, v13, v85, 0 op_sel:[0,1,0] op_sel_hi:[0,1,0]
	v_fma_mix_f32 v16, v94, v90, v16 op_sel:[0,0,0] op_sel_hi:[1,1,0]
	v_add_f32_dpp v20, v20, v20 row_half_mirror row_mask:0xf bank_mask:0xf bound_ctrl:1
	v_fma_mix_f32 v17, v94, v90, v17 op_sel:[0,1,0] op_sel_hi:[1,1,0]
	v_fma_mix_f32 v18, v94, v91, v18 op_sel:[0,0,0] op_sel_hi:[1,1,0]
	v_add_f32_dpp v20, v20, v20 row_mirror row_mask:0xf bank_mask:0xf bound_ctrl:1
	v_fma_mix_f32 v19, v94, v91, v19 op_sel:[0,1,0] op_sel_hi:[1,1,0]
	v_fma_mix_f32 v10, v20, v88, v16 op_sel:[0,0,0] op_sel_hi:[0,1,0]
	v_fma_mix_f32 v11, v20, v88, v17 op_sel:[0,1,0] op_sel_hi:[0,1,0]
	v_fma_mix_f32 v12, v20, v89, v18 op_sel:[0,0,0] op_sel_hi:[0,1,0]
	v_fma_mix_f32 v13, v20, v89, v19 op_sel:[0,1,0] op_sel_hi:[0,1,0]
	s_waitcnt lgkmcnt(4)
	ds_read_b64 v[72:73], v6 offset:6160
	ds_read_b128 v[74:77], v6 offset:6416
	ds_read_b128 v[78:81], v6 offset:6672
	ds_read_u16 v82, v7 offset:6160
	v_fma_mix_f32 v14, v10, v26, 0 op_sel:[0,0,0] op_sel_hi:[0,1,0]
	v_fma_mix_f32 v51, v10, v92, 0 op_sel:[0,0,0] op_sel_hi:[0,1,0]
	v_fma_mix_f32 v14, v11, v26, v14 op_sel:[0,1,0] op_sel_hi:[0,1,0]
	v_fma_mix_f32 v51, v11, v92, v51 op_sel:[0,1,0] op_sel_hi:[0,1,0]
	v_fma_mix_f32 v14, v12, v27, v14 op_sel:[0,0,0] op_sel_hi:[0,1,0]
	v_fma_mix_f32 v51, v12, v93, v51 op_sel:[0,0,0] op_sel_hi:[0,1,0]
	v_fma_mix_f32 v14, v13, v27, v14 op_sel:[0,1,0] op_sel_hi:[0,1,0]
	v_fma_mix_f32 v16, v10, v24, 0 op_sel:[0,0,0] op_sel_hi:[0,1,0]
	v_fma_mix_f32 v17, v11, v24, 0 op_sel:[0,1,0] op_sel_hi:[0,1,0]
	v_add_f32_dpp v20, v14, v14 quad_perm:[1,0,3,2] row_mask:0xf bank_mask:0xf bound_ctrl:1
	v_fma_mix_f32 v51, v13, v93, v51 op_sel:[0,1,0] op_sel_hi:[0,1,0]
	v_fma_mix_f32 v18, v12, v25, 0 op_sel:[0,0,0] op_sel_hi:[0,1,0]
	v_add_f32_dpp v20, v20, v20 quad_perm:[2,3,0,1] row_mask:0xf bank_mask:0xf bound_ctrl:1
	v_fma_mix_f32 v19, v13, v25, 0 op_sel:[0,1,0] op_sel_hi:[0,1,0]
	v_fma_mix_f32 v16, v34, v30, v16 op_sel:[0,0,0] op_sel_hi:[1,1,0]
	v_add_f32_dpp v20, v20, v20 row_half_mirror row_mask:0xf bank_mask:0xf bound_ctrl:1
	v_fma_mix_f32 v17, v34, v30, v17 op_sel:[0,1,0] op_sel_hi:[1,1,0]
	v_fma_mix_f32 v18, v34, v31, v18 op_sel:[0,0,0] op_sel_hi:[1,1,0]
	v_add_f32_dpp v20, v20, v20 row_mirror row_mask:0xf bank_mask:0xf bound_ctrl:1
	v_fma_mix_f32 v19, v34, v31, v19 op_sel:[0,1,0] op_sel_hi:[1,1,0]
	v_fma_mix_f32 v10, v20, v28, v16 op_sel:[0,0,0] op_sel_hi:[0,1,0]
	v_fma_mix_f32 v11, v20, v28, v17 op_sel:[0,1,0] op_sel_hi:[0,1,0]
	v_fma_mix_f32 v12, v20, v29, v18 op_sel:[0,0,0] op_sel_hi:[0,1,0]
	v_fma_mix_f32 v13, v20, v29, v19 op_sel:[0,1,0] op_sel_hi:[0,1,0]
	s_waitcnt lgkmcnt(4)
	ds_read_b64 v[84:85], v6 offset:7184
	ds_read_b128 v[86:89], v6 offset:7440
	ds_read_b128 v[90:93], v6 offset:7696
	ds_read_u16 v94, v7 offset:7184
	v_fma_mix_f32 v14, v10, v38, 0 op_sel:[0,0,0] op_sel_hi:[0,1,0]
	v_fma_mix_f32 v52, v10, v32, 0 op_sel:[0,0,0] op_sel_hi:[0,1,0]
	v_fma_mix_f32 v14, v11, v38, v14 op_sel:[0,1,0] op_sel_hi:[0,1,0]
	v_fma_mix_f32 v52, v11, v32, v52 op_sel:[0,1,0] op_sel_hi:[0,1,0]
	v_fma_mix_f32 v14, v12, v39, v14 op_sel:[0,0,0] op_sel_hi:[0,1,0]
	v_fma_mix_f32 v52, v12, v33, v52 op_sel:[0,0,0] op_sel_hi:[0,1,0]
	v_fma_mix_f32 v14, v13, v39, v14 op_sel:[0,1,0] op_sel_hi:[0,1,0]
	v_fma_mix_f32 v16, v10, v36, 0 op_sel:[0,0,0] op_sel_hi:[0,1,0]
	v_fma_mix_f32 v17, v11, v36, 0 op_sel:[0,1,0] op_sel_hi:[0,1,0]
	v_add_f32_dpp v20, v14, v14 quad_perm:[1,0,3,2] row_mask:0xf bank_mask:0xf bound_ctrl:1
	v_fma_mix_f32 v52, v13, v33, v52 op_sel:[0,1,0] op_sel_hi:[0,1,0]
	v_fma_mix_f32 v18, v12, v37, 0 op_sel:[0,0,0] op_sel_hi:[0,1,0]
	v_add_f32_dpp v20, v20, v20 quad_perm:[2,3,0,1] row_mask:0xf bank_mask:0xf bound_ctrl:1
	v_fma_mix_f32 v19, v13, v37, 0 op_sel:[0,1,0] op_sel_hi:[0,1,0]
	v_fma_mix_f32 v16, v46, v42, v16 op_sel:[0,0,0] op_sel_hi:[1,1,0]
	v_add_f32_dpp v20, v20, v20 row_half_mirror row_mask:0xf bank_mask:0xf bound_ctrl:1
	v_fma_mix_f32 v17, v46, v42, v17 op_sel:[0,1,0] op_sel_hi:[1,1,0]
	v_fma_mix_f32 v18, v46, v43, v18 op_sel:[0,0,0] op_sel_hi:[1,1,0]
	v_add_f32_dpp v20, v20, v20 row_mirror row_mask:0xf bank_mask:0xf bound_ctrl:1
	v_fma_mix_f32 v19, v46, v43, v19 op_sel:[0,1,0] op_sel_hi:[1,1,0]
	v_fma_mix_f32 v10, v20, v40, v16 op_sel:[0,0,0] op_sel_hi:[0,1,0]
	v_fma_mix_f32 v11, v20, v40, v17 op_sel:[0,1,0] op_sel_hi:[0,1,0]
	v_fma_mix_f32 v12, v20, v41, v18 op_sel:[0,0,0] op_sel_hi:[0,1,0]
	v_fma_mix_f32 v13, v20, v41, v19 op_sel:[0,1,0] op_sel_hi:[0,1,0]
	s_waitcnt lgkmcnt(4)
	ds_read_b64 v[24:25], v6 offset:8208
	ds_read_b128 v[26:29], v6 offset:8464
	ds_read_b128 v[30:33], v6 offset:8720
	ds_read_u16 v34, v7 offset:8208
	v_fma_mix_f32 v14, v10, v74, 0 op_sel:[0,0,0] op_sel_hi:[0,1,0]
	v_fma_mix_f32 v53, v10, v44, 0 op_sel:[0,0,0] op_sel_hi:[0,1,0]
	v_fma_mix_f32 v14, v11, v74, v14 op_sel:[0,1,0] op_sel_hi:[0,1,0]
	v_fma_mix_f32 v53, v11, v44, v53 op_sel:[0,1,0] op_sel_hi:[0,1,0]
	v_fma_mix_f32 v14, v12, v75, v14 op_sel:[0,0,0] op_sel_hi:[0,1,0]
	v_fma_mix_f32 v53, v12, v45, v53 op_sel:[0,0,0] op_sel_hi:[0,1,0]
	v_fma_mix_f32 v14, v13, v75, v14 op_sel:[0,1,0] op_sel_hi:[0,1,0]
	v_fma_mix_f32 v16, v10, v72, 0 op_sel:[0,0,0] op_sel_hi:[0,1,0]
	v_fma_mix_f32 v17, v11, v72, 0 op_sel:[0,1,0] op_sel_hi:[0,1,0]
	v_add_f32_dpp v20, v14, v14 quad_perm:[1,0,3,2] row_mask:0xf bank_mask:0xf bound_ctrl:1
	v_fma_mix_f32 v53, v13, v45, v53 op_sel:[0,1,0] op_sel_hi:[0,1,0]
	v_fma_mix_f32 v18, v12, v73, 0 op_sel:[0,0,0] op_sel_hi:[0,1,0]
	v_add_f32_dpp v20, v20, v20 quad_perm:[2,3,0,1] row_mask:0xf bank_mask:0xf bound_ctrl:1
	v_fma_mix_f32 v19, v13, v73, 0 op_sel:[0,1,0] op_sel_hi:[0,1,0]
	v_fma_mix_f32 v16, v82, v78, v16 op_sel:[0,0,0] op_sel_hi:[1,1,0]
	v_add_f32_dpp v20, v20, v20 row_half_mirror row_mask:0xf bank_mask:0xf bound_ctrl:1
	v_fma_mix_f32 v17, v82, v78, v17 op_sel:[0,1,0] op_sel_hi:[1,1,0]
	v_fma_mix_f32 v18, v82, v79, v18 op_sel:[0,0,0] op_sel_hi:[1,1,0]
	v_add_f32_dpp v20, v20, v20 row_mirror row_mask:0xf bank_mask:0xf bound_ctrl:1
	v_fma_mix_f32 v19, v82, v79, v19 op_sel:[0,1,0] op_sel_hi:[1,1,0]
	v_fma_mix_f32 v10, v20, v76, v16 op_sel:[0,0,0] op_sel_hi:[0,1,0]
	v_fma_mix_f32 v11, v20, v76, v17 op_sel:[0,1,0] op_sel_hi:[0,1,0]
	v_fma_mix_f32 v12, v20, v77, v18 op_sel:[0,0,0] op_sel_hi:[0,1,0]
	v_fma_mix_f32 v13, v20, v77, v19 op_sel:[0,1,0] op_sel_hi:[0,1,0]
	s_waitcnt lgkmcnt(4)
	ds_read_b64 v[36:37], v6 offset:9232
	ds_read_b128 v[38:41], v6 offset:9488
	ds_read_b128 v[42:45], v6 offset:9744
	ds_read_u16 v46, v7 offset:9232
	v_fma_mix_f32 v14, v10, v86, 0 op_sel:[0,0,0] op_sel_hi:[0,1,0]
	v_fma_mix_f32 v54, v10, v80, 0 op_sel:[0,0,0] op_sel_hi:[0,1,0]
	v_fma_mix_f32 v14, v11, v86, v14 op_sel:[0,1,0] op_sel_hi:[0,1,0]
	v_fma_mix_f32 v54, v11, v80, v54 op_sel:[0,1,0] op_sel_hi:[0,1,0]
	v_fma_mix_f32 v14, v12, v87, v14 op_sel:[0,0,0] op_sel_hi:[0,1,0]
	v_fma_mix_f32 v54, v12, v81, v54 op_sel:[0,0,0] op_sel_hi:[0,1,0]
	v_fma_mix_f32 v14, v13, v87, v14 op_sel:[0,1,0] op_sel_hi:[0,1,0]
	v_fma_mix_f32 v16, v10, v84, 0 op_sel:[0,0,0] op_sel_hi:[0,1,0]
	v_fma_mix_f32 v17, v11, v84, 0 op_sel:[0,1,0] op_sel_hi:[0,1,0]
	v_add_f32_dpp v20, v14, v14 quad_perm:[1,0,3,2] row_mask:0xf bank_mask:0xf bound_ctrl:1
	v_fma_mix_f32 v54, v13, v81, v54 op_sel:[0,1,0] op_sel_hi:[0,1,0]
	v_fma_mix_f32 v18, v12, v85, 0 op_sel:[0,0,0] op_sel_hi:[0,1,0]
	v_add_f32_dpp v20, v20, v20 quad_perm:[2,3,0,1] row_mask:0xf bank_mask:0xf bound_ctrl:1
	v_fma_mix_f32 v19, v13, v85, 0 op_sel:[0,1,0] op_sel_hi:[0,1,0]
	v_fma_mix_f32 v16, v94, v90, v16 op_sel:[0,0,0] op_sel_hi:[1,1,0]
	v_add_f32_dpp v20, v20, v20 row_half_mirror row_mask:0xf bank_mask:0xf bound_ctrl:1
	v_fma_mix_f32 v17, v94, v90, v17 op_sel:[0,1,0] op_sel_hi:[1,1,0]
	v_fma_mix_f32 v18, v94, v91, v18 op_sel:[0,0,0] op_sel_hi:[1,1,0]
	v_add_f32_dpp v20, v20, v20 row_mirror row_mask:0xf bank_mask:0xf bound_ctrl:1
	v_fma_mix_f32 v19, v94, v91, v19 op_sel:[0,1,0] op_sel_hi:[1,1,0]
	v_fma_mix_f32 v10, v20, v88, v16 op_sel:[0,0,0] op_sel_hi:[0,1,0]
	v_fma_mix_f32 v11, v20, v88, v17 op_sel:[0,1,0] op_sel_hi:[0,1,0]
	v_fma_mix_f32 v12, v20, v89, v18 op_sel:[0,0,0] op_sel_hi:[0,1,0]
	v_fma_mix_f32 v13, v20, v89, v19 op_sel:[0,1,0] op_sel_hi:[0,1,0]
	s_waitcnt lgkmcnt(4)
	ds_read_b64 v[72:73], v6 offset:10256
	ds_read_b128 v[74:77], v6 offset:10512
	ds_read_b128 v[78:81], v6 offset:10768
	ds_read_u16 v82, v7 offset:10256
	v_fma_mix_f32 v14, v10, v26, 0 op_sel:[0,0,0] op_sel_hi:[0,1,0]
	v_fma_mix_f32 v55, v10, v92, 0 op_sel:[0,0,0] op_sel_hi:[0,1,0]
	v_fma_mix_f32 v14, v11, v26, v14 op_sel:[0,1,0] op_sel_hi:[0,1,0]
	v_fma_mix_f32 v55, v11, v92, v55 op_sel:[0,1,0] op_sel_hi:[0,1,0]
	v_fma_mix_f32 v14, v12, v27, v14 op_sel:[0,0,0] op_sel_hi:[0,1,0]
	v_fma_mix_f32 v55, v12, v93, v55 op_sel:[0,0,0] op_sel_hi:[0,1,0]
	v_fma_mix_f32 v14, v13, v27, v14 op_sel:[0,1,0] op_sel_hi:[0,1,0]
	v_fma_mix_f32 v16, v10, v24, 0 op_sel:[0,0,0] op_sel_hi:[0,1,0]
	v_fma_mix_f32 v17, v11, v24, 0 op_sel:[0,1,0] op_sel_hi:[0,1,0]
	v_add_f32_dpp v20, v14, v14 quad_perm:[1,0,3,2] row_mask:0xf bank_mask:0xf bound_ctrl:1
	v_fma_mix_f32 v55, v13, v93, v55 op_sel:[0,1,0] op_sel_hi:[0,1,0]
	v_fma_mix_f32 v18, v12, v25, 0 op_sel:[0,0,0] op_sel_hi:[0,1,0]
	v_add_f32_dpp v20, v20, v20 quad_perm:[2,3,0,1] row_mask:0xf bank_mask:0xf bound_ctrl:1
	v_fma_mix_f32 v19, v13, v25, 0 op_sel:[0,1,0] op_sel_hi:[0,1,0]
	v_fma_mix_f32 v16, v34, v30, v16 op_sel:[0,0,0] op_sel_hi:[1,1,0]
	v_add_f32_dpp v20, v20, v20 row_half_mirror row_mask:0xf bank_mask:0xf bound_ctrl:1
	v_fma_mix_f32 v17, v34, v30, v17 op_sel:[0,1,0] op_sel_hi:[1,1,0]
	v_fma_mix_f32 v18, v34, v31, v18 op_sel:[0,0,0] op_sel_hi:[1,1,0]
	v_add_f32_dpp v20, v20, v20 row_mirror row_mask:0xf bank_mask:0xf bound_ctrl:1
	v_fma_mix_f32 v19, v34, v31, v19 op_sel:[0,1,0] op_sel_hi:[1,1,0]
	v_fma_mix_f32 v10, v20, v28, v16 op_sel:[0,0,0] op_sel_hi:[0,1,0]
	v_fma_mix_f32 v11, v20, v28, v17 op_sel:[0,1,0] op_sel_hi:[0,1,0]
	v_fma_mix_f32 v12, v20, v29, v18 op_sel:[0,0,0] op_sel_hi:[0,1,0]
	v_fma_mix_f32 v13, v20, v29, v19 op_sel:[0,1,0] op_sel_hi:[0,1,0]
	s_waitcnt lgkmcnt(4)
	ds_read_b64 v[84:85], v6 offset:11280
	ds_read_b128 v[86:89], v6 offset:11536
	ds_read_b128 v[90:93], v6 offset:11792
	ds_read_u16 v94, v7 offset:11280
	v_fma_mix_f32 v14, v10, v38, 0 op_sel:[0,0,0] op_sel_hi:[0,1,0]
	v_fma_mix_f32 v56, v10, v32, 0 op_sel:[0,0,0] op_sel_hi:[0,1,0]
	v_fma_mix_f32 v14, v11, v38, v14 op_sel:[0,1,0] op_sel_hi:[0,1,0]
	v_fma_mix_f32 v56, v11, v32, v56 op_sel:[0,1,0] op_sel_hi:[0,1,0]
	v_fma_mix_f32 v14, v12, v39, v14 op_sel:[0,0,0] op_sel_hi:[0,1,0]
	v_fma_mix_f32 v56, v12, v33, v56 op_sel:[0,0,0] op_sel_hi:[0,1,0]
	v_fma_mix_f32 v14, v13, v39, v14 op_sel:[0,1,0] op_sel_hi:[0,1,0]
	v_fma_mix_f32 v16, v10, v36, 0 op_sel:[0,0,0] op_sel_hi:[0,1,0]
	v_fma_mix_f32 v17, v11, v36, 0 op_sel:[0,1,0] op_sel_hi:[0,1,0]
	v_add_f32_dpp v20, v14, v14 quad_perm:[1,0,3,2] row_mask:0xf bank_mask:0xf bound_ctrl:1
	v_fma_mix_f32 v56, v13, v33, v56 op_sel:[0,1,0] op_sel_hi:[0,1,0]
	v_fma_mix_f32 v18, v12, v37, 0 op_sel:[0,0,0] op_sel_hi:[0,1,0]
	v_add_f32_dpp v20, v20, v20 quad_perm:[2,3,0,1] row_mask:0xf bank_mask:0xf bound_ctrl:1
	v_fma_mix_f32 v19, v13, v37, 0 op_sel:[0,1,0] op_sel_hi:[0,1,0]
	v_fma_mix_f32 v16, v46, v42, v16 op_sel:[0,0,0] op_sel_hi:[1,1,0]
	v_add_f32_dpp v20, v20, v20 row_half_mirror row_mask:0xf bank_mask:0xf bound_ctrl:1
	v_fma_mix_f32 v17, v46, v42, v17 op_sel:[0,1,0] op_sel_hi:[1,1,0]
	v_fma_mix_f32 v18, v46, v43, v18 op_sel:[0,0,0] op_sel_hi:[1,1,0]
	v_add_f32_dpp v20, v20, v20 row_mirror row_mask:0xf bank_mask:0xf bound_ctrl:1
	v_fma_mix_f32 v19, v46, v43, v19 op_sel:[0,1,0] op_sel_hi:[1,1,0]
	v_fma_mix_f32 v10, v20, v40, v16 op_sel:[0,0,0] op_sel_hi:[0,1,0]
	v_fma_mix_f32 v11, v20, v40, v17 op_sel:[0,1,0] op_sel_hi:[0,1,0]
	v_fma_mix_f32 v12, v20, v41, v18 op_sel:[0,0,0] op_sel_hi:[0,1,0]
	v_fma_mix_f32 v13, v20, v41, v19 op_sel:[0,1,0] op_sel_hi:[0,1,0]
	s_waitcnt lgkmcnt(4)
	ds_read_b64 v[24:25], v6 offset:12304
	ds_read_b128 v[26:29], v6 offset:12560
	ds_read_b128 v[30:33], v6 offset:12816
	ds_read_u16 v34, v7 offset:12304
	v_fma_mix_f32 v14, v10, v74, 0 op_sel:[0,0,0] op_sel_hi:[0,1,0]
	v_fma_mix_f32 v57, v10, v44, 0 op_sel:[0,0,0] op_sel_hi:[0,1,0]
	v_fma_mix_f32 v14, v11, v74, v14 op_sel:[0,1,0] op_sel_hi:[0,1,0]
	v_fma_mix_f32 v57, v11, v44, v57 op_sel:[0,1,0] op_sel_hi:[0,1,0]
	v_fma_mix_f32 v14, v12, v75, v14 op_sel:[0,0,0] op_sel_hi:[0,1,0]
	v_fma_mix_f32 v57, v12, v45, v57 op_sel:[0,0,0] op_sel_hi:[0,1,0]
	v_fma_mix_f32 v14, v13, v75, v14 op_sel:[0,1,0] op_sel_hi:[0,1,0]
	v_fma_mix_f32 v16, v10, v72, 0 op_sel:[0,0,0] op_sel_hi:[0,1,0]
	v_fma_mix_f32 v17, v11, v72, 0 op_sel:[0,1,0] op_sel_hi:[0,1,0]
	v_add_f32_dpp v20, v14, v14 quad_perm:[1,0,3,2] row_mask:0xf bank_mask:0xf bound_ctrl:1
	v_fma_mix_f32 v57, v13, v45, v57 op_sel:[0,1,0] op_sel_hi:[0,1,0]
	v_fma_mix_f32 v18, v12, v73, 0 op_sel:[0,0,0] op_sel_hi:[0,1,0]
	v_add_f32_dpp v20, v20, v20 quad_perm:[2,3,0,1] row_mask:0xf bank_mask:0xf bound_ctrl:1
	v_fma_mix_f32 v19, v13, v73, 0 op_sel:[0,1,0] op_sel_hi:[0,1,0]
	v_fma_mix_f32 v16, v82, v78, v16 op_sel:[0,0,0] op_sel_hi:[1,1,0]
	v_add_f32_dpp v20, v20, v20 row_half_mirror row_mask:0xf bank_mask:0xf bound_ctrl:1
	v_fma_mix_f32 v17, v82, v78, v17 op_sel:[0,1,0] op_sel_hi:[1,1,0]
	v_fma_mix_f32 v18, v82, v79, v18 op_sel:[0,0,0] op_sel_hi:[1,1,0]
	v_add_f32_dpp v20, v20, v20 row_mirror row_mask:0xf bank_mask:0xf bound_ctrl:1
	v_fma_mix_f32 v19, v82, v79, v19 op_sel:[0,1,0] op_sel_hi:[1,1,0]
	v_fma_mix_f32 v10, v20, v76, v16 op_sel:[0,0,0] op_sel_hi:[0,1,0]
	v_fma_mix_f32 v11, v20, v76, v17 op_sel:[0,1,0] op_sel_hi:[0,1,0]
	v_fma_mix_f32 v12, v20, v77, v18 op_sel:[0,0,0] op_sel_hi:[0,1,0]
	v_fma_mix_f32 v13, v20, v77, v19 op_sel:[0,1,0] op_sel_hi:[0,1,0]
	s_waitcnt lgkmcnt(4)
	ds_read_b64 v[36:37], v6 offset:13328
	ds_read_b128 v[38:41], v6 offset:13584
	ds_read_b128 v[42:45], v6 offset:13840
	ds_read_u16 v46, v7 offset:13328
	v_fma_mix_f32 v14, v10, v86, 0 op_sel:[0,0,0] op_sel_hi:[0,1,0]
	v_fma_mix_f32 v58, v10, v80, 0 op_sel:[0,0,0] op_sel_hi:[0,1,0]
	v_fma_mix_f32 v14, v11, v86, v14 op_sel:[0,1,0] op_sel_hi:[0,1,0]
	v_fma_mix_f32 v58, v11, v80, v58 op_sel:[0,1,0] op_sel_hi:[0,1,0]
	v_fma_mix_f32 v14, v12, v87, v14 op_sel:[0,0,0] op_sel_hi:[0,1,0]
	v_fma_mix_f32 v58, v12, v81, v58 op_sel:[0,0,0] op_sel_hi:[0,1,0]
	v_fma_mix_f32 v14, v13, v87, v14 op_sel:[0,1,0] op_sel_hi:[0,1,0]
	v_fma_mix_f32 v16, v10, v84, 0 op_sel:[0,0,0] op_sel_hi:[0,1,0]
	v_fma_mix_f32 v17, v11, v84, 0 op_sel:[0,1,0] op_sel_hi:[0,1,0]
	v_add_f32_dpp v20, v14, v14 quad_perm:[1,0,3,2] row_mask:0xf bank_mask:0xf bound_ctrl:1
	v_fma_mix_f32 v58, v13, v81, v58 op_sel:[0,1,0] op_sel_hi:[0,1,0]
	v_fma_mix_f32 v18, v12, v85, 0 op_sel:[0,0,0] op_sel_hi:[0,1,0]
	v_add_f32_dpp v20, v20, v20 quad_perm:[2,3,0,1] row_mask:0xf bank_mask:0xf bound_ctrl:1
	v_fma_mix_f32 v19, v13, v85, 0 op_sel:[0,1,0] op_sel_hi:[0,1,0]
	v_fma_mix_f32 v16, v94, v90, v16 op_sel:[0,0,0] op_sel_hi:[1,1,0]
	v_add_f32_dpp v20, v20, v20 row_half_mirror row_mask:0xf bank_mask:0xf bound_ctrl:1
	v_fma_mix_f32 v17, v94, v90, v17 op_sel:[0,1,0] op_sel_hi:[1,1,0]
	v_fma_mix_f32 v18, v94, v91, v18 op_sel:[0,0,0] op_sel_hi:[1,1,0]
	v_add_f32_dpp v20, v20, v20 row_mirror row_mask:0xf bank_mask:0xf bound_ctrl:1
	v_fma_mix_f32 v19, v94, v91, v19 op_sel:[0,1,0] op_sel_hi:[1,1,0]
	v_fma_mix_f32 v10, v20, v88, v16 op_sel:[0,0,0] op_sel_hi:[0,1,0]
	v_fma_mix_f32 v11, v20, v88, v17 op_sel:[0,1,0] op_sel_hi:[0,1,0]
	v_fma_mix_f32 v12, v20, v89, v18 op_sel:[0,0,0] op_sel_hi:[0,1,0]
	v_fma_mix_f32 v13, v20, v89, v19 op_sel:[0,1,0] op_sel_hi:[0,1,0]
	s_waitcnt lgkmcnt(4)
	ds_read_b64 v[72:73], v6 offset:14352
	ds_read_b128 v[74:77], v6 offset:14608
	ds_read_b128 v[78:81], v6 offset:14864
	ds_read_u16 v82, v7 offset:14352
	v_fma_mix_f32 v14, v10, v26, 0 op_sel:[0,0,0] op_sel_hi:[0,1,0]
	v_fma_mix_f32 v59, v10, v92, 0 op_sel:[0,0,0] op_sel_hi:[0,1,0]
	v_fma_mix_f32 v14, v11, v26, v14 op_sel:[0,1,0] op_sel_hi:[0,1,0]
	v_fma_mix_f32 v59, v11, v92, v59 op_sel:[0,1,0] op_sel_hi:[0,1,0]
	v_fma_mix_f32 v14, v12, v27, v14 op_sel:[0,0,0] op_sel_hi:[0,1,0]
	v_fma_mix_f32 v59, v12, v93, v59 op_sel:[0,0,0] op_sel_hi:[0,1,0]
	v_fma_mix_f32 v14, v13, v27, v14 op_sel:[0,1,0] op_sel_hi:[0,1,0]
	v_fma_mix_f32 v16, v10, v24, 0 op_sel:[0,0,0] op_sel_hi:[0,1,0]
	v_fma_mix_f32 v17, v11, v24, 0 op_sel:[0,1,0] op_sel_hi:[0,1,0]
	v_add_f32_dpp v20, v14, v14 quad_perm:[1,0,3,2] row_mask:0xf bank_mask:0xf bound_ctrl:1
	v_fma_mix_f32 v59, v13, v93, v59 op_sel:[0,1,0] op_sel_hi:[0,1,0]
	v_fma_mix_f32 v18, v12, v25, 0 op_sel:[0,0,0] op_sel_hi:[0,1,0]
	v_add_f32_dpp v20, v20, v20 quad_perm:[2,3,0,1] row_mask:0xf bank_mask:0xf bound_ctrl:1
	v_fma_mix_f32 v19, v13, v25, 0 op_sel:[0,1,0] op_sel_hi:[0,1,0]
	v_fma_mix_f32 v16, v34, v30, v16 op_sel:[0,0,0] op_sel_hi:[1,1,0]
	v_add_f32_dpp v20, v20, v20 row_half_mirror row_mask:0xf bank_mask:0xf bound_ctrl:1
	v_fma_mix_f32 v17, v34, v30, v17 op_sel:[0,1,0] op_sel_hi:[1,1,0]
	v_fma_mix_f32 v18, v34, v31, v18 op_sel:[0,0,0] op_sel_hi:[1,1,0]
	v_add_f32_dpp v20, v20, v20 row_mirror row_mask:0xf bank_mask:0xf bound_ctrl:1
	v_fma_mix_f32 v19, v34, v31, v19 op_sel:[0,1,0] op_sel_hi:[1,1,0]
	v_fma_mix_f32 v10, v20, v28, v16 op_sel:[0,0,0] op_sel_hi:[0,1,0]
	v_fma_mix_f32 v11, v20, v28, v17 op_sel:[0,1,0] op_sel_hi:[0,1,0]
	v_fma_mix_f32 v12, v20, v29, v18 op_sel:[0,0,0] op_sel_hi:[0,1,0]
	v_fma_mix_f32 v13, v20, v29, v19 op_sel:[0,1,0] op_sel_hi:[0,1,0]
	s_waitcnt lgkmcnt(4)
	ds_read_b128 v[100:103], v9
	ds_read_b64 v[84:85], v6 offset:15376
	ds_read_b128 v[86:89], v6 offset:15632
	ds_read_b128 v[90:93], v6 offset:15888
	ds_read_u16 v94, v7 offset:15376
	v_fma_mix_f32 v14, v10, v38, 0 op_sel:[0,0,0] op_sel_hi:[0,1,0]
	v_fma_mix_f32 v60, v10, v32, 0 op_sel:[0,0,0] op_sel_hi:[0,1,0]
	v_fma_mix_f32 v14, v11, v38, v14 op_sel:[0,1,0] op_sel_hi:[0,1,0]
	v_fma_mix_f32 v60, v11, v32, v60 op_sel:[0,1,0] op_sel_hi:[0,1,0]
	v_fma_mix_f32 v14, v12, v39, v14 op_sel:[0,0,0] op_sel_hi:[0,1,0]
	v_fma_mix_f32 v60, v12, v33, v60 op_sel:[0,0,0] op_sel_hi:[0,1,0]
	v_fma_mix_f32 v14, v13, v39, v14 op_sel:[0,1,0] op_sel_hi:[0,1,0]
	v_fma_mix_f32 v16, v10, v36, 0 op_sel:[0,0,0] op_sel_hi:[0,1,0]
	v_fma_mix_f32 v17, v11, v36, 0 op_sel:[0,1,0] op_sel_hi:[0,1,0]
	v_add_f32_dpp v20, v14, v14 quad_perm:[1,0,3,2] row_mask:0xf bank_mask:0xf bound_ctrl:1
	v_fma_mix_f32 v60, v13, v33, v60 op_sel:[0,1,0] op_sel_hi:[0,1,0]
	v_fma_mix_f32 v18, v12, v37, 0 op_sel:[0,0,0] op_sel_hi:[0,1,0]
	v_add_f32_dpp v20, v20, v20 quad_perm:[2,3,0,1] row_mask:0xf bank_mask:0xf bound_ctrl:1
	v_fma_mix_f32 v19, v13, v37, 0 op_sel:[0,1,0] op_sel_hi:[0,1,0]
	v_fma_mix_f32 v16, v46, v42, v16 op_sel:[0,0,0] op_sel_hi:[1,1,0]
	v_add_f32_dpp v20, v20, v20 row_half_mirror row_mask:0xf bank_mask:0xf bound_ctrl:1
	v_fma_mix_f32 v17, v46, v42, v17 op_sel:[0,1,0] op_sel_hi:[1,1,0]
	v_fma_mix_f32 v18, v46, v43, v18 op_sel:[0,0,0] op_sel_hi:[1,1,0]
	v_add_f32_dpp v20, v20, v20 row_mirror row_mask:0xf bank_mask:0xf bound_ctrl:1
	v_fma_mix_f32 v19, v46, v43, v19 op_sel:[0,1,0] op_sel_hi:[1,1,0]
	v_fma_mix_f32 v10, v20, v40, v16 op_sel:[0,0,0] op_sel_hi:[0,1,0]
	v_fma_mix_f32 v11, v20, v40, v17 op_sel:[0,1,0] op_sel_hi:[0,1,0]
	v_fma_mix_f32 v12, v20, v41, v18 op_sel:[0,0,0] op_sel_hi:[0,1,0]
	v_fma_mix_f32 v13, v20, v41, v19 op_sel:[0,1,0] op_sel_hi:[0,1,0]
	s_waitcnt lgkmcnt(4)
	v_add_u32_e32 v6, 0x4000, v6
	v_add_u32_e32 v7, 0x4000, v7
	v_and_b32_e32 v6, 0x1ffff, v6
	v_and_b32_e32 v7, 0x1ffff, v7
	ds_read_b64 v[24:25], v6 offset:16
	ds_read_b128 v[26:29], v6 offset:272
	ds_read_b128 v[30:33], v6 offset:528
	ds_read_u16 v34, v7 offset:16
	v_fma_mix_f32 v14, v10, v74, 0 op_sel:[0,0,0] op_sel_hi:[0,1,0]
	v_fma_mix_f32 v61, v10, v44, 0 op_sel:[0,0,0] op_sel_hi:[0,1,0]
	v_fma_mix_f32 v14, v11, v74, v14 op_sel:[0,1,0] op_sel_hi:[0,1,0]
	v_fma_mix_f32 v61, v11, v44, v61 op_sel:[0,1,0] op_sel_hi:[0,1,0]
	v_fma_mix_f32 v14, v12, v75, v14 op_sel:[0,0,0] op_sel_hi:[0,1,0]
	v_fma_mix_f32 v61, v12, v45, v61 op_sel:[0,0,0] op_sel_hi:[0,1,0]
	v_fma_mix_f32 v14, v13, v75, v14 op_sel:[0,1,0] op_sel_hi:[0,1,0]
	v_fma_mix_f32 v16, v10, v72, 0 op_sel:[0,0,0] op_sel_hi:[0,1,0]
	v_fma_mix_f32 v17, v11, v72, 0 op_sel:[0,1,0] op_sel_hi:[0,1,0]
	v_add_f32_dpp v20, v14, v14 quad_perm:[1,0,3,2] row_mask:0xf bank_mask:0xf bound_ctrl:1
	v_fma_mix_f32 v61, v13, v45, v61 op_sel:[0,1,0] op_sel_hi:[0,1,0]
	v_fma_mix_f32 v18, v12, v73, 0 op_sel:[0,0,0] op_sel_hi:[0,1,0]
	v_add_f32_dpp v20, v20, v20 quad_perm:[2,3,0,1] row_mask:0xf bank_mask:0xf bound_ctrl:1
	v_fma_mix_f32 v19, v13, v73, 0 op_sel:[0,1,0] op_sel_hi:[0,1,0]
	v_fma_mix_f32 v16, v82, v78, v16 op_sel:[0,0,0] op_sel_hi:[1,1,0]
	v_add_f32_dpp v20, v20, v20 row_half_mirror row_mask:0xf bank_mask:0xf bound_ctrl:1
	v_fma_mix_f32 v17, v82, v78, v17 op_sel:[0,1,0] op_sel_hi:[1,1,0]
	v_fma_mix_f32 v18, v82, v79, v18 op_sel:[0,0,0] op_sel_hi:[1,1,0]
	v_add_f32_dpp v20, v20, v20 row_mirror row_mask:0xf bank_mask:0xf bound_ctrl:1
	v_fma_mix_f32 v19, v82, v79, v19 op_sel:[0,1,0] op_sel_hi:[1,1,0]
	v_fma_mix_f32 v10, v20, v76, v16 op_sel:[0,0,0] op_sel_hi:[0,1,0]
	v_fma_mix_f32 v11, v20, v76, v17 op_sel:[0,1,0] op_sel_hi:[0,1,0]
	v_fma_mix_f32 v12, v20, v77, v18 op_sel:[0,0,0] op_sel_hi:[0,1,0]
	v_fma_mix_f32 v13, v20, v77, v19 op_sel:[0,1,0] op_sel_hi:[0,1,0]
	s_waitcnt lgkmcnt(4)
; DEVINL u16 f2bf(float a) { return (u16)(pk2(a, 0.f) & 0xffffu); }
; #define RW_STEP2(B) RW_STEP(B, WvA, XA, KrA, vhA, WvB, XB, KrB, vhB); RW_STEP((B) + 1, WvB, XB, KrB, vhB, WvA, XA, KrA, vhA)
; #define RW_STEP4(B) RW_STEP2(B); RW_STEP2((B) + 2)
; template <int DIR>
; DEVINL void rwkv_scan_dir(const Params& p, int task, int lane, int wave) {
;   const int b = (task >> 8) & 1, head = (task >> 4) & 15, rg = task & 15;
;   const int seg = lane & 15, rl = lane >> 4, row = rg * 4 + rl;
;   constexpr int DIST = 24;
;   constexpr int WOFS = DIR ? 8 : 0;
;   const char* recbase = p.ws + O_REC + ((long)(b * 16 + head) * 4096) * 1024 + lane * 16;
;   const unsigned ring_lds = (unsigned)(unsigned long)(__attribute__((address_space(3))) char*)(dynsmem + wave * 32768);
;   const unsigned ring_u = __builtin_amdgcn_readfirstlane(ring_lds);
;   const unsigned a_seg = ring_lds + seg * 64;
;   const unsigned a_v = ring_lds + (row >> 2) * 64 + 48 + (row & 3) * 2;
;   u16* yo = (u16*)(p.ws + (DIR ? O_YB : O_YSUM)) + ((long)b * 4096) * 1024 + head * 64 + row;
;   float s0 = 0.f, s1 = 0.f, s2 = 0.f, s3 = 0.f;
;   float ykeep = 0.f;
;   const char* recdir = recbase + (DIR ? (long)4095 * 1024 : 0);
;     ...
;   for (int st = 0; st < 4096; st += 32) {
;     RW_STEP(0, WvA, XA, KrA, vhA, WvB, XB, KrB, vhB);
;     if (st > 0) { const int q0 = st - 16 + seg; yo[(long)(DIR ? (4095 - q0) : q0) * 1024] = f2bf(ykeep); }
;     RW_STEP(1, WvB, XB, KrB, vhB, WvA, XA, KrA, vhA);
;     RW_STEP2(2); RW_STEP4(4); RW_STEP4(8); RW_STEP4(12);
;     RW_STEP(16, WvA, XA, KrA, vhA, WvB, XB, KrB, vhB);
;     { const int q0 = st + seg; yo[(long)(DIR ? (4095 - q0) : q0) * 1024] = f2bf(ykeep); }
;     RW_STEP(17, WvB, XB, KrB, vhB, WvA, XA, KrA, vhA);
;     RW_STEP2(18); RW_STEP4(20); RW_STEP4(24); RW_STEP4(28);
;   }
;   {
;     const float ylast = allred16(ypart);
;     ykeep = (seg == 15) ? ylast : ykeep;
;     const int q0 = 4096 - 16 + seg; yo[(long)(DIR ? (4095 - q0) : q0) * 1024] = f2bf(ykeep);
;   }
;   asm volatile("s_waitcnt vmcnt(0)" ::: "memory");
	ds_read_b64 v[36:37], v6 offset:1040
	ds_read_b128 v[38:41], v6 offset:1296
	ds_read_b128 v[42:45], v6 offset:1552
	ds_read_u16 v46, v7 offset:1040
	v_fma_mix_f32 v14, v10, v86, 0 op_sel:[0,0,0] op_sel_hi:[0,1,0]
	v_fma_mix_f32 v62, v10, v80, 0 op_sel:[0,0,0] op_sel_hi:[0,1,0]
	v_fma_mix_f32 v14, v11, v86, v14 op_sel:[0,1,0] op_sel_hi:[0,1,0]
	v_fma_mix_f32 v62, v11, v80, v62 op_sel:[0,1,0] op_sel_hi:[0,1,0]
	v_fma_mix_f32 v14, v12, v87, v14 op_sel:[0,0,0] op_sel_hi:[0,1,0]
	v_fma_mix_f32 v62, v12, v81, v62 op_sel:[0,0,0] op_sel_hi:[0,1,0]
	v_fma_mix_f32 v14, v13, v87, v14 op_sel:[0,1,0] op_sel_hi:[0,1,0]
	v_fma_mix_f32 v16, v10, v84, 0 op_sel:[0,0,0] op_sel_hi:[0,1,0]
	v_fma_mix_f32 v17, v11, v84, 0 op_sel:[0,1,0] op_sel_hi:[0,1,0]
	v_add_f32_dpp v20, v14, v14 quad_perm:[1,0,3,2] row_mask:0xf bank_mask:0xf bound_ctrl:1
	v_fma_mix_f32 v62, v13, v81, v62 op_sel:[0,1,0] op_sel_hi:[0,1,0]
	v_fma_mix_f32 v18, v12, v85, 0 op_sel:[0,0,0] op_sel_hi:[0,1,0]
	v_add_f32_dpp v20, v20, v20 quad_perm:[2,3,0,1] row_mask:0xf bank_mask:0xf bound_ctrl:1
	v_fma_mix_f32 v19, v13, v85, 0 op_sel:[0,1,0] op_sel_hi:[0,1,0]
	v_fma_mix_f32 v16, v94, v90, v16 op_sel:[0,0,0] op_sel_hi:[1,1,0]
	v_add_f32_dpp v20, v20, v20 row_half_mirror row_mask:0xf bank_mask:0xf bound_ctrl:1
	v_fma_mix_f32 v17, v94, v90, v17 op_sel:[0,1,0] op_sel_hi:[1,1,0]
	v_fma_mix_f32 v18, v94, v91, v18 op_sel:[0,0,0] op_sel_hi:[1,1,0]
	v_add_f32_dpp v20, v20, v20 row_mirror row_mask:0xf bank_mask:0xf bound_ctrl:1
	v_fma_mix_f32 v19, v94, v91, v19 op_sel:[0,1,0] op_sel_hi:[1,1,0]
	v_fma_mix_f32 v10, v20, v88, v16 op_sel:[0,0,0] op_sel_hi:[0,1,0]
	v_fma_mix_f32 v11, v20, v88, v17 op_sel:[0,1,0] op_sel_hi:[0,1,0]
	v_fma_mix_f32 v12, v20, v89, v18 op_sel:[0,0,0] op_sel_hi:[0,1,0]
	v_fma_mix_f32 v13, v20, v89, v19 op_sel:[0,1,0] op_sel_hi:[0,1,0]
	s_waitcnt lgkmcnt(4)
	s_add_u32 s43, s43, 1
	s_cmp_lg_u32 s43, s45
	s_cbranch_scc1 .Lrw_blk_d0
	s_sub_u32 s15, s43, 2
	v_fma_mix_f32 v21, v10, v92, 0 op_sel:[0,0,0] op_sel_hi:[0,1,0]
	v_fma_mix_f32 v22, v12, v93, 0 op_sel:[0,0,0] op_sel_hi:[0,1,0]
	v_fma_mix_f32 v21, v11, v92, v21 op_sel:[0,1,0] op_sel_hi:[0,1,0]
	v_fma_mix_f32 v22, v13, v93, v22 op_sel:[0,1,0] op_sel_hi:[0,1,0]
	v_add_f32_e32 v63, v21, v22
	s_nop 1
	v_add_f32_dpp v48, v48, v48 row_ror:8 row_mask:0xf bank_mask:0x3
	v_add_f32_dpp v49, v49, v49 row_ror:8 row_mask:0xf bank_mask:0x3
	v_add_f32_dpp v50, v50, v50 row_ror:8 row_mask:0xf bank_mask:0x3
	v_add_f32_dpp v51, v51, v51 row_ror:8 row_mask:0xf bank_mask:0x3
	v_add_f32_dpp v52, v52, v52 row_ror:8 row_mask:0xf bank_mask:0x3
	v_add_f32_dpp v53, v53, v53 row_ror:8 row_mask:0xf bank_mask:0x3
	v_add_f32_dpp v54, v54, v54 row_ror:8 row_mask:0xf bank_mask:0x3
	v_add_f32_dpp v55, v55, v55 row_ror:8 row_mask:0xf bank_mask:0x3
	v_add_f32_dpp v48, v56, v56 row_ror:8 row_mask:0xf bank_mask:0xc
	v_add_f32_dpp v49, v57, v57 row_ror:8 row_mask:0xf bank_mask:0xc
	v_add_f32_dpp v50, v58, v58 row_ror:8 row_mask:0xf bank_mask:0xc
	v_add_f32_dpp v51, v59, v59 row_ror:8 row_mask:0xf bank_mask:0xc
	v_add_f32_dpp v52, v60, v60 row_ror:8 row_mask:0xf bank_mask:0xc
	v_add_f32_dpp v53, v61, v61 row_ror:8 row_mask:0xf bank_mask:0xc
	v_add_f32_dpp v54, v62, v62 row_ror:8 row_mask:0xf bank_mask:0xc
	v_add_f32_dpp v55, v63, v63 row_ror:8 row_mask:0xf bank_mask:0xc
	v_add_f32_dpp v48, v48, v48 row_ror:12 row_mask:0xf bank_mask:0x5
	v_add_f32_dpp v49, v49, v49 row_ror:12 row_mask:0xf bank_mask:0x5
	v_add_f32_dpp v50, v50, v50 row_ror:12 row_mask:0xf bank_mask:0x5
	v_add_f32_dpp v51, v51, v51 row_ror:12 row_mask:0xf bank_mask:0x5
	v_add_f32_dpp v48, v52, v52 row_ror:4 row_mask:0xf bank_mask:0xa
	v_add_f32_dpp v49, v53, v53 row_ror:4 row_mask:0xf bank_mask:0xa
	v_add_f32_dpp v50, v54, v54 row_ror:4 row_mask:0xf bank_mask:0xa
	v_add_f32_dpp v51, v55, v55 row_ror:4 row_mask:0xf bank_mask:0xa
	v_add_f32_dpp v64, v48, v48 quad_perm:[2,3,0,1] row_mask:0xf bank_mask:0xf bound_ctrl:1
	v_add_f32_dpp v65, v50, v50 quad_perm:[2,3,0,1] row_mask:0xf bank_mask:0xf bound_ctrl:1
	v_cndmask_b32_e64 v56, v64, v65, s[50:51]
	v_add_f32_dpp v64, v49, v49 quad_perm:[2,3,0,1] row_mask:0xf bank_mask:0xf bound_ctrl:1
	v_add_f32_dpp v65, v51, v51 quad_perm:[2,3,0,1] row_mask:0xf bank_mask:0xf bound_ctrl:1
	v_cndmask_b32_e64 v57, v64, v65, s[50:51]
	v_add_f32_dpp v64, v56, v56 quad_perm:[1,0,3,2] row_mask:0xf bank_mask:0xf bound_ctrl:1
	s_nop 0
	v_add_f32_dpp v65, v57, v57 quad_perm:[1,0,3,2] row_mask:0xf bank_mask:0xf bound_ctrl:1
	v_cndmask_b32_e64 v66, v64, v65, s[48:49]
	v_cvt_pk_bf16_f32 v66, v66, v66
	global_store_short v8, v66, s[12:13]
	s_add_u32 s12, s12, 0x8000
	s_addc_u32 s13, s13, 0
	s_branch .Lrw_next
.Lrw_bwd:
	s_add_u32 s12, s12, 0x1f700000
	s_addc_u32 s13, s13, 0
	v_sub_u32_e32 v69, 0xfff, v3
	v_lshl_add_u32 v8, v69, 11, v8
	s_add_u32 s10, s10, 0x3ff000
	s_addc_u32 s11, s11, 0
	s_sub_u32 s10, s10, s39
	s_subb_u32 s11, s11, 0
	s_sub_u32 s40, 0x1f000, s39
	s_mov_b32 s41, 0
	v_lshlrev_b32_e32 v6, 4, v3
	v_add_u32_e32 v6, 0x1c000, v6
	s_add_u32 s3, s37, 0x1c300
	v_lshl_add_u32 v7, v4, 1, s3
	s_add_u32 s41, s40, s41
	s_and_b32 s41, s41, 0x1ffff
	s_add_u32 m0, s41, 16
	s_nop 0
	global_load_lds_dwordx4 v5, s[10:11] offset:0
	global_load_lds_dwordx4 v5, s[10:11] offset:1024
	global_load_lds_dwordx4 v5, s[10:11] offset:2048
	global_load_lds_dwordx4 v5, s[10:11] offset:3072
	s_sub_u32 s10, s10, 0x4000
	s_subb_u32 s11, s11, 0
	s_sub_u32 s41, s41, 0x4000
	s_and_b32 s41, s41, 0x1ffff
	s_add_u32 m0, s41, 16
	s_nop 0
	global_load_lds_dwordx4 v5, s[10:11] offset:0
	global_load_lds_dwordx4 v5, s[10:11] offset:1024
	global_load_lds_dwordx4 v5, s[10:11] offset:2048
	global_load_lds_dwordx4 v5, s[10:11] offset:3072
	s_sub_u32 s10, s10, 0x4000
	s_subb_u32 s11, s11, 0
	s_sub_u32 s41, s41, 0x4000
	s_and_b32 s41, s41, 0x1ffff
	s_add_u32 m0, s41, 16
	s_nop 0
	global_load_lds_dwordx4 v5, s[10:11] offset:0
	global_load_lds_dwordx4 v5, s[10:11] offset:1024
	global_load_lds_dwordx4 v5, s[10:11] offset:2048
	global_load_lds_dwordx4 v5, s[10:11] offset:3072
	s_sub_u32 s10, s10, 0x4000
	s_subb_u32 s11, s11, 0
	s_sub_u32 s41, s41, 0x4000
	s_and_b32 s41, s41, 0x1ffff
	s_waitcnt vmcnt(0)
	v_mov_b32_e32 v10, 0
	v_mov_b32_e32 v11, 0
	v_mov_b32_e32 v12, 0
	v_mov_b32_e32 v13, 0
	s_add_u32 s43, s15, 2
	s_add_u32 s45, s43, 0x100
	s_add_u32 s3, s15, 2
	v_mov_b32_e32 v69, s3
	ds_write_b32 v23, v69
	ds_read_b128 v[100:103], v9
	s_waitcnt lgkmcnt(0)
	v_min3_u32 v100, v100, v101, v102
	v_min_u32_e32 v100, v100, v103
	s_nop 0
	v_readfirstlane_b32 s24, v100
	s_nop 0
	s_cmp_ge_u32 s24, s43
	s_cbranch_scc0 .Lrw_slow_d1p
; #define RW_LANDED(WN, XN, KN, VN) asm volatile("s_waitcnt lgkmcnt(0)" : "+v"(WN), "+v"(XN), "+v"(KN), "+v"(VN) :: "memory")
; #define RW_DMA4(B) RW_DMA_ONLY(B); RW_DMA_ONLY((B) + 1); RW_DMA_ONLY((B) + 2); RW_DMA_ONLY((B) + 3)
; template <int DIR>
; DEVINL void rwkv_scan_dir(const Params& p, int task, int lane, int wave) {
;     ...
;   u32x2 WvA, WvB; u32x4 XA, XB, KrA, KrB; unsigned vhA, vhB;
;   RW_DMA4(0); RW_DMA4(4); RW_DMA4(8); RW_DMA4(12); RW_DMA4(16); RW_DMA4(20);
;   RW_READ(0, WvA, XA, KrA, vhA, 23);
;   RW_LANDED(WvA, XA, KrA, vhA);
;   float ypart = 0.f;
.Lrw_ready_d1p:
	ds_read_b64 v[24:25], v6 offset:15384
	ds_read_b128 v[26:29], v6 offset:15632
	ds_read_b128 v[30:33], v6 offset:15888
	ds_read_u16 v34, v7 offset:15376
	ds_read_b64 v[36:37], v6 offset:14360
	ds_read_b128 v[38:41], v6 offset:14608
	ds_read_b128 v[42:45], v6 offset:14864
	ds_read_u16 v46, v7 offset:14352
	s_waitcnt lgkmcnt(0)
	s_waitcnt vmcnt(0)
	v_add_u32_e32 v69, 1, v69
	ds_write_b32 v23, v69
	v_min3_u32 v100, v100, v101, v102
	v_min_u32_e32 v100, v100, v103
	s_nop 0
	v_readfirstlane_b32 s24, v100
	s_nop 0
	s_cmp_ge_u32 s24, s43
	s_cbranch_scc0 .Lrw_slow_d1b0
.Lrw_ready_d1b0:
	s_add_u32 m0, s41, 16
	s_nop 0
	global_load_lds_dwordx4 v5, s[10:11] offset:0
	global_load_lds_dwordx4 v5, s[10:11] offset:1024
	global_load_lds_dwordx4 v5, s[10:11] offset:2048
	global_load_lds_dwordx4 v5, s[10:11] offset:3072
	s_sub_u32 s10, s10, 0x4000
	s_subb_u32 s11, s11, 0
	s_sub_u32 s41, s41, 0x4000
	s_and_b32 s41, s41, 0x1ffff
	ds_read_b64 v[72:73], v6 offset:13336
	ds_read_b128 v[74:77], v6 offset:13584
	ds_read_b128 v[78:81], v6 offset:13840
	ds_read_u16 v82, v7 offset:13328
	v_fma_mix_f32 v14, v10, v26, 0 op_sel:[0,0,0] op_sel_hi:[0,1,0]
	v_fma_mix_f32 v63, v10, v92, 0 op_sel:[0,0,0] op_sel_hi:[0,1,0]
	v_fma_mix_f32 v14, v11, v26, v14 op_sel:[0,1,0] op_sel_hi:[0,1,0]
	v_fma_mix_f32 v63, v11, v92, v63 op_sel:[0,1,0] op_sel_hi:[0,1,0]
	v_fma_mix_f32 v14, v12, v27, v14 op_sel:[0,0,0] op_sel_hi:[0,1,0]
	v_fma_mix_f32 v63, v12, v93, v63 op_sel:[0,0,0] op_sel_hi:[0,1,0]
	v_fma_mix_f32 v14, v13, v27, v14 op_sel:[0,1,0] op_sel_hi:[0,1,0]
	v_fma_mix_f32 v16, v10, v24, 0 op_sel:[0,0,0] op_sel_hi:[0,1,0]
	v_fma_mix_f32 v17, v11, v24, 0 op_sel:[0,1,0] op_sel_hi:[0,1,0]
	v_add_f32_dpp v20, v14, v14 quad_perm:[1,0,3,2] row_mask:0xf bank_mask:0xf bound_ctrl:1
	v_fma_mix_f32 v63, v13, v93, v63 op_sel:[0,1,0] op_sel_hi:[0,1,0]
	v_fma_mix_f32 v18, v12, v25, 0 op_sel:[0,0,0] op_sel_hi:[0,1,0]
	v_add_f32_dpp v20, v20, v20 quad_perm:[2,3,0,1] row_mask:0xf bank_mask:0xf bound_ctrl:1
	v_fma_mix_f32 v19, v13, v25, 0 op_sel:[0,1,0] op_sel_hi:[0,1,0]
	v_fma_mix_f32 v16, v34, v30, v16 op_sel:[0,0,0] op_sel_hi:[1,1,0]
	v_add_f32_dpp v20, v20, v20 row_half_mirror row_mask:0xf bank_mask:0xf bound_ctrl:1
	v_fma_mix_f32 v17, v34, v30, v17 op_sel:[0,1,0] op_sel_hi:[1,1,0]
	v_fma_mix_f32 v18, v34, v31, v18 op_sel:[0,0,0] op_sel_hi:[1,1,0]
	v_add_f32_dpp v20, v20, v20 row_mirror row_mask:0xf bank_mask:0xf bound_ctrl:1
	v_fma_mix_f32 v19, v34, v31, v19 op_sel:[0,1,0] op_sel_hi:[1,1,0]
	v_fma_mix_f32 v10, v20, v28, v16 op_sel:[0,0,0] op_sel_hi:[0,1,0]
	v_fma_mix_f32 v11, v20, v28, v17 op_sel:[0,1,0] op_sel_hi:[0,1,0]
	v_fma_mix_f32 v12, v20, v29, v18 op_sel:[0,0,0] op_sel_hi:[0,1,0]
	v_fma_mix_f32 v13, v20, v29, v19 op_sel:[0,1,0] op_sel_hi:[0,1,0]
	s_waitcnt lgkmcnt(4)
	ds_read_b64 v[84:85], v6 offset:12312
	ds_read_b128 v[86:89], v6 offset:12560
	ds_read_b128 v[90:93], v6 offset:12816
	ds_read_u16 v94, v7 offset:12304
	v_fma_mix_f32 v14, v10, v38, 0 op_sel:[0,0,0] op_sel_hi:[0,1,0]
	v_fma_mix_f32 v48, v10, v32, 0 op_sel:[0,0,0] op_sel_hi:[0,1,0]
	v_fma_mix_f32 v14, v11, v38, v14 op_sel:[0,1,0] op_sel_hi:[0,1,0]
	v_fma_mix_f32 v48, v11, v32, v48 op_sel:[0,1,0] op_sel_hi:[0,1,0]
	v_fma_mix_f32 v14, v12, v39, v14 op_sel:[0,0,0] op_sel_hi:[0,1,0]
	v_fma_mix_f32 v48, v12, v33, v48 op_sel:[0,0,0] op_sel_hi:[0,1,0]
	v_fma_mix_f32 v14, v13, v39, v14 op_sel:[0,1,0] op_sel_hi:[0,1,0]
	v_fma_mix_f32 v16, v10, v36, 0 op_sel:[0,0,0] op_sel_hi:[0,1,0]
	v_fma_mix_f32 v17, v11, v36, 0 op_sel:[0,1,0] op_sel_hi:[0,1,0]
	v_add_f32_dpp v20, v14, v14 quad_perm:[1,0,3,2] row_mask:0xf bank_mask:0xf bound_ctrl:1
	v_fma_mix_f32 v48, v13, v33, v48 op_sel:[0,1,0] op_sel_hi:[0,1,0]
	v_fma_mix_f32 v18, v12, v37, 0 op_sel:[0,0,0] op_sel_hi:[0,1,0]
	v_add_f32_dpp v20, v20, v20 quad_perm:[2,3,0,1] row_mask:0xf bank_mask:0xf bound_ctrl:1
	v_fma_mix_f32 v19, v13, v37, 0 op_sel:[0,1,0] op_sel_hi:[0,1,0]
	v_fma_mix_f32 v16, v46, v42, v16 op_sel:[0,0,0] op_sel_hi:[1,1,0]
	v_add_f32_dpp v20, v20, v20 row_half_mirror row_mask:0xf bank_mask:0xf bound_ctrl:1
	v_fma_mix_f32 v17, v46, v42, v17 op_sel:[0,1,0] op_sel_hi:[1,1,0]
	v_fma_mix_f32 v18, v46, v43, v18 op_sel:[0,0,0] op_sel_hi:[1,1,0]
	v_add_f32_dpp v20, v20, v20 row_mirror row_mask:0xf bank_mask:0xf bound_ctrl:1
	v_fma_mix_f32 v19, v46, v43, v19 op_sel:[0,1,0] op_sel_hi:[1,1,0]
	v_fma_mix_f32 v10, v20, v40, v16 op_sel:[0,0,0] op_sel_hi:[0,1,0]
	v_fma_mix_f32 v11, v20, v40, v17 op_sel:[0,1,0] op_sel_hi:[0,1,0]
	v_fma_mix_f32 v12, v20, v41, v18 op_sel:[0,0,0] op_sel_hi:[0,1,0]
	v_fma_mix_f32 v13, v20, v41, v19 op_sel:[0,1,0] op_sel_hi:[0,1,0]
	s_waitcnt lgkmcnt(4)
	ds_read_b64 v[24:25], v6 offset:11288
	ds_read_b128 v[26:29], v6 offset:11536
	ds_read_b128 v[30:33], v6 offset:11792
	ds_read_u16 v34, v7 offset:11280
	v_fma_mix_f32 v14, v10, v74, 0 op_sel:[0,0,0] op_sel_hi:[0,1,0]
	v_fma_mix_f32 v49, v10, v44, 0 op_sel:[0,0,0] op_sel_hi:[0,1,0]
	v_fma_mix_f32 v14, v11, v74, v14 op_sel:[0,1,0] op_sel_hi:[0,1,0]
	v_fma_mix_f32 v49, v11, v44, v49 op_sel:[0,1,0] op_sel_hi:[0,1,0]
	v_fma_mix_f32 v14, v12, v75, v14 op_sel:[0,0,0] op_sel_hi:[0,1,0]
	v_fma_mix_f32 v49, v12, v45, v49 op_sel:[0,0,0] op_sel_hi:[0,1,0]
	v_fma_mix_f32 v14, v13, v75, v14 op_sel:[0,1,0] op_sel_hi:[0,1,0]
	v_fma_mix_f32 v16, v10, v72, 0 op_sel:[0,0,0] op_sel_hi:[0,1,0]
	v_fma_mix_f32 v17, v11, v72, 0 op_sel:[0,1,0] op_sel_hi:[0,1,0]
	v_add_f32_dpp v20, v14, v14 quad_perm:[1,0,3,2] row_mask:0xf bank_mask:0xf bound_ctrl:1
	v_fma_mix_f32 v49, v13, v45, v49 op_sel:[0,1,0] op_sel_hi:[0,1,0]
	v_fma_mix_f32 v18, v12, v73, 0 op_sel:[0,0,0] op_sel_hi:[0,1,0]
	v_add_f32_dpp v20, v20, v20 quad_perm:[2,3,0,1] row_mask:0xf bank_mask:0xf bound_ctrl:1
	v_fma_mix_f32 v19, v13, v73, 0 op_sel:[0,1,0] op_sel_hi:[0,1,0]
	v_fma_mix_f32 v16, v82, v78, v16 op_sel:[0,0,0] op_sel_hi:[1,1,0]
	v_add_f32_dpp v20, v20, v20 row_half_mirror row_mask:0xf bank_mask:0xf bound_ctrl:1
	v_fma_mix_f32 v17, v82, v78, v17 op_sel:[0,1,0] op_sel_hi:[1,1,0]
	v_fma_mix_f32 v18, v82, v79, v18 op_sel:[0,0,0] op_sel_hi:[1,1,0]
	v_add_f32_dpp v20, v20, v20 row_mirror row_mask:0xf bank_mask:0xf bound_ctrl:1
	v_fma_mix_f32 v19, v82, v79, v19 op_sel:[0,1,0] op_sel_hi:[1,1,0]
	v_fma_mix_f32 v10, v20, v76, v16 op_sel:[0,0,0] op_sel_hi:[0,1,0]
	v_fma_mix_f32 v11, v20, v76, v17 op_sel:[0,1,0] op_sel_hi:[0,1,0]
	v_fma_mix_f32 v12, v20, v77, v18 op_sel:[0,0,0] op_sel_hi:[0,1,0]
	v_fma_mix_f32 v13, v20, v77, v19 op_sel:[0,1,0] op_sel_hi:[0,1,0]
	s_waitcnt lgkmcnt(4)
	ds_read_b64 v[36:37], v6 offset:10264
	ds_read_b128 v[38:41], v6 offset:10512
	ds_read_b128 v[42:45], v6 offset:10768
	ds_read_u16 v46, v7 offset:10256
	v_fma_mix_f32 v14, v10, v86, 0 op_sel:[0,0,0] op_sel_hi:[0,1,0]
	v_fma_mix_f32 v50, v10, v80, 0 op_sel:[0,0,0] op_sel_hi:[0,1,0]
	v_fma_mix_f32 v14, v11, v86, v14 op_sel:[0,1,0] op_sel_hi:[0,1,0]
	v_fma_mix_f32 v50, v11, v80, v50 op_sel:[0,1,0] op_sel_hi:[0,1,0]
	v_fma_mix_f32 v14, v12, v87, v14 op_sel:[0,0,0] op_sel_hi:[0,1,0]
	v_fma_mix_f32 v50, v12, v81, v50 op_sel:[0,0,0] op_sel_hi:[0,1,0]
	v_fma_mix_f32 v14, v13, v87, v14 op_sel:[0,1,0] op_sel_hi:[0,1,0]
	v_fma_mix_f32 v16, v10, v84, 0 op_sel:[0,0,0] op_sel_hi:[0,1,0]
	v_fma_mix_f32 v17, v11, v84, 0 op_sel:[0,1,0] op_sel_hi:[0,1,0]
	v_add_f32_dpp v20, v14, v14 quad_perm:[1,0,3,2] row_mask:0xf bank_mask:0xf bound_ctrl:1
	v_fma_mix_f32 v50, v13, v81, v50 op_sel:[0,1,0] op_sel_hi:[0,1,0]
	v_fma_mix_f32 v18, v12, v85, 0 op_sel:[0,0,0] op_sel_hi:[0,1,0]
	v_add_f32_dpp v20, v20, v20 quad_perm:[2,3,0,1] row_mask:0xf bank_mask:0xf bound_ctrl:1
	v_fma_mix_f32 v19, v13, v85, 0 op_sel:[0,1,0] op_sel_hi:[0,1,0]
	v_fma_mix_f32 v16, v94, v90, v16 op_sel:[0,0,0] op_sel_hi:[1,1,0]
	v_add_f32_dpp v20, v20, v20 row_half_mirror row_mask:0xf bank_mask:0xf bound_ctrl:1
	v_fma_mix_f32 v17, v94, v90, v17 op_sel:[0,1,0] op_sel_hi:[1,1,0]
	v_fma_mix_f32 v18, v94, v91, v18 op_sel:[0,0,0] op_sel_hi:[1,1,0]
	v_add_f32_dpp v20, v20, v20 row_mirror row_mask:0xf bank_mask:0xf bound_ctrl:1
	v_fma_mix_f32 v19, v94, v91, v19 op_sel:[0,1,0] op_sel_hi:[1,1,0]
	v_fma_mix_f32 v10, v20, v88, v16 op_sel:[0,0,0] op_sel_hi:[0,1,0]
	v_fma_mix_f32 v11, v20, v88, v17 op_sel:[0,1,0] op_sel_hi:[0,1,0]
	v_fma_mix_f32 v12, v20, v89, v18 op_sel:[0,0,0] op_sel_hi:[0,1,0]
	v_fma_mix_f32 v13, v20, v89, v19 op_sel:[0,1,0] op_sel_hi:[0,1,0]
	s_waitcnt lgkmcnt(4)
	ds_read_b64 v[72:73], v6 offset:9240
	ds_read_b128 v[74:77], v6 offset:9488
	ds_read_b128 v[78:81], v6 offset:9744
	ds_read_u16 v82, v7 offset:9232
	v_fma_mix_f32 v14, v10, v26, 0 op_sel:[0,0,0] op_sel_hi:[0,1,0]
	v_fma_mix_f32 v51, v10, v92, 0 op_sel:[0,0,0] op_sel_hi:[0,1,0]
	v_fma_mix_f32 v14, v11, v26, v14 op_sel:[0,1,0] op_sel_hi:[0,1,0]
	v_fma_mix_f32 v51, v11, v92, v51 op_sel:[0,1,0] op_sel_hi:[0,1,0]
	v_fma_mix_f32 v14, v12, v27, v14 op_sel:[0,0,0] op_sel_hi:[0,1,0]
	v_fma_mix_f32 v51, v12, v93, v51 op_sel:[0,0,0] op_sel_hi:[0,1,0]
	v_fma_mix_f32 v14, v13, v27, v14 op_sel:[0,1,0] op_sel_hi:[0,1,0]
	v_fma_mix_f32 v16, v10, v24, 0 op_sel:[0,0,0] op_sel_hi:[0,1,0]
	v_fma_mix_f32 v17, v11, v24, 0 op_sel:[0,1,0] op_sel_hi:[0,1,0]
	v_add_f32_dpp v20, v14, v14 quad_perm:[1,0,3,2] row_mask:0xf bank_mask:0xf bound_ctrl:1
	v_fma_mix_f32 v51, v13, v93, v51 op_sel:[0,1,0] op_sel_hi:[0,1,0]
	v_fma_mix_f32 v18, v12, v25, 0 op_sel:[0,0,0] op_sel_hi:[0,1,0]
	v_add_f32_dpp v20, v20, v20 quad_perm:[2,3,0,1] row_mask:0xf bank_mask:0xf bound_ctrl:1
	v_fma_mix_f32 v19, v13, v25, 0 op_sel:[0,1,0] op_sel_hi:[0,1,0]
	v_fma_mix_f32 v16, v34, v30, v16 op_sel:[0,0,0] op_sel_hi:[1,1,0]
	v_add_f32_dpp v20, v20, v20 row_half_mirror row_mask:0xf bank_mask:0xf bound_ctrl:1
	v_fma_mix_f32 v17, v34, v30, v17 op_sel:[0,1,0] op_sel_hi:[1,1,0]
	v_fma_mix_f32 v18, v34, v31, v18 op_sel:[0,0,0] op_sel_hi:[1,1,0]
	v_add_f32_dpp v20, v20, v20 row_mirror row_mask:0xf bank_mask:0xf bound_ctrl:1
	v_fma_mix_f32 v19, v34, v31, v19 op_sel:[0,1,0] op_sel_hi:[1,1,0]
	v_fma_mix_f32 v10, v20, v28, v16 op_sel:[0,0,0] op_sel_hi:[0,1,0]
	v_fma_mix_f32 v11, v20, v28, v17 op_sel:[0,1,0] op_sel_hi:[0,1,0]
	v_fma_mix_f32 v12, v20, v29, v18 op_sel:[0,0,0] op_sel_hi:[0,1,0]
	v_fma_mix_f32 v13, v20, v29, v19 op_sel:[0,1,0] op_sel_hi:[0,1,0]
	s_waitcnt lgkmcnt(4)
	ds_read_b64 v[84:85], v6 offset:8216
	ds_read_b128 v[86:89], v6 offset:8464
	ds_read_b128 v[90:93], v6 offset:8720
	ds_read_u16 v94, v7 offset:8208
	v_fma_mix_f32 v14, v10, v38, 0 op_sel:[0,0,0] op_sel_hi:[0,1,0]
	v_fma_mix_f32 v52, v10, v32, 0 op_sel:[0,0,0] op_sel_hi:[0,1,0]
	v_fma_mix_f32 v14, v11, v38, v14 op_sel:[0,1,0] op_sel_hi:[0,1,0]
	v_fma_mix_f32 v52, v11, v32, v52 op_sel:[0,1,0] op_sel_hi:[0,1,0]
	v_fma_mix_f32 v14, v12, v39, v14 op_sel:[0,0,0] op_sel_hi:[0,1,0]
	v_fma_mix_f32 v52, v12, v33, v52 op_sel:[0,0,0] op_sel_hi:[0,1,0]
	v_fma_mix_f32 v14, v13, v39, v14 op_sel:[0,1,0] op_sel_hi:[0,1,0]
	v_fma_mix_f32 v16, v10, v36, 0 op_sel:[0,0,0] op_sel_hi:[0,1,0]
	v_fma_mix_f32 v17, v11, v36, 0 op_sel:[0,1,0] op_sel_hi:[0,1,0]
	v_add_f32_dpp v20, v14, v14 quad_perm:[1,0,3,2] row_mask:0xf bank_mask:0xf bound_ctrl:1
	v_fma_mix_f32 v52, v13, v33, v52 op_sel:[0,1,0] op_sel_hi:[0,1,0]
	v_fma_mix_f32 v18, v12, v37, 0 op_sel:[0,0,0] op_sel_hi:[0,1,0]
	v_add_f32_dpp v20, v20, v20 quad_perm:[2,3,0,1] row_mask:0xf bank_mask:0xf bound_ctrl:1
	v_fma_mix_f32 v19, v13, v37, 0 op_sel:[0,1,0] op_sel_hi:[0,1,0]
	v_fma_mix_f32 v16, v46, v42, v16 op_sel:[0,0,0] op_sel_hi:[1,1,0]
	v_add_f32_dpp v20, v20, v20 row_half_mirror row_mask:0xf bank_mask:0xf bound_ctrl:1
	v_fma_mix_f32 v17, v46, v42, v17 op_sel:[0,1,0] op_sel_hi:[1,1,0]
	v_fma_mix_f32 v18, v46, v43, v18 op_sel:[0,0,0] op_sel_hi:[1,1,0]
	v_add_f32_dpp v20, v20, v20 row_mirror row_mask:0xf bank_mask:0xf bound_ctrl:1
	v_fma_mix_f32 v19, v46, v43, v19 op_sel:[0,1,0] op_sel_hi:[1,1,0]
	v_fma_mix_f32 v10, v20, v40, v16 op_sel:[0,0,0] op_sel_hi:[0,1,0]
	v_fma_mix_f32 v11, v20, v40, v17 op_sel:[0,1,0] op_sel_hi:[0,1,0]
	v_fma_mix_f32 v12, v20, v41, v18 op_sel:[0,0,0] op_sel_hi:[0,1,0]
	v_fma_mix_f32 v13, v20, v41, v19 op_sel:[0,1,0] op_sel_hi:[0,1,0]
	s_waitcnt lgkmcnt(4)
	ds_read_b64 v[24:25], v6 offset:7192
	ds_read_b128 v[26:29], v6 offset:7440
	ds_read_b128 v[30:33], v6 offset:7696
	ds_read_u16 v34, v7 offset:7184
	v_fma_mix_f32 v14, v10, v74, 0 op_sel:[0,0,0] op_sel_hi:[0,1,0]
	v_fma_mix_f32 v53, v10, v44, 0 op_sel:[0,0,0] op_sel_hi:[0,1,0]
	v_fma_mix_f32 v14, v11, v74, v14 op_sel:[0,1,0] op_sel_hi:[0,1,0]
	v_fma_mix_f32 v53, v11, v44, v53 op_sel:[0,1,0] op_sel_hi:[0,1,0]
	v_fma_mix_f32 v14, v12, v75, v14 op_sel:[0,0,0] op_sel_hi:[0,1,0]
	v_fma_mix_f32 v53, v12, v45, v53 op_sel:[0,0,0] op_sel_hi:[0,1,0]
	v_fma_mix_f32 v14, v13, v75, v14 op_sel:[0,1,0] op_sel_hi:[0,1,0]
	v_fma_mix_f32 v16, v10, v72, 0 op_sel:[0,0,0] op_sel_hi:[0,1,0]
	v_fma_mix_f32 v17, v11, v72, 0 op_sel:[0,1,0] op_sel_hi:[0,1,0]
	v_add_f32_dpp v20, v14, v14 quad_perm:[1,0,3,2] row_mask:0xf bank_mask:0xf bound_ctrl:1
	v_fma_mix_f32 v53, v13, v45, v53 op_sel:[0,1,0] op_sel_hi:[0,1,0]
	v_fma_mix_f32 v18, v12, v73, 0 op_sel:[0,0,0] op_sel_hi:[0,1,0]
	v_add_f32_dpp v20, v20, v20 quad_perm:[2,3,0,1] row_mask:0xf bank_mask:0xf bound_ctrl:1
	v_fma_mix_f32 v19, v13, v73, 0 op_sel:[0,1,0] op_sel_hi:[0,1,0]
	v_fma_mix_f32 v16, v82, v78, v16 op_sel:[0,0,0] op_sel_hi:[1,1,0]
	v_add_f32_dpp v20, v20, v20 row_half_mirror row_mask:0xf bank_mask:0xf bound_ctrl:1
	v_fma_mix_f32 v17, v82, v78, v17 op_sel:[0,1,0] op_sel_hi:[1,1,0]
	v_fma_mix_f32 v18, v82, v79, v18 op_sel:[0,0,0] op_sel_hi:[1,1,0]
	v_add_f32_dpp v20, v20, v20 row_mirror row_mask:0xf bank_mask:0xf bound_ctrl:1
	v_fma_mix_f32 v19, v82, v79, v19 op_sel:[0,1,0] op_sel_hi:[1,1,0]
	v_fma_mix_f32 v10, v20, v76, v16 op_sel:[0,0,0] op_sel_hi:[0,1,0]
	v_fma_mix_f32 v11, v20, v76, v17 op_sel:[0,1,0] op_sel_hi:[0,1,0]
	v_fma_mix_f32 v12, v20, v77, v18 op_sel:[0,0,0] op_sel_hi:[0,1,0]
	v_fma_mix_f32 v13, v20, v77, v19 op_sel:[0,1,0] op_sel_hi:[0,1,0]
	s_waitcnt lgkmcnt(4)
	ds_read_b64 v[36:37], v6 offset:6168
	ds_read_b128 v[38:41], v6 offset:6416
	ds_read_b128 v[42:45], v6 offset:6672
	ds_read_u16 v46, v7 offset:6160
	v_fma_mix_f32 v14, v10, v86, 0 op_sel:[0,0,0] op_sel_hi:[0,1,0]
	v_fma_mix_f32 v54, v10, v80, 0 op_sel:[0,0,0] op_sel_hi:[0,1,0]
	v_fma_mix_f32 v14, v11, v86, v14 op_sel:[0,1,0] op_sel_hi:[0,1,0]
	v_fma_mix_f32 v54, v11, v80, v54 op_sel:[0,1,0] op_sel_hi:[0,1,0]
	v_fma_mix_f32 v14, v12, v87, v14 op_sel:[0,0,0] op_sel_hi:[0,1,0]
	v_fma_mix_f32 v54, v12, v81, v54 op_sel:[0,0,0] op_sel_hi:[0,1,0]
	v_fma_mix_f32 v14, v13, v87, v14 op_sel:[0,1,0] op_sel_hi:[0,1,0]
	v_fma_mix_f32 v16, v10, v84, 0 op_sel:[0,0,0] op_sel_hi:[0,1,0]
	v_fma_mix_f32 v17, v11, v84, 0 op_sel:[0,1,0] op_sel_hi:[0,1,0]
	v_add_f32_dpp v20, v14, v14 quad_perm:[1,0,3,2] row_mask:0xf bank_mask:0xf bound_ctrl:1
	v_fma_mix_f32 v54, v13, v81, v54 op_sel:[0,1,0] op_sel_hi:[0,1,0]
	v_fma_mix_f32 v18, v12, v85, 0 op_sel:[0,0,0] op_sel_hi:[0,1,0]
	v_add_f32_dpp v20, v20, v20 quad_perm:[2,3,0,1] row_mask:0xf bank_mask:0xf bound_ctrl:1
	v_fma_mix_f32 v19, v13, v85, 0 op_sel:[0,1,0] op_sel_hi:[0,1,0]
	v_fma_mix_f32 v16, v94, v90, v16 op_sel:[0,0,0] op_sel_hi:[1,1,0]
	v_add_f32_dpp v20, v20, v20 row_half_mirror row_mask:0xf bank_mask:0xf bound_ctrl:1
	v_fma_mix_f32 v17, v94, v90, v17 op_sel:[0,1,0] op_sel_hi:[1,1,0]
	v_fma_mix_f32 v18, v94, v91, v18 op_sel:[0,0,0] op_sel_hi:[1,1,0]
	v_add_f32_dpp v20, v20, v20 row_mirror row_mask:0xf bank_mask:0xf bound_ctrl:1
	v_fma_mix_f32 v19, v94, v91, v19 op_sel:[0,1,0] op_sel_hi:[1,1,0]
	v_fma_mix_f32 v10, v20, v88, v16 op_sel:[0,0,0] op_sel_hi:[0,1,0]
	v_fma_mix_f32 v11, v20, v88, v17 op_sel:[0,1,0] op_sel_hi:[0,1,0]
	v_fma_mix_f32 v12, v20, v89, v18 op_sel:[0,0,0] op_sel_hi:[0,1,0]
	v_fma_mix_f32 v13, v20, v89, v19 op_sel:[0,1,0] op_sel_hi:[0,1,0]
	s_waitcnt lgkmcnt(4)
	ds_read_b64 v[72:73], v6 offset:5144
	ds_read_b128 v[74:77], v6 offset:5392
	ds_read_b128 v[78:81], v6 offset:5648
	ds_read_u16 v82, v7 offset:5136
	v_fma_mix_f32 v14, v10, v26, 0 op_sel:[0,0,0] op_sel_hi:[0,1,0]
	v_fma_mix_f32 v55, v10, v92, 0 op_sel:[0,0,0] op_sel_hi:[0,1,0]
	v_fma_mix_f32 v14, v11, v26, v14 op_sel:[0,1,0] op_sel_hi:[0,1,0]
	v_fma_mix_f32 v55, v11, v92, v55 op_sel:[0,1,0] op_sel_hi:[0,1,0]
	v_fma_mix_f32 v14, v12, v27, v14 op_sel:[0,0,0] op_sel_hi:[0,1,0]
	v_fma_mix_f32 v55, v12, v93, v55 op_sel:[0,0,0] op_sel_hi:[0,1,0]
	v_fma_mix_f32 v14, v13, v27, v14 op_sel:[0,1,0] op_sel_hi:[0,1,0]
	v_fma_mix_f32 v16, v10, v24, 0 op_sel:[0,0,0] op_sel_hi:[0,1,0]
	v_fma_mix_f32 v17, v11, v24, 0 op_sel:[0,1,0] op_sel_hi:[0,1,0]
	v_add_f32_dpp v20, v14, v14 quad_perm:[1,0,3,2] row_mask:0xf bank_mask:0xf bound_ctrl:1
	v_fma_mix_f32 v55, v13, v93, v55 op_sel:[0,1,0] op_sel_hi:[0,1,0]
	v_fma_mix_f32 v18, v12, v25, 0 op_sel:[0,0,0] op_sel_hi:[0,1,0]
	v_add_f32_dpp v20, v20, v20 quad_perm:[2,3,0,1] row_mask:0xf bank_mask:0xf bound_ctrl:1
	v_fma_mix_f32 v19, v13, v25, 0 op_sel:[0,1,0] op_sel_hi:[0,1,0]
	v_fma_mix_f32 v16, v34, v30, v16 op_sel:[0,0,0] op_sel_hi:[1,1,0]
	v_add_f32_dpp v20, v20, v20 row_half_mirror row_mask:0xf bank_mask:0xf bound_ctrl:1
	v_fma_mix_f32 v17, v34, v30, v17 op_sel:[0,1,0] op_sel_hi:[1,1,0]
	v_fma_mix_f32 v18, v34, v31, v18 op_sel:[0,0,0] op_sel_hi:[1,1,0]
	v_add_f32_dpp v20, v20, v20 row_mirror row_mask:0xf bank_mask:0xf bound_ctrl:1
	v_fma_mix_f32 v19, v34, v31, v19 op_sel:[0,1,0] op_sel_hi:[1,1,0]
	v_fma_mix_f32 v10, v20, v28, v16 op_sel:[0,0,0] op_sel_hi:[0,1,0]
	v_fma_mix_f32 v11, v20, v28, v17 op_sel:[0,1,0] op_sel_hi:[0,1,0]
	v_fma_mix_f32 v12, v20, v29, v18 op_sel:[0,0,0] op_sel_hi:[0,1,0]
	v_fma_mix_f32 v13, v20, v29, v19 op_sel:[0,1,0] op_sel_hi:[0,1,0]
	s_waitcnt lgkmcnt(4)
	ds_read_b64 v[84:85], v6 offset:4120
	ds_read_b128 v[86:89], v6 offset:4368
	ds_read_b128 v[90:93], v6 offset:4624
	ds_read_u16 v94, v7 offset:4112
	v_fma_mix_f32 v14, v10, v38, 0 op_sel:[0,0,0] op_sel_hi:[0,1,0]
	v_fma_mix_f32 v56, v10, v32, 0 op_sel:[0,0,0] op_sel_hi:[0,1,0]
	v_fma_mix_f32 v14, v11, v38, v14 op_sel:[0,1,0] op_sel_hi:[0,1,0]
	v_fma_mix_f32 v56, v11, v32, v56 op_sel:[0,1,0] op_sel_hi:[0,1,0]
	v_fma_mix_f32 v14, v12, v39, v14 op_sel:[0,0,0] op_sel_hi:[0,1,0]
	v_fma_mix_f32 v56, v12, v33, v56 op_sel:[0,0,0] op_sel_hi:[0,1,0]
	v_fma_mix_f32 v14, v13, v39, v14 op_sel:[0,1,0] op_sel_hi:[0,1,0]
	v_fma_mix_f32 v16, v10, v36, 0 op_sel:[0,0,0] op_sel_hi:[0,1,0]
	v_fma_mix_f32 v17, v11, v36, 0 op_sel:[0,1,0] op_sel_hi:[0,1,0]
	v_add_f32_dpp v20, v14, v14 quad_perm:[1,0,3,2] row_mask:0xf bank_mask:0xf bound_ctrl:1
	v_fma_mix_f32 v56, v13, v33, v56 op_sel:[0,1,0] op_sel_hi:[0,1,0]
	v_fma_mix_f32 v18, v12, v37, 0 op_sel:[0,0,0] op_sel_hi:[0,1,0]
	v_add_f32_dpp v20, v20, v20 quad_perm:[2,3,0,1] row_mask:0xf bank_mask:0xf bound_ctrl:1
	v_fma_mix_f32 v19, v13, v37, 0 op_sel:[0,1,0] op_sel_hi:[0,1,0]
	v_fma_mix_f32 v16, v46, v42, v16 op_sel:[0,0,0] op_sel_hi:[1,1,0]
	v_add_f32_dpp v20, v20, v20 row_half_mirror row_mask:0xf bank_mask:0xf bound_ctrl:1
	v_fma_mix_f32 v17, v46, v42, v17 op_sel:[0,1,0] op_sel_hi:[1,1,0]
	v_fma_mix_f32 v18, v46, v43, v18 op_sel:[0,0,0] op_sel_hi:[1,1,0]
	v_add_f32_dpp v20, v20, v20 row_mirror row_mask:0xf bank_mask:0xf bound_ctrl:1
	v_fma_mix_f32 v19, v46, v43, v19 op_sel:[0,1,0] op_sel_hi:[1,1,0]
	v_fma_mix_f32 v10, v20, v40, v16 op_sel:[0,0,0] op_sel_hi:[0,1,0]
	v_fma_mix_f32 v11, v20, v40, v17 op_sel:[0,1,0] op_sel_hi:[0,1,0]
	v_fma_mix_f32 v12, v20, v41, v18 op_sel:[0,0,0] op_sel_hi:[0,1,0]
	v_fma_mix_f32 v13, v20, v41, v19 op_sel:[0,1,0] op_sel_hi:[0,1,0]
	s_waitcnt lgkmcnt(4)
	ds_read_b64 v[24:25], v6 offset:3096
	ds_read_b128 v[26:29], v6 offset:3344
	ds_read_b128 v[30:33], v6 offset:3600
	ds_read_u16 v34, v7 offset:3088
	v_fma_mix_f32 v14, v10, v74, 0 op_sel:[0,0,0] op_sel_hi:[0,1,0]
	v_fma_mix_f32 v57, v10, v44, 0 op_sel:[0,0,0] op_sel_hi:[0,1,0]
	v_fma_mix_f32 v14, v11, v74, v14 op_sel:[0,1,0] op_sel_hi:[0,1,0]
	v_fma_mix_f32 v57, v11, v44, v57 op_sel:[0,1,0] op_sel_hi:[0,1,0]
	v_fma_mix_f32 v14, v12, v75, v14 op_sel:[0,0,0] op_sel_hi:[0,1,0]
	v_fma_mix_f32 v57, v12, v45, v57 op_sel:[0,0,0] op_sel_hi:[0,1,0]
	v_fma_mix_f32 v14, v13, v75, v14 op_sel:[0,1,0] op_sel_hi:[0,1,0]
	v_fma_mix_f32 v16, v10, v72, 0 op_sel:[0,0,0] op_sel_hi:[0,1,0]
	v_fma_mix_f32 v17, v11, v72, 0 op_sel:[0,1,0] op_sel_hi:[0,1,0]
	v_add_f32_dpp v20, v14, v14 quad_perm:[1,0,3,2] row_mask:0xf bank_mask:0xf bound_ctrl:1
	v_fma_mix_f32 v57, v13, v45, v57 op_sel:[0,1,0] op_sel_hi:[0,1,0]
	v_fma_mix_f32 v18, v12, v73, 0 op_sel:[0,0,0] op_sel_hi:[0,1,0]
	v_add_f32_dpp v20, v20, v20 quad_perm:[2,3,0,1] row_mask:0xf bank_mask:0xf bound_ctrl:1
	v_fma_mix_f32 v19, v13, v73, 0 op_sel:[0,1,0] op_sel_hi:[0,1,0]
	v_fma_mix_f32 v16, v82, v78, v16 op_sel:[0,0,0] op_sel_hi:[1,1,0]
	v_add_f32_dpp v20, v20, v20 row_half_mirror row_mask:0xf bank_mask:0xf bound_ctrl:1
	v_fma_mix_f32 v17, v82, v78, v17 op_sel:[0,1,0] op_sel_hi:[1,1,0]
	v_fma_mix_f32 v18, v82, v79, v18 op_sel:[0,0,0] op_sel_hi:[1,1,0]
	v_add_f32_dpp v20, v20, v20 row_mirror row_mask:0xf bank_mask:0xf bound_ctrl:1
	v_fma_mix_f32 v19, v82, v79, v19 op_sel:[0,1,0] op_sel_hi:[1,1,0]
	v_fma_mix_f32 v10, v20, v76, v16 op_sel:[0,0,0] op_sel_hi:[0,1,0]
	v_fma_mix_f32 v11, v20, v76, v17 op_sel:[0,1,0] op_sel_hi:[0,1,0]
	v_fma_mix_f32 v12, v20, v77, v18 op_sel:[0,0,0] op_sel_hi:[0,1,0]
	v_fma_mix_f32 v13, v20, v77, v19 op_sel:[0,1,0] op_sel_hi:[0,1,0]
	s_waitcnt lgkmcnt(4)
	ds_read_b64 v[36:37], v6 offset:2072
	ds_read_b128 v[38:41], v6 offset:2320
	ds_read_b128 v[42:45], v6 offset:2576
	ds_read_u16 v46, v7 offset:2064
	v_fma_mix_f32 v14, v10, v86, 0 op_sel:[0,0,0] op_sel_hi:[0,1,0]
	v_fma_mix_f32 v58, v10, v80, 0 op_sel:[0,0,0] op_sel_hi:[0,1,0]
	v_fma_mix_f32 v14, v11, v86, v14 op_sel:[0,1,0] op_sel_hi:[0,1,0]
	v_fma_mix_f32 v58, v11, v80, v58 op_sel:[0,1,0] op_sel_hi:[0,1,0]
	v_fma_mix_f32 v14, v12, v87, v14 op_sel:[0,0,0] op_sel_hi:[0,1,0]
	v_fma_mix_f32 v58, v12, v81, v58 op_sel:[0,0,0] op_sel_hi:[0,1,0]
	v_fma_mix_f32 v14, v13, v87, v14 op_sel:[0,1,0] op_sel_hi:[0,1,0]
	v_fma_mix_f32 v16, v10, v84, 0 op_sel:[0,0,0] op_sel_hi:[0,1,0]
	v_fma_mix_f32 v17, v11, v84, 0 op_sel:[0,1,0] op_sel_hi:[0,1,0]
	v_add_f32_dpp v20, v14, v14 quad_perm:[1,0,3,2] row_mask:0xf bank_mask:0xf bound_ctrl:1
	v_fma_mix_f32 v58, v13, v81, v58 op_sel:[0,1,0] op_sel_hi:[0,1,0]
	v_fma_mix_f32 v18, v12, v85, 0 op_sel:[0,0,0] op_sel_hi:[0,1,0]
	v_add_f32_dpp v20, v20, v20 quad_perm:[2,3,0,1] row_mask:0xf bank_mask:0xf bound_ctrl:1
	v_fma_mix_f32 v19, v13, v85, 0 op_sel:[0,1,0] op_sel_hi:[0,1,0]
	v_fma_mix_f32 v16, v94, v90, v16 op_sel:[0,0,0] op_sel_hi:[1,1,0]
	v_add_f32_dpp v20, v20, v20 row_half_mirror row_mask:0xf bank_mask:0xf bound_ctrl:1
	v_fma_mix_f32 v17, v94, v90, v17 op_sel:[0,1,0] op_sel_hi:[1,1,0]
	v_fma_mix_f32 v18, v94, v91, v18 op_sel:[0,0,0] op_sel_hi:[1,1,0]
	v_add_f32_dpp v20, v20, v20 row_mirror row_mask:0xf bank_mask:0xf bound_ctrl:1
	v_fma_mix_f32 v19, v94, v91, v19 op_sel:[0,1,0] op_sel_hi:[1,1,0]
	v_fma_mix_f32 v10, v20, v88, v16 op_sel:[0,0,0] op_sel_hi:[0,1,0]
	v_fma_mix_f32 v11, v20, v88, v17 op_sel:[0,1,0] op_sel_hi:[0,1,0]
	v_fma_mix_f32 v12, v20, v89, v18 op_sel:[0,0,0] op_sel_hi:[0,1,0]
	v_fma_mix_f32 v13, v20, v89, v19 op_sel:[0,1,0] op_sel_hi:[0,1,0]
	s_waitcnt lgkmcnt(4)
	ds_read_b64 v[72:73], v6 offset:1048
	ds_read_b128 v[74:77], v6 offset:1296
	ds_read_b128 v[78:81], v6 offset:1552
	ds_read_u16 v82, v7 offset:1040
	v_fma_mix_f32 v14, v10, v26, 0 op_sel:[0,0,0] op_sel_hi:[0,1,0]
	v_fma_mix_f32 v59, v10, v92, 0 op_sel:[0,0,0] op_sel_hi:[0,1,0]
	v_fma_mix_f32 v14, v11, v26, v14 op_sel:[0,1,0] op_sel_hi:[0,1,0]
	v_fma_mix_f32 v59, v11, v92, v59 op_sel:[0,1,0] op_sel_hi:[0,1,0]
	v_fma_mix_f32 v14, v12, v27, v14 op_sel:[0,0,0] op_sel_hi:[0,1,0]
	v_fma_mix_f32 v59, v12, v93, v59 op_sel:[0,0,0] op_sel_hi:[0,1,0]
	v_fma_mix_f32 v14, v13, v27, v14 op_sel:[0,1,0] op_sel_hi:[0,1,0]
	v_fma_mix_f32 v16, v10, v24, 0 op_sel:[0,0,0] op_sel_hi:[0,1,0]
	v_fma_mix_f32 v17, v11, v24, 0 op_sel:[0,1,0] op_sel_hi:[0,1,0]
	v_add_f32_dpp v20, v14, v14 quad_perm:[1,0,3,2] row_mask:0xf bank_mask:0xf bound_ctrl:1
	v_fma_mix_f32 v59, v13, v93, v59 op_sel:[0,1,0] op_sel_hi:[0,1,0]
	v_fma_mix_f32 v18, v12, v25, 0 op_sel:[0,0,0] op_sel_hi:[0,1,0]
	v_add_f32_dpp v20, v20, v20 quad_perm:[2,3,0,1] row_mask:0xf bank_mask:0xf bound_ctrl:1
	v_fma_mix_f32 v19, v13, v25, 0 op_sel:[0,1,0] op_sel_hi:[0,1,0]
	v_fma_mix_f32 v16, v34, v30, v16 op_sel:[0,0,0] op_sel_hi:[1,1,0]
	v_add_f32_dpp v20, v20, v20 row_half_mirror row_mask:0xf bank_mask:0xf bound_ctrl:1
	v_fma_mix_f32 v17, v34, v30, v17 op_sel:[0,1,0] op_sel_hi:[1,1,0]
	v_fma_mix_f32 v18, v34, v31, v18 op_sel:[0,0,0] op_sel_hi:[1,1,0]
	v_add_f32_dpp v20, v20, v20 row_mirror row_mask:0xf bank_mask:0xf bound_ctrl:1
	v_fma_mix_f32 v19, v34, v31, v19 op_sel:[0,1,0] op_sel_hi:[1,1,0]
	v_fma_mix_f32 v10, v20, v28, v16 op_sel:[0,0,0] op_sel_hi:[0,1,0]
	v_fma_mix_f32 v11, v20, v28, v17 op_sel:[0,1,0] op_sel_hi:[0,1,0]
	v_fma_mix_f32 v12, v20, v29, v18 op_sel:[0,0,0] op_sel_hi:[0,1,0]
	v_fma_mix_f32 v13, v20, v29, v19 op_sel:[0,1,0] op_sel_hi:[0,1,0]
	s_waitcnt lgkmcnt(4)
	ds_read_b128 v[100:103], v9
	ds_read_b64 v[84:85], v6 offset:24
	ds_read_b128 v[86:89], v6 offset:272
	ds_read_b128 v[90:93], v6 offset:528
	ds_read_u16 v94, v7 offset:16
	v_fma_mix_f32 v14, v10, v38, 0 op_sel:[0,0,0] op_sel_hi:[0,1,0]
	v_fma_mix_f32 v60, v10, v32, 0 op_sel:[0,0,0] op_sel_hi:[0,1,0]
	v_fma_mix_f32 v14, v11, v38, v14 op_sel:[0,1,0] op_sel_hi:[0,1,0]
	v_fma_mix_f32 v60, v11, v32, v60 op_sel:[0,1,0] op_sel_hi:[0,1,0]
	v_fma_mix_f32 v14, v12, v39, v14 op_sel:[0,0,0] op_sel_hi:[0,1,0]
	v_fma_mix_f32 v60, v12, v33, v60 op_sel:[0,0,0] op_sel_hi:[0,1,0]
	v_fma_mix_f32 v14, v13, v39, v14 op_sel:[0,1,0] op_sel_hi:[0,1,0]
	v_fma_mix_f32 v16, v10, v36, 0 op_sel:[0,0,0] op_sel_hi:[0,1,0]
	v_fma_mix_f32 v17, v11, v36, 0 op_sel:[0,1,0] op_sel_hi:[0,1,0]
	v_add_f32_dpp v20, v14, v14 quad_perm:[1,0,3,2] row_mask:0xf bank_mask:0xf bound_ctrl:1
	v_fma_mix_f32 v60, v13, v33, v60 op_sel:[0,1,0] op_sel_hi:[0,1,0]
	v_fma_mix_f32 v18, v12, v37, 0 op_sel:[0,0,0] op_sel_hi:[0,1,0]
	v_add_f32_dpp v20, v20, v20 quad_perm:[2,3,0,1] row_mask:0xf bank_mask:0xf bound_ctrl:1
	v_fma_mix_f32 v19, v13, v37, 0 op_sel:[0,1,0] op_sel_hi:[0,1,0]
	v_fma_mix_f32 v16, v46, v42, v16 op_sel:[0,0,0] op_sel_hi:[1,1,0]
	v_add_f32_dpp v20, v20, v20 row_half_mirror row_mask:0xf bank_mask:0xf bound_ctrl:1
	v_fma_mix_f32 v17, v46, v42, v17 op_sel:[0,1,0] op_sel_hi:[1,1,0]
	v_fma_mix_f32 v18, v46, v43, v18 op_sel:[0,0,0] op_sel_hi:[1,1,0]
	v_add_f32_dpp v20, v20, v20 row_mirror row_mask:0xf bank_mask:0xf bound_ctrl:1
	v_fma_mix_f32 v19, v46, v43, v19 op_sel:[0,1,0] op_sel_hi:[1,1,0]
	v_fma_mix_f32 v10, v20, v40, v16 op_sel:[0,0,0] op_sel_hi:[0,1,0]
	v_fma_mix_f32 v11, v20, v40, v17 op_sel:[0,1,0] op_sel_hi:[0,1,0]
	v_fma_mix_f32 v12, v20, v41, v18 op_sel:[0,0,0] op_sel_hi:[0,1,0]
	v_fma_mix_f32 v13, v20, v41, v19 op_sel:[0,1,0] op_sel_hi:[0,1,0]
	s_waitcnt lgkmcnt(4)
	v_add_u32_e32 v6, 0xffffc000, v6
	v_add_u32_e32 v7, 0xffffc000, v7
	v_and_b32_e32 v6, 0x1ffff, v6
	v_and_b32_e32 v7, 0x1ffff, v7
	ds_read_b64 v[24:25], v6 offset:15384
	ds_read_b128 v[26:29], v6 offset:15632
	ds_read_b128 v[30:33], v6 offset:15888
	ds_read_u16 v34, v7 offset:15376
	v_fma_mix_f32 v14, v10, v74, 0 op_sel:[0,0,0] op_sel_hi:[0,1,0]
	v_fma_mix_f32 v61, v10, v44, 0 op_sel:[0,0,0] op_sel_hi:[0,1,0]
	v_fma_mix_f32 v14, v11, v74, v14 op_sel:[0,1,0] op_sel_hi:[0,1,0]
	v_fma_mix_f32 v61, v11, v44, v61 op_sel:[0,1,0] op_sel_hi:[0,1,0]
	v_fma_mix_f32 v14, v12, v75, v14 op_sel:[0,0,0] op_sel_hi:[0,1,0]
	v_fma_mix_f32 v61, v12, v45, v61 op_sel:[0,0,0] op_sel_hi:[0,1,0]
	v_fma_mix_f32 v14, v13, v75, v14 op_sel:[0,1,0] op_sel_hi:[0,1,0]
	v_fma_mix_f32 v16, v10, v72, 0 op_sel:[0,0,0] op_sel_hi:[0,1,0]
	v_fma_mix_f32 v17, v11, v72, 0 op_sel:[0,1,0] op_sel_hi:[0,1,0]
	v_add_f32_dpp v20, v14, v14 quad_perm:[1,0,3,2] row_mask:0xf bank_mask:0xf bound_ctrl:1
	v_fma_mix_f32 v61, v13, v45, v61 op_sel:[0,1,0] op_sel_hi:[0,1,0]
	v_fma_mix_f32 v18, v12, v73, 0 op_sel:[0,0,0] op_sel_hi:[0,1,0]
	v_add_f32_dpp v20, v20, v20 quad_perm:[2,3,0,1] row_mask:0xf bank_mask:0xf bound_ctrl:1
	v_fma_mix_f32 v19, v13, v73, 0 op_sel:[0,1,0] op_sel_hi:[0,1,0]
	v_fma_mix_f32 v16, v82, v78, v16 op_sel:[0,0,0] op_sel_hi:[1,1,0]
	v_add_f32_dpp v20, v20, v20 row_half_mirror row_mask:0xf bank_mask:0xf bound_ctrl:1
	v_fma_mix_f32 v17, v82, v78, v17 op_sel:[0,1,0] op_sel_hi:[1,1,0]
	v_fma_mix_f32 v18, v82, v79, v18 op_sel:[0,0,0] op_sel_hi:[1,1,0]
	v_add_f32_dpp v20, v20, v20 row_mirror row_mask:0xf bank_mask:0xf bound_ctrl:1
	v_fma_mix_f32 v19, v82, v79, v19 op_sel:[0,1,0] op_sel_hi:[1,1,0]
	v_fma_mix_f32 v10, v20, v76, v16 op_sel:[0,0,0] op_sel_hi:[0,1,0]
	v_fma_mix_f32 v11, v20, v76, v17 op_sel:[0,1,0] op_sel_hi:[0,1,0]
	v_fma_mix_f32 v12, v20, v77, v18 op_sel:[0,0,0] op_sel_hi:[0,1,0]
	v_fma_mix_f32 v13, v20, v77, v19 op_sel:[0,1,0] op_sel_hi:[0,1,0]
	s_waitcnt lgkmcnt(4)
; DEVINL u16 f2bf(float a) { return (u16)(pk2(a, 0.f) & 0xffffu); }
; template <int DIR>
; DEVINL void rwkv_scan_dir(const Params& p, int task, int lane, int wave) {
;     ...
;   for (int st = 0; st < 4096; st += 32) {
;     RW_STEP(0, WvA, XA, KrA, vhA, WvB, XB, KrB, vhB);
;     if (st > 0) { const int q0 = st - 16 + seg; yo[(long)(DIR ? (4095 - q0) : q0) * 1024] = f2bf(ykeep); }
;     RW_STEP(1, WvB, XB, KrB, vhB, WvA, XA, KrA, vhA);
	ds_read_b64 v[36:37], v6 offset:14360
	ds_read_b128 v[38:41], v6 offset:14608
	ds_read_b128 v[42:45], v6 offset:14864
	ds_read_u16 v46, v7 offset:14352
	v_fma_mix_f32 v14, v10, v86, 0 op_sel:[0,0,0] op_sel_hi:[0,1,0]
	v_fma_mix_f32 v62, v10, v80, 0 op_sel:[0,0,0] op_sel_hi:[0,1,0]
	v_fma_mix_f32 v14, v11, v86, v14 op_sel:[0,1,0] op_sel_hi:[0,1,0]
	v_fma_mix_f32 v62, v11, v80, v62 op_sel:[0,1,0] op_sel_hi:[0,1,0]
	v_fma_mix_f32 v14, v12, v87, v14 op_sel:[0,0,0] op_sel_hi:[0,1,0]
	v_fma_mix_f32 v62, v12, v81, v62 op_sel:[0,0,0] op_sel_hi:[0,1,0]
	v_fma_mix_f32 v14, v13, v87, v14 op_sel:[0,1,0] op_sel_hi:[0,1,0]
	v_fma_mix_f32 v16, v10, v84, 0 op_sel:[0,0,0] op_sel_hi:[0,1,0]
	v_fma_mix_f32 v17, v11, v84, 0 op_sel:[0,1,0] op_sel_hi:[0,1,0]
	v_add_f32_dpp v20, v14, v14 quad_perm:[1,0,3,2] row_mask:0xf bank_mask:0xf bound_ctrl:1
	v_fma_mix_f32 v62, v13, v81, v62 op_sel:[0,1,0] op_sel_hi:[0,1,0]
	v_fma_mix_f32 v18, v12, v85, 0 op_sel:[0,0,0] op_sel_hi:[0,1,0]
	v_add_f32_dpp v20, v20, v20 quad_perm:[2,3,0,1] row_mask:0xf bank_mask:0xf bound_ctrl:1
	v_fma_mix_f32 v19, v13, v85, 0 op_sel:[0,1,0] op_sel_hi:[0,1,0]
	v_fma_mix_f32 v16, v94, v90, v16 op_sel:[0,0,0] op_sel_hi:[1,1,0]
	v_add_f32_dpp v20, v20, v20 row_half_mirror row_mask:0xf bank_mask:0xf bound_ctrl:1
	v_fma_mix_f32 v17, v94, v90, v17 op_sel:[0,1,0] op_sel_hi:[1,1,0]
	v_fma_mix_f32 v18, v94, v91, v18 op_sel:[0,0,0] op_sel_hi:[1,1,0]
	v_add_f32_dpp v20, v20, v20 row_mirror row_mask:0xf bank_mask:0xf bound_ctrl:1
	v_fma_mix_f32 v19, v94, v91, v19 op_sel:[0,1,0] op_sel_hi:[1,1,0]
	v_fma_mix_f32 v10, v20, v88, v16 op_sel:[0,0,0] op_sel_hi:[0,1,0]
	v_fma_mix_f32 v11, v20, v88, v17 op_sel:[0,1,0] op_sel_hi:[0,1,0]
	v_fma_mix_f32 v12, v20, v89, v18 op_sel:[0,0,0] op_sel_hi:[0,1,0]
	v_fma_mix_f32 v13, v20, v89, v19 op_sel:[0,1,0] op_sel_hi:[0,1,0]
	s_waitcnt lgkmcnt(4)
	s_add_u32 s43, s43, 1
	s_waitcnt vmcnt(0)
	v_add_u32_e32 v69, 1, v69
	ds_write_b32 v23, v69
	v_min3_u32 v100, v100, v101, v102
	v_min_u32_e32 v100, v100, v103
	s_nop 0
	v_readfirstlane_b32 s24, v100
	s_nop 0
	s_cmp_ge_u32 s24, s43
	s_cbranch_scc0 .Lrw_slow_d1b1
.Lrw_ready_d1b1:
	s_add_u32 m0, s41, 16
	s_nop 0
	global_load_lds_dwordx4 v5, s[10:11] offset:0
	global_load_lds_dwordx4 v5, s[10:11] offset:1024
	global_load_lds_dwordx4 v5, s[10:11] offset:2048
	global_load_lds_dwordx4 v5, s[10:11] offset:3072
	s_sub_u32 s10, s10, 0x4000
	s_subb_u32 s11, s11, 0
	s_sub_u32 s41, s41, 0x4000
	s_and_b32 s41, s41, 0x1ffff
	ds_read_b64 v[72:73], v6 offset:13336
	ds_read_b128 v[74:77], v6 offset:13584
	ds_read_b128 v[78:81], v6 offset:13840
	ds_read_u16 v82, v7 offset:13328
	v_fma_mix_f32 v14, v10, v26, 0 op_sel:[0,0,0] op_sel_hi:[0,1,0]
	v_fma_mix_f32 v63, v10, v92, 0 op_sel:[0,0,0] op_sel_hi:[0,1,0]
	v_fma_mix_f32 v14, v11, v26, v14 op_sel:[0,1,0] op_sel_hi:[0,1,0]
	v_fma_mix_f32 v63, v11, v92, v63 op_sel:[0,1,0] op_sel_hi:[0,1,0]
	v_fma_mix_f32 v14, v12, v27, v14 op_sel:[0,0,0] op_sel_hi:[0,1,0]
	v_fma_mix_f32 v63, v12, v93, v63 op_sel:[0,0,0] op_sel_hi:[0,1,0]
	v_fma_mix_f32 v14, v13, v27, v14 op_sel:[0,1,0] op_sel_hi:[0,1,0]
	v_fma_mix_f32 v16, v10, v24, 0 op_sel:[0,0,0] op_sel_hi:[0,1,0]
	v_fma_mix_f32 v17, v11, v24, 0 op_sel:[0,1,0] op_sel_hi:[0,1,0]
	v_add_f32_dpp v20, v14, v14 quad_perm:[1,0,3,2] row_mask:0xf bank_mask:0xf bound_ctrl:1
	v_fma_mix_f32 v63, v13, v93, v63 op_sel:[0,1,0] op_sel_hi:[0,1,0]
	v_fma_mix_f32 v18, v12, v25, 0 op_sel:[0,0,0] op_sel_hi:[0,1,0]
	v_add_f32_dpp v20, v20, v20 quad_perm:[2,3,0,1] row_mask:0xf bank_mask:0xf bound_ctrl:1
	v_fma_mix_f32 v19, v13, v25, 0 op_sel:[0,1,0] op_sel_hi:[0,1,0]
	v_fma_mix_f32 v16, v34, v30, v16 op_sel:[0,0,0] op_sel_hi:[1,1,0]
	v_add_f32_dpp v20, v20, v20 row_half_mirror row_mask:0xf bank_mask:0xf bound_ctrl:1
	v_fma_mix_f32 v17, v34, v30, v17 op_sel:[0,1,0] op_sel_hi:[1,1,0]
	v_fma_mix_f32 v18, v34, v31, v18 op_sel:[0,0,0] op_sel_hi:[1,1,0]
	v_add_f32_dpp v20, v20, v20 row_mirror row_mask:0xf bank_mask:0xf bound_ctrl:1
	v_fma_mix_f32 v19, v34, v31, v19 op_sel:[0,1,0] op_sel_hi:[1,1,0]
	v_fma_mix_f32 v10, v20, v28, v16 op_sel:[0,0,0] op_sel_hi:[0,1,0]
	v_fma_mix_f32 v11, v20, v28, v17 op_sel:[0,1,0] op_sel_hi:[0,1,0]
	v_fma_mix_f32 v12, v20, v29, v18 op_sel:[0,0,0] op_sel_hi:[0,1,0]
	v_fma_mix_f32 v13, v20, v29, v19 op_sel:[0,1,0] op_sel_hi:[0,1,0]
	s_waitcnt lgkmcnt(4)
; DEVINL u16 f2bf(float a) { return (u16)(pk2(a, 0.f) & 0xffffu); }
; #define RW_STEP2(B) RW_STEP(B, WvA, XA, KrA, vhA, WvB, XB, KrB, vhB); RW_STEP((B) + 1, WvB, XB, KrB, vhB, WvA, XA, KrA, vhA)
; #define RW_STEP4(B) RW_STEP2(B); RW_STEP2((B) + 2)
; template <int DIR>
; DEVINL void rwkv_scan_dir(const Params& p, int task, int lane, int wave) {
;     ...
;     if (st > 0) { const int q0 = st - 16 + seg; yo[(long)(DIR ? (4095 - q0) : q0) * 1024] = f2bf(ykeep); }
;     RW_STEP(1, WvB, XB, KrB, vhB, WvA, XA, KrA, vhA);
;     RW_STEP2(2); RW_STEP4(4); RW_STEP4(8); RW_STEP4(12);
;     RW_STEP(16, WvA, XA, KrA, vhA, WvB, XB, KrB, vhB);
;     { const int q0 = st + seg; yo[(long)(DIR ? (4095 - q0) : q0) * 1024] = f2bf(ykeep); }
	v_add_f32_dpp v48, v48, v48 row_ror:8 row_mask:0xf bank_mask:0x3
	v_add_f32_dpp v49, v49, v49 row_ror:8 row_mask:0xf bank_mask:0x3
	v_add_f32_dpp v50, v50, v50 row_ror:8 row_mask:0xf bank_mask:0x3
	v_add_f32_dpp v51, v51, v51 row_ror:8 row_mask:0xf bank_mask:0x3
	v_add_f32_dpp v52, v52, v52 row_ror:8 row_mask:0xf bank_mask:0x3
	v_add_f32_dpp v53, v53, v53 row_ror:8 row_mask:0xf bank_mask:0x3
	v_add_f32_dpp v54, v54, v54 row_ror:8 row_mask:0xf bank_mask:0x3
	v_add_f32_dpp v55, v55, v55 row_ror:8 row_mask:0xf bank_mask:0x3
	v_add_f32_dpp v48, v56, v56 row_ror:8 row_mask:0xf bank_mask:0xc
	v_add_f32_dpp v49, v57, v57 row_ror:8 row_mask:0xf bank_mask:0xc
	v_add_f32_dpp v50, v58, v58 row_ror:8 row_mask:0xf bank_mask:0xc
	v_add_f32_dpp v51, v59, v59 row_ror:8 row_mask:0xf bank_mask:0xc
	v_add_f32_dpp v52, v60, v60 row_ror:8 row_mask:0xf bank_mask:0xc
	v_add_f32_dpp v53, v61, v61 row_ror:8 row_mask:0xf bank_mask:0xc
	v_add_f32_dpp v54, v62, v62 row_ror:8 row_mask:0xf bank_mask:0xc
	v_add_f32_dpp v55, v63, v63 row_ror:8 row_mask:0xf bank_mask:0xc
	v_add_f32_dpp v48, v48, v48 row_ror:12 row_mask:0xf bank_mask:0x5
	v_add_f32_dpp v49, v49, v49 row_ror:12 row_mask:0xf bank_mask:0x5
	v_add_f32_dpp v50, v50, v50 row_ror:12 row_mask:0xf bank_mask:0x5
	v_add_f32_dpp v51, v51, v51 row_ror:12 row_mask:0xf bank_mask:0x5
	v_add_f32_dpp v48, v52, v52 row_ror:4 row_mask:0xf bank_mask:0xa
	v_add_f32_dpp v49, v53, v53 row_ror:4 row_mask:0xf bank_mask:0xa
	v_add_f32_dpp v50, v54, v54 row_ror:4 row_mask:0xf bank_mask:0xa
	v_add_f32_dpp v51, v55, v55 row_ror:4 row_mask:0xf bank_mask:0xa
	v_add_f32_dpp v64, v48, v48 quad_perm:[2,3,0,1] row_mask:0xf bank_mask:0xf bound_ctrl:1
	v_add_f32_dpp v65, v50, v50 quad_perm:[2,3,0,1] row_mask:0xf bank_mask:0xf bound_ctrl:1
	v_cndmask_b32_e64 v56, v64, v65, s[50:51]
	v_add_f32_dpp v64, v49, v49 quad_perm:[2,3,0,1] row_mask:0xf bank_mask:0xf bound_ctrl:1
	v_add_f32_dpp v65, v51, v51 quad_perm:[2,3,0,1] row_mask:0xf bank_mask:0xf bound_ctrl:1
	v_cndmask_b32_e64 v57, v64, v65, s[50:51]
	v_add_f32_dpp v64, v56, v56 quad_perm:[1,0,3,2] row_mask:0xf bank_mask:0xf bound_ctrl:1
	s_nop 0
	v_add_f32_dpp v65, v57, v57 quad_perm:[1,0,3,2] row_mask:0xf bank_mask:0xf bound_ctrl:1
	v_cndmask_b32_e64 v66, v64, v65, s[48:49]
	v_cvt_pk_bf16_f32 v66, v66, v66
	global_store_short v8, v66, s[12:13]
	s_sub_u32 s12, s12, 0x8000
	s_subb_u32 s13, s13, 0
	ds_read_b64 v[84:85], v6 offset:12312
	ds_read_b128 v[86:89], v6 offset:12560
	ds_read_b128 v[90:93], v6 offset:12816
	ds_read_u16 v94, v7 offset:12304
	v_fma_mix_f32 v14, v10, v38, 0 op_sel:[0,0,0] op_sel_hi:[0,1,0]
	v_fma_mix_f32 v48, v10, v32, 0 op_sel:[0,0,0] op_sel_hi:[0,1,0]
	v_fma_mix_f32 v14, v11, v38, v14 op_sel:[0,1,0] op_sel_hi:[0,1,0]
	v_fma_mix_f32 v48, v11, v32, v48 op_sel:[0,1,0] op_sel_hi:[0,1,0]
	v_fma_mix_f32 v14, v12, v39, v14 op_sel:[0,0,0] op_sel_hi:[0,1,0]
	v_fma_mix_f32 v48, v12, v33, v48 op_sel:[0,0,0] op_sel_hi:[0,1,0]
	v_fma_mix_f32 v14, v13, v39, v14 op_sel:[0,1,0] op_sel_hi:[0,1,0]
	v_fma_mix_f32 v16, v10, v36, 0 op_sel:[0,0,0] op_sel_hi:[0,1,0]
	v_fma_mix_f32 v17, v11, v36, 0 op_sel:[0,1,0] op_sel_hi:[0,1,0]
	v_add_f32_dpp v20, v14, v14 quad_perm:[1,0,3,2] row_mask:0xf bank_mask:0xf bound_ctrl:1
	v_fma_mix_f32 v48, v13, v33, v48 op_sel:[0,1,0] op_sel_hi:[0,1,0]
	v_fma_mix_f32 v18, v12, v37, 0 op_sel:[0,0,0] op_sel_hi:[0,1,0]
	v_add_f32_dpp v20, v20, v20 quad_perm:[2,3,0,1] row_mask:0xf bank_mask:0xf bound_ctrl:1
	v_fma_mix_f32 v19, v13, v37, 0 op_sel:[0,1,0] op_sel_hi:[0,1,0]
	v_fma_mix_f32 v16, v46, v42, v16 op_sel:[0,0,0] op_sel_hi:[1,1,0]
	v_add_f32_dpp v20, v20, v20 row_half_mirror row_mask:0xf bank_mask:0xf bound_ctrl:1
	v_fma_mix_f32 v17, v46, v42, v17 op_sel:[0,1,0] op_sel_hi:[1,1,0]
	v_fma_mix_f32 v18, v46, v43, v18 op_sel:[0,0,0] op_sel_hi:[1,1,0]
	v_add_f32_dpp v20, v20, v20 row_mirror row_mask:0xf bank_mask:0xf bound_ctrl:1
	v_fma_mix_f32 v19, v46, v43, v19 op_sel:[0,1,0] op_sel_hi:[1,1,0]
	v_fma_mix_f32 v10, v20, v40, v16 op_sel:[0,0,0] op_sel_hi:[0,1,0]
	v_fma_mix_f32 v11, v20, v40, v17 op_sel:[0,1,0] op_sel_hi:[0,1,0]
	v_fma_mix_f32 v12, v20, v41, v18 op_sel:[0,0,0] op_sel_hi:[0,1,0]
	v_fma_mix_f32 v13, v20, v41, v19 op_sel:[0,1,0] op_sel_hi:[0,1,0]
	s_waitcnt lgkmcnt(4)
	ds_read_b64 v[24:25], v6 offset:11288
	ds_read_b128 v[26:29], v6 offset:11536
	ds_read_b128 v[30:33], v6 offset:11792
	ds_read_u16 v34, v7 offset:11280
	v_fma_mix_f32 v14, v10, v74, 0 op_sel:[0,0,0] op_sel_hi:[0,1,0]
	v_fma_mix_f32 v49, v10, v44, 0 op_sel:[0,0,0] op_sel_hi:[0,1,0]
	v_fma_mix_f32 v14, v11, v74, v14 op_sel:[0,1,0] op_sel_hi:[0,1,0]
	v_fma_mix_f32 v49, v11, v44, v49 op_sel:[0,1,0] op_sel_hi:[0,1,0]
	v_fma_mix_f32 v14, v12, v75, v14 op_sel:[0,0,0] op_sel_hi:[0,1,0]
	v_fma_mix_f32 v49, v12, v45, v49 op_sel:[0,0,0] op_sel_hi:[0,1,0]
	v_fma_mix_f32 v14, v13, v75, v14 op_sel:[0,1,0] op_sel_hi:[0,1,0]
	v_fma_mix_f32 v16, v10, v72, 0 op_sel:[0,0,0] op_sel_hi:[0,1,0]
	v_fma_mix_f32 v17, v11, v72, 0 op_sel:[0,1,0] op_sel_hi:[0,1,0]
	v_add_f32_dpp v20, v14, v14 quad_perm:[1,0,3,2] row_mask:0xf bank_mask:0xf bound_ctrl:1
	v_fma_mix_f32 v49, v13, v45, v49 op_sel:[0,1,0] op_sel_hi:[0,1,0]
	v_fma_mix_f32 v18, v12, v73, 0 op_sel:[0,0,0] op_sel_hi:[0,1,0]
	v_add_f32_dpp v20, v20, v20 quad_perm:[2,3,0,1] row_mask:0xf bank_mask:0xf bound_ctrl:1
	v_fma_mix_f32 v19, v13, v73, 0 op_sel:[0,1,0] op_sel_hi:[0,1,0]
	v_fma_mix_f32 v16, v82, v78, v16 op_sel:[0,0,0] op_sel_hi:[1,1,0]
	v_add_f32_dpp v20, v20, v20 row_half_mirror row_mask:0xf bank_mask:0xf bound_ctrl:1
	v_fma_mix_f32 v17, v82, v78, v17 op_sel:[0,1,0] op_sel_hi:[1,1,0]
	v_fma_mix_f32 v18, v82, v79, v18 op_sel:[0,0,0] op_sel_hi:[1,1,0]
	v_add_f32_dpp v20, v20, v20 row_mirror row_mask:0xf bank_mask:0xf bound_ctrl:1
	v_fma_mix_f32 v19, v82, v79, v19 op_sel:[0,1,0] op_sel_hi:[1,1,0]
	v_fma_mix_f32 v10, v20, v76, v16 op_sel:[0,0,0] op_sel_hi:[0,1,0]
	v_fma_mix_f32 v11, v20, v76, v17 op_sel:[0,1,0] op_sel_hi:[0,1,0]
	v_fma_mix_f32 v12, v20, v77, v18 op_sel:[0,0,0] op_sel_hi:[0,1,0]
	v_fma_mix_f32 v13, v20, v77, v19 op_sel:[0,1,0] op_sel_hi:[0,1,0]
	s_waitcnt lgkmcnt(4)
	ds_read_b64 v[36:37], v6 offset:10264
	ds_read_b128 v[38:41], v6 offset:10512
	ds_read_b128 v[42:45], v6 offset:10768
	ds_read_u16 v46, v7 offset:10256
	v_fma_mix_f32 v14, v10, v86, 0 op_sel:[0,0,0] op_sel_hi:[0,1,0]
	v_fma_mix_f32 v50, v10, v80, 0 op_sel:[0,0,0] op_sel_hi:[0,1,0]
	v_fma_mix_f32 v14, v11, v86, v14 op_sel:[0,1,0] op_sel_hi:[0,1,0]
	v_fma_mix_f32 v50, v11, v80, v50 op_sel:[0,1,0] op_sel_hi:[0,1,0]
	v_fma_mix_f32 v14, v12, v87, v14 op_sel:[0,0,0] op_sel_hi:[0,1,0]
	v_fma_mix_f32 v50, v12, v81, v50 op_sel:[0,0,0] op_sel_hi:[0,1,0]
	v_fma_mix_f32 v14, v13, v87, v14 op_sel:[0,1,0] op_sel_hi:[0,1,0]
	v_fma_mix_f32 v16, v10, v84, 0 op_sel:[0,0,0] op_sel_hi:[0,1,0]
	v_fma_mix_f32 v17, v11, v84, 0 op_sel:[0,1,0] op_sel_hi:[0,1,0]
	v_add_f32_dpp v20, v14, v14 quad_perm:[1,0,3,2] row_mask:0xf bank_mask:0xf bound_ctrl:1
	v_fma_mix_f32 v50, v13, v81, v50 op_sel:[0,1,0] op_sel_hi:[0,1,0]
	v_fma_mix_f32 v18, v12, v85, 0 op_sel:[0,0,0] op_sel_hi:[0,1,0]
	v_add_f32_dpp v20, v20, v20 quad_perm:[2,3,0,1] row_mask:0xf bank_mask:0xf bound_ctrl:1
	v_fma_mix_f32 v19, v13, v85, 0 op_sel:[0,1,0] op_sel_hi:[0,1,0]
	v_fma_mix_f32 v16, v94, v90, v16 op_sel:[0,0,0] op_sel_hi:[1,1,0]
	v_add_f32_dpp v20, v20, v20 row_half_mirror row_mask:0xf bank_mask:0xf bound_ctrl:1
	v_fma_mix_f32 v17, v94, v90, v17 op_sel:[0,1,0] op_sel_hi:[1,1,0]
	v_fma_mix_f32 v18, v94, v91, v18 op_sel:[0,0,0] op_sel_hi:[1,1,0]
	v_add_f32_dpp v20, v20, v20 row_mirror row_mask:0xf bank_mask:0xf bound_ctrl:1
	v_fma_mix_f32 v19, v94, v91, v19 op_sel:[0,1,0] op_sel_hi:[1,1,0]
	v_fma_mix_f32 v10, v20, v88, v16 op_sel:[0,0,0] op_sel_hi:[0,1,0]
	v_fma_mix_f32 v11, v20, v88, v17 op_sel:[0,1,0] op_sel_hi:[0,1,0]
	v_fma_mix_f32 v12, v20, v89, v18 op_sel:[0,0,0] op_sel_hi:[0,1,0]
	v_fma_mix_f32 v13, v20, v89, v19 op_sel:[0,1,0] op_sel_hi:[0,1,0]
	s_waitcnt lgkmcnt(4)
	ds_read_b64 v[72:73], v6 offset:9240
	ds_read_b128 v[74:77], v6 offset:9488
	ds_read_b128 v[78:81], v6 offset:9744
	ds_read_u16 v82, v7 offset:9232
	v_fma_mix_f32 v14, v10, v26, 0 op_sel:[0,0,0] op_sel_hi:[0,1,0]
	v_fma_mix_f32 v51, v10, v92, 0 op_sel:[0,0,0] op_sel_hi:[0,1,0]
	v_fma_mix_f32 v14, v11, v26, v14 op_sel:[0,1,0] op_sel_hi:[0,1,0]
	v_fma_mix_f32 v51, v11, v92, v51 op_sel:[0,1,0] op_sel_hi:[0,1,0]
	v_fma_mix_f32 v14, v12, v27, v14 op_sel:[0,0,0] op_sel_hi:[0,1,0]
	v_fma_mix_f32 v51, v12, v93, v51 op_sel:[0,0,0] op_sel_hi:[0,1,0]
	v_fma_mix_f32 v14, v13, v27, v14 op_sel:[0,1,0] op_sel_hi:[0,1,0]
	v_fma_mix_f32 v16, v10, v24, 0 op_sel:[0,0,0] op_sel_hi:[0,1,0]
	v_fma_mix_f32 v17, v11, v24, 0 op_sel:[0,1,0] op_sel_hi:[0,1,0]
	v_add_f32_dpp v20, v14, v14 quad_perm:[1,0,3,2] row_mask:0xf bank_mask:0xf bound_ctrl:1
	v_fma_mix_f32 v51, v13, v93, v51 op_sel:[0,1,0] op_sel_hi:[0,1,0]
	v_fma_mix_f32 v18, v12, v25, 0 op_sel:[0,0,0] op_sel_hi:[0,1,0]
	v_add_f32_dpp v20, v20, v20 quad_perm:[2,3,0,1] row_mask:0xf bank_mask:0xf bound_ctrl:1
	v_fma_mix_f32 v19, v13, v25, 0 op_sel:[0,1,0] op_sel_hi:[0,1,0]
	v_fma_mix_f32 v16, v34, v30, v16 op_sel:[0,0,0] op_sel_hi:[1,1,0]
	v_add_f32_dpp v20, v20, v20 row_half_mirror row_mask:0xf bank_mask:0xf bound_ctrl:1
	v_fma_mix_f32 v17, v34, v30, v17 op_sel:[0,1,0] op_sel_hi:[1,1,0]
	v_fma_mix_f32 v18, v34, v31, v18 op_sel:[0,0,0] op_sel_hi:[1,1,0]
	v_add_f32_dpp v20, v20, v20 row_mirror row_mask:0xf bank_mask:0xf bound_ctrl:1
	v_fma_mix_f32 v19, v34, v31, v19 op_sel:[0,1,0] op_sel_hi:[1,1,0]
	v_fma_mix_f32 v10, v20, v28, v16 op_sel:[0,0,0] op_sel_hi:[0,1,0]
	v_fma_mix_f32 v11, v20, v28, v17 op_sel:[0,1,0] op_sel_hi:[0,1,0]
	v_fma_mix_f32 v12, v20, v29, v18 op_sel:[0,0,0] op_sel_hi:[0,1,0]
	v_fma_mix_f32 v13, v20, v29, v19 op_sel:[0,1,0] op_sel_hi:[0,1,0]
	s_waitcnt lgkmcnt(4)
	ds_read_b64 v[84:85], v6 offset:8216
	ds_read_b128 v[86:89], v6 offset:8464
	ds_read_b128 v[90:93], v6 offset:8720
	ds_read_u16 v94, v7 offset:8208
	v_fma_mix_f32 v14, v10, v38, 0 op_sel:[0,0,0] op_sel_hi:[0,1,0]
	v_fma_mix_f32 v52, v10, v32, 0 op_sel:[0,0,0] op_sel_hi:[0,1,0]
	v_fma_mix_f32 v14, v11, v38, v14 op_sel:[0,1,0] op_sel_hi:[0,1,0]
	v_fma_mix_f32 v52, v11, v32, v52 op_sel:[0,1,0] op_sel_hi:[0,1,0]
	v_fma_mix_f32 v14, v12, v39, v14 op_sel:[0,0,0] op_sel_hi:[0,1,0]
	v_fma_mix_f32 v52, v12, v33, v52 op_sel:[0,0,0] op_sel_hi:[0,1,0]
	v_fma_mix_f32 v14, v13, v39, v14 op_sel:[0,1,0] op_sel_hi:[0,1,0]
	v_fma_mix_f32 v16, v10, v36, 0 op_sel:[0,0,0] op_sel_hi:[0,1,0]
	v_fma_mix_f32 v17, v11, v36, 0 op_sel:[0,1,0] op_sel_hi:[0,1,0]
	v_add_f32_dpp v20, v14, v14 quad_perm:[1,0,3,2] row_mask:0xf bank_mask:0xf bound_ctrl:1
	v_fma_mix_f32 v52, v13, v33, v52 op_sel:[0,1,0] op_sel_hi:[0,1,0]
	v_fma_mix_f32 v18, v12, v37, 0 op_sel:[0,0,0] op_sel_hi:[0,1,0]
	v_add_f32_dpp v20, v20, v20 quad_perm:[2,3,0,1] row_mask:0xf bank_mask:0xf bound_ctrl:1
	v_fma_mix_f32 v19, v13, v37, 0 op_sel:[0,1,0] op_sel_hi:[0,1,0]
	v_fma_mix_f32 v16, v46, v42, v16 op_sel:[0,0,0] op_sel_hi:[1,1,0]
	v_add_f32_dpp v20, v20, v20 row_half_mirror row_mask:0xf bank_mask:0xf bound_ctrl:1
	v_fma_mix_f32 v17, v46, v42, v17 op_sel:[0,1,0] op_sel_hi:[1,1,0]
	v_fma_mix_f32 v18, v46, v43, v18 op_sel:[0,0,0] op_sel_hi:[1,1,0]
	v_add_f32_dpp v20, v20, v20 row_mirror row_mask:0xf bank_mask:0xf bound_ctrl:1
	v_fma_mix_f32 v19, v46, v43, v19 op_sel:[0,1,0] op_sel_hi:[1,1,0]
	v_fma_mix_f32 v10, v20, v40, v16 op_sel:[0,0,0] op_sel_hi:[0,1,0]
	v_fma_mix_f32 v11, v20, v40, v17 op_sel:[0,1,0] op_sel_hi:[0,1,0]
	v_fma_mix_f32 v12, v20, v41, v18 op_sel:[0,0,0] op_sel_hi:[0,1,0]
	v_fma_mix_f32 v13, v20, v41, v19 op_sel:[0,1,0] op_sel_hi:[0,1,0]
	s_waitcnt lgkmcnt(4)
	ds_read_b64 v[24:25], v6 offset:7192
	ds_read_b128 v[26:29], v6 offset:7440
	ds_read_b128 v[30:33], v6 offset:7696
	ds_read_u16 v34, v7 offset:7184
	v_fma_mix_f32 v14, v10, v74, 0 op_sel:[0,0,0] op_sel_hi:[0,1,0]
	v_fma_mix_f32 v53, v10, v44, 0 op_sel:[0,0,0] op_sel_hi:[0,1,0]
	v_fma_mix_f32 v14, v11, v74, v14 op_sel:[0,1,0] op_sel_hi:[0,1,0]
	v_fma_mix_f32 v53, v11, v44, v53 op_sel:[0,1,0] op_sel_hi:[0,1,0]
	v_fma_mix_f32 v14, v12, v75, v14 op_sel:[0,0,0] op_sel_hi:[0,1,0]
	v_fma_mix_f32 v53, v12, v45, v53 op_sel:[0,0,0] op_sel_hi:[0,1,0]
	v_fma_mix_f32 v14, v13, v75, v14 op_sel:[0,1,0] op_sel_hi:[0,1,0]
	v_fma_mix_f32 v16, v10, v72, 0 op_sel:[0,0,0] op_sel_hi:[0,1,0]
	v_fma_mix_f32 v17, v11, v72, 0 op_sel:[0,1,0] op_sel_hi:[0,1,0]
	v_add_f32_dpp v20, v14, v14 quad_perm:[1,0,3,2] row_mask:0xf bank_mask:0xf bound_ctrl:1
	v_fma_mix_f32 v53, v13, v45, v53 op_sel:[0,1,0] op_sel_hi:[0,1,0]
	v_fma_mix_f32 v18, v12, v73, 0 op_sel:[0,0,0] op_sel_hi:[0,1,0]
	v_add_f32_dpp v20, v20, v20 quad_perm:[2,3,0,1] row_mask:0xf bank_mask:0xf bound_ctrl:1
	v_fma_mix_f32 v19, v13, v73, 0 op_sel:[0,1,0] op_sel_hi:[0,1,0]
	v_fma_mix_f32 v16, v82, v78, v16 op_sel:[0,0,0] op_sel_hi:[1,1,0]
	v_add_f32_dpp v20, v20, v20 row_half_mirror row_mask:0xf bank_mask:0xf bound_ctrl:1
	v_fma_mix_f32 v17, v82, v78, v17 op_sel:[0,1,0] op_sel_hi:[1,1,0]
	v_fma_mix_f32 v18, v82, v79, v18 op_sel:[0,0,0] op_sel_hi:[1,1,0]
	v_add_f32_dpp v20, v20, v20 row_mirror row_mask:0xf bank_mask:0xf bound_ctrl:1
	v_fma_mix_f32 v19, v82, v79, v19 op_sel:[0,1,0] op_sel_hi:[1,1,0]
	v_fma_mix_f32 v10, v20, v76, v16 op_sel:[0,0,0] op_sel_hi:[0,1,0]
	v_fma_mix_f32 v11, v20, v76, v17 op_sel:[0,1,0] op_sel_hi:[0,1,0]
	v_fma_mix_f32 v12, v20, v77, v18 op_sel:[0,0,0] op_sel_hi:[0,1,0]
	v_fma_mix_f32 v13, v20, v77, v19 op_sel:[0,1,0] op_sel_hi:[0,1,0]
	s_waitcnt lgkmcnt(4)
	ds_read_b64 v[36:37], v6 offset:6168
	ds_read_b128 v[38:41], v6 offset:6416
	ds_read_b128 v[42:45], v6 offset:6672
	ds_read_u16 v46, v7 offset:6160
	v_fma_mix_f32 v14, v10, v86, 0 op_sel:[0,0,0] op_sel_hi:[0,1,0]
	v_fma_mix_f32 v54, v10, v80, 0 op_sel:[0,0,0] op_sel_hi:[0,1,0]
	v_fma_mix_f32 v14, v11, v86, v14 op_sel:[0,1,0] op_sel_hi:[0,1,0]
	v_fma_mix_f32 v54, v11, v80, v54 op_sel:[0,1,0] op_sel_hi:[0,1,0]
	v_fma_mix_f32 v14, v12, v87, v14 op_sel:[0,0,0] op_sel_hi:[0,1,0]
	v_fma_mix_f32 v54, v12, v81, v54 op_sel:[0,0,0] op_sel_hi:[0,1,0]
	v_fma_mix_f32 v14, v13, v87, v14 op_sel:[0,1,0] op_sel_hi:[0,1,0]
	v_fma_mix_f32 v16, v10, v84, 0 op_sel:[0,0,0] op_sel_hi:[0,1,0]
	v_fma_mix_f32 v17, v11, v84, 0 op_sel:[0,1,0] op_sel_hi:[0,1,0]
	v_add_f32_dpp v20, v14, v14 quad_perm:[1,0,3,2] row_mask:0xf bank_mask:0xf bound_ctrl:1
	v_fma_mix_f32 v54, v13, v81, v54 op_sel:[0,1,0] op_sel_hi:[0,1,0]
	v_fma_mix_f32 v18, v12, v85, 0 op_sel:[0,0,0] op_sel_hi:[0,1,0]
	v_add_f32_dpp v20, v20, v20 quad_perm:[2,3,0,1] row_mask:0xf bank_mask:0xf bound_ctrl:1
	v_fma_mix_f32 v19, v13, v85, 0 op_sel:[0,1,0] op_sel_hi:[0,1,0]
	v_fma_mix_f32 v16, v94, v90, v16 op_sel:[0,0,0] op_sel_hi:[1,1,0]
	v_add_f32_dpp v20, v20, v20 row_half_mirror row_mask:0xf bank_mask:0xf bound_ctrl:1
	v_fma_mix_f32 v17, v94, v90, v17 op_sel:[0,1,0] op_sel_hi:[1,1,0]
	v_fma_mix_f32 v18, v94, v91, v18 op_sel:[0,0,0] op_sel_hi:[1,1,0]
	v_add_f32_dpp v20, v20, v20 row_mirror row_mask:0xf bank_mask:0xf bound_ctrl:1
	v_fma_mix_f32 v19, v94, v91, v19 op_sel:[0,1,0] op_sel_hi:[1,1,0]
	v_fma_mix_f32 v10, v20, v88, v16 op_sel:[0,0,0] op_sel_hi:[0,1,0]
	v_fma_mix_f32 v11, v20, v88, v17 op_sel:[0,1,0] op_sel_hi:[0,1,0]
	v_fma_mix_f32 v12, v20, v89, v18 op_sel:[0,0,0] op_sel_hi:[0,1,0]
	v_fma_mix_f32 v13, v20, v89, v19 op_sel:[0,1,0] op_sel_hi:[0,1,0]
	s_waitcnt lgkmcnt(4)
	ds_read_b64 v[72:73], v6 offset:5144
	ds_read_b128 v[74:77], v6 offset:5392
	ds_read_b128 v[78:81], v6 offset:5648
	ds_read_u16 v82, v7 offset:5136
	v_fma_mix_f32 v14, v10, v26, 0 op_sel:[0,0,0] op_sel_hi:[0,1,0]
	v_fma_mix_f32 v55, v10, v92, 0 op_sel:[0,0,0] op_sel_hi:[0,1,0]
	v_fma_mix_f32 v14, v11, v26, v14 op_sel:[0,1,0] op_sel_hi:[0,1,0]
	v_fma_mix_f32 v55, v11, v92, v55 op_sel:[0,1,0] op_sel_hi:[0,1,0]
	v_fma_mix_f32 v14, v12, v27, v14 op_sel:[0,0,0] op_sel_hi:[0,1,0]
	v_fma_mix_f32 v55, v12, v93, v55 op_sel:[0,0,0] op_sel_hi:[0,1,0]
	v_fma_mix_f32 v14, v13, v27, v14 op_sel:[0,1,0] op_sel_hi:[0,1,0]
	v_fma_mix_f32 v16, v10, v24, 0 op_sel:[0,0,0] op_sel_hi:[0,1,0]
	v_fma_mix_f32 v17, v11, v24, 0 op_sel:[0,1,0] op_sel_hi:[0,1,0]
	v_add_f32_dpp v20, v14, v14 quad_perm:[1,0,3,2] row_mask:0xf bank_mask:0xf bound_ctrl:1
	v_fma_mix_f32 v55, v13, v93, v55 op_sel:[0,1,0] op_sel_hi:[0,1,0]
	v_fma_mix_f32 v18, v12, v25, 0 op_sel:[0,0,0] op_sel_hi:[0,1,0]
	v_add_f32_dpp v20, v20, v20 quad_perm:[2,3,0,1] row_mask:0xf bank_mask:0xf bound_ctrl:1
	v_fma_mix_f32 v19, v13, v25, 0 op_sel:[0,1,0] op_sel_hi:[0,1,0]
	v_fma_mix_f32 v16, v34, v30, v16 op_sel:[0,0,0] op_sel_hi:[1,1,0]
	v_add_f32_dpp v20, v20, v20 row_half_mirror row_mask:0xf bank_mask:0xf bound_ctrl:1
	v_fma_mix_f32 v17, v34, v30, v17 op_sel:[0,1,0] op_sel_hi:[1,1,0]
	v_fma_mix_f32 v18, v34, v31, v18 op_sel:[0,0,0] op_sel_hi:[1,1,0]
	v_add_f32_dpp v20, v20, v20 row_mirror row_mask:0xf bank_mask:0xf bound_ctrl:1
	v_fma_mix_f32 v19, v34, v31, v19 op_sel:[0,1,0] op_sel_hi:[1,1,0]
	v_fma_mix_f32 v10, v20, v28, v16 op_sel:[0,0,0] op_sel_hi:[0,1,0]
	v_fma_mix_f32 v11, v20, v28, v17 op_sel:[0,1,0] op_sel_hi:[0,1,0]
	v_fma_mix_f32 v12, v20, v29, v18 op_sel:[0,0,0] op_sel_hi:[0,1,0]
	v_fma_mix_f32 v13, v20, v29, v19 op_sel:[0,1,0] op_sel_hi:[0,1,0]
	s_waitcnt lgkmcnt(4)
	ds_read_b64 v[84:85], v6 offset:4120
	ds_read_b128 v[86:89], v6 offset:4368
	ds_read_b128 v[90:93], v6 offset:4624
	ds_read_u16 v94, v7 offset:4112
	v_fma_mix_f32 v14, v10, v38, 0 op_sel:[0,0,0] op_sel_hi:[0,1,0]
	v_fma_mix_f32 v56, v10, v32, 0 op_sel:[0,0,0] op_sel_hi:[0,1,0]
	v_fma_mix_f32 v14, v11, v38, v14 op_sel:[0,1,0] op_sel_hi:[0,1,0]
	v_fma_mix_f32 v56, v11, v32, v56 op_sel:[0,1,0] op_sel_hi:[0,1,0]
	v_fma_mix_f32 v14, v12, v39, v14 op_sel:[0,0,0] op_sel_hi:[0,1,0]
	v_fma_mix_f32 v56, v12, v33, v56 op_sel:[0,0,0] op_sel_hi:[0,1,0]
	v_fma_mix_f32 v14, v13, v39, v14 op_sel:[0,1,0] op_sel_hi:[0,1,0]
	v_fma_mix_f32 v16, v10, v36, 0 op_sel:[0,0,0] op_sel_hi:[0,1,0]
	v_fma_mix_f32 v17, v11, v36, 0 op_sel:[0,1,0] op_sel_hi:[0,1,0]
	v_add_f32_dpp v20, v14, v14 quad_perm:[1,0,3,2] row_mask:0xf bank_mask:0xf bound_ctrl:1
	v_fma_mix_f32 v56, v13, v33, v56 op_sel:[0,1,0] op_sel_hi:[0,1,0]
	v_fma_mix_f32 v18, v12, v37, 0 op_sel:[0,0,0] op_sel_hi:[0,1,0]
	v_add_f32_dpp v20, v20, v20 quad_perm:[2,3,0,1] row_mask:0xf bank_mask:0xf bound_ctrl:1
	v_fma_mix_f32 v19, v13, v37, 0 op_sel:[0,1,0] op_sel_hi:[0,1,0]
	v_fma_mix_f32 v16, v46, v42, v16 op_sel:[0,0,0] op_sel_hi:[1,1,0]
	v_add_f32_dpp v20, v20, v20 row_half_mirror row_mask:0xf bank_mask:0xf bound_ctrl:1
	v_fma_mix_f32 v17, v46, v42, v17 op_sel:[0,1,0] op_sel_hi:[1,1,0]
	v_fma_mix_f32 v18, v46, v43, v18 op_sel:[0,0,0] op_sel_hi:[1,1,0]
	v_add_f32_dpp v20, v20, v20 row_mirror row_mask:0xf bank_mask:0xf bound_ctrl:1
	v_fma_mix_f32 v19, v46, v43, v19 op_sel:[0,1,0] op_sel_hi:[1,1,0]
	v_fma_mix_f32 v10, v20, v40, v16 op_sel:[0,0,0] op_sel_hi:[0,1,0]
	v_fma_mix_f32 v11, v20, v40, v17 op_sel:[0,1,0] op_sel_hi:[0,1,0]
	v_fma_mix_f32 v12, v20, v41, v18 op_sel:[0,0,0] op_sel_hi:[0,1,0]
	v_fma_mix_f32 v13, v20, v41, v19 op_sel:[0,1,0] op_sel_hi:[0,1,0]
	s_waitcnt lgkmcnt(4)
	ds_read_b64 v[24:25], v6 offset:3096
	ds_read_b128 v[26:29], v6 offset:3344
	ds_read_b128 v[30:33], v6 offset:3600
	ds_read_u16 v34, v7 offset:3088
	v_fma_mix_f32 v14, v10, v74, 0 op_sel:[0,0,0] op_sel_hi:[0,1,0]
	v_fma_mix_f32 v57, v10, v44, 0 op_sel:[0,0,0] op_sel_hi:[0,1,0]
	v_fma_mix_f32 v14, v11, v74, v14 op_sel:[0,1,0] op_sel_hi:[0,1,0]
	v_fma_mix_f32 v57, v11, v44, v57 op_sel:[0,1,0] op_sel_hi:[0,1,0]
	v_fma_mix_f32 v14, v12, v75, v14 op_sel:[0,0,0] op_sel_hi:[0,1,0]
	v_fma_mix_f32 v57, v12, v45, v57 op_sel:[0,0,0] op_sel_hi:[0,1,0]
	v_fma_mix_f32 v14, v13, v75, v14 op_sel:[0,1,0] op_sel_hi:[0,1,0]
	v_fma_mix_f32 v16, v10, v72, 0 op_sel:[0,0,0] op_sel_hi:[0,1,0]
	v_fma_mix_f32 v17, v11, v72, 0 op_sel:[0,1,0] op_sel_hi:[0,1,0]
	v_add_f32_dpp v20, v14, v14 quad_perm:[1,0,3,2] row_mask:0xf bank_mask:0xf bound_ctrl:1
	v_fma_mix_f32 v57, v13, v45, v57 op_sel:[0,1,0] op_sel_hi:[0,1,0]
	v_fma_mix_f32 v18, v12, v73, 0 op_sel:[0,0,0] op_sel_hi:[0,1,0]
	v_add_f32_dpp v20, v20, v20 quad_perm:[2,3,0,1] row_mask:0xf bank_mask:0xf bound_ctrl:1
	v_fma_mix_f32 v19, v13, v73, 0 op_sel:[0,1,0] op_sel_hi:[0,1,0]
	v_fma_mix_f32 v16, v82, v78, v16 op_sel:[0,0,0] op_sel_hi:[1,1,0]
	v_add_f32_dpp v20, v20, v20 row_half_mirror row_mask:0xf bank_mask:0xf bound_ctrl:1
	v_fma_mix_f32 v17, v82, v78, v17 op_sel:[0,1,0] op_sel_hi:[1,1,0]
	v_fma_mix_f32 v18, v82, v79, v18 op_sel:[0,0,0] op_sel_hi:[1,1,0]
	v_add_f32_dpp v20, v20, v20 row_mirror row_mask:0xf bank_mask:0xf bound_ctrl:1
	v_fma_mix_f32 v19, v82, v79, v19 op_sel:[0,1,0] op_sel_hi:[1,1,0]
	v_fma_mix_f32 v10, v20, v76, v16 op_sel:[0,0,0] op_sel_hi:[0,1,0]
	v_fma_mix_f32 v11, v20, v76, v17 op_sel:[0,1,0] op_sel_hi:[0,1,0]
	v_fma_mix_f32 v12, v20, v77, v18 op_sel:[0,0,0] op_sel_hi:[0,1,0]
	v_fma_mix_f32 v13, v20, v77, v19 op_sel:[0,1,0] op_sel_hi:[0,1,0]
	s_waitcnt lgkmcnt(4)
	ds_read_b64 v[36:37], v6 offset:2072
	ds_read_b128 v[38:41], v6 offset:2320
	ds_read_b128 v[42:45], v6 offset:2576
	ds_read_u16 v46, v7 offset:2064
	v_fma_mix_f32 v14, v10, v86, 0 op_sel:[0,0,0] op_sel_hi:[0,1,0]
	v_fma_mix_f32 v58, v10, v80, 0 op_sel:[0,0,0] op_sel_hi:[0,1,0]
	v_fma_mix_f32 v14, v11, v86, v14 op_sel:[0,1,0] op_sel_hi:[0,1,0]
	v_fma_mix_f32 v58, v11, v80, v58 op_sel:[0,1,0] op_sel_hi:[0,1,0]
	v_fma_mix_f32 v14, v12, v87, v14 op_sel:[0,0,0] op_sel_hi:[0,1,0]
	v_fma_mix_f32 v58, v12, v81, v58 op_sel:[0,0,0] op_sel_hi:[0,1,0]
	v_fma_mix_f32 v14, v13, v87, v14 op_sel:[0,1,0] op_sel_hi:[0,1,0]
	v_fma_mix_f32 v16, v10, v84, 0 op_sel:[0,0,0] op_sel_hi:[0,1,0]
	v_fma_mix_f32 v17, v11, v84, 0 op_sel:[0,1,0] op_sel_hi:[0,1,0]
	v_add_f32_dpp v20, v14, v14 quad_perm:[1,0,3,2] row_mask:0xf bank_mask:0xf bound_ctrl:1
	v_fma_mix_f32 v58, v13, v81, v58 op_sel:[0,1,0] op_sel_hi:[0,1,0]
	v_fma_mix_f32 v18, v12, v85, 0 op_sel:[0,0,0] op_sel_hi:[0,1,0]
	v_add_f32_dpp v20, v20, v20 quad_perm:[2,3,0,1] row_mask:0xf bank_mask:0xf bound_ctrl:1
	v_fma_mix_f32 v19, v13, v85, 0 op_sel:[0,1,0] op_sel_hi:[0,1,0]
	v_fma_mix_f32 v16, v94, v90, v16 op_sel:[0,0,0] op_sel_hi:[1,1,0]
	v_add_f32_dpp v20, v20, v20 row_half_mirror row_mask:0xf bank_mask:0xf bound_ctrl:1
	v_fma_mix_f32 v17, v94, v90, v17 op_sel:[0,1,0] op_sel_hi:[1,1,0]
	v_fma_mix_f32 v18, v94, v91, v18 op_sel:[0,0,0] op_sel_hi:[1,1,0]
	v_add_f32_dpp v20, v20, v20 row_mirror row_mask:0xf bank_mask:0xf bound_ctrl:1
	v_fma_mix_f32 v19, v94, v91, v19 op_sel:[0,1,0] op_sel_hi:[1,1,0]
	v_fma_mix_f32 v10, v20, v88, v16 op_sel:[0,0,0] op_sel_hi:[0,1,0]
	v_fma_mix_f32 v11, v20, v88, v17 op_sel:[0,1,0] op_sel_hi:[0,1,0]
	v_fma_mix_f32 v12, v20, v89, v18 op_sel:[0,0,0] op_sel_hi:[0,1,0]
	v_fma_mix_f32 v13, v20, v89, v19 op_sel:[0,1,0] op_sel_hi:[0,1,0]
	s_waitcnt lgkmcnt(4)
	ds_read_b64 v[72:73], v6 offset:1048
	ds_read_b128 v[74:77], v6 offset:1296
	ds_read_b128 v[78:81], v6 offset:1552
	ds_read_u16 v82, v7 offset:1040
	v_fma_mix_f32 v14, v10, v26, 0 op_sel:[0,0,0] op_sel_hi:[0,1,0]
	v_fma_mix_f32 v59, v10, v92, 0 op_sel:[0,0,0] op_sel_hi:[0,1,0]
	v_fma_mix_f32 v14, v11, v26, v14 op_sel:[0,1,0] op_sel_hi:[0,1,0]
	v_fma_mix_f32 v59, v11, v92, v59 op_sel:[0,1,0] op_sel_hi:[0,1,0]
	v_fma_mix_f32 v14, v12, v27, v14 op_sel:[0,0,0] op_sel_hi:[0,1,0]
	v_fma_mix_f32 v59, v12, v93, v59 op_sel:[0,0,0] op_sel_hi:[0,1,0]
	v_fma_mix_f32 v14, v13, v27, v14 op_sel:[0,1,0] op_sel_hi:[0,1,0]
	v_fma_mix_f32 v16, v10, v24, 0 op_sel:[0,0,0] op_sel_hi:[0,1,0]
	v_fma_mix_f32 v17, v11, v24, 0 op_sel:[0,1,0] op_sel_hi:[0,1,0]
	v_add_f32_dpp v20, v14, v14 quad_perm:[1,0,3,2] row_mask:0xf bank_mask:0xf bound_ctrl:1
	v_fma_mix_f32 v59, v13, v93, v59 op_sel:[0,1,0] op_sel_hi:[0,1,0]
	v_fma_mix_f32 v18, v12, v25, 0 op_sel:[0,0,0] op_sel_hi:[0,1,0]
	v_add_f32_dpp v20, v20, v20 quad_perm:[2,3,0,1] row_mask:0xf bank_mask:0xf bound_ctrl:1
	v_fma_mix_f32 v19, v13, v25, 0 op_sel:[0,1,0] op_sel_hi:[0,1,0]
	v_fma_mix_f32 v16, v34, v30, v16 op_sel:[0,0,0] op_sel_hi:[1,1,0]
	v_add_f32_dpp v20, v20, v20 row_half_mirror row_mask:0xf bank_mask:0xf bound_ctrl:1
	v_fma_mix_f32 v17, v34, v30, v17 op_sel:[0,1,0] op_sel_hi:[1,1,0]
	v_fma_mix_f32 v18, v34, v31, v18 op_sel:[0,0,0] op_sel_hi:[1,1,0]
	v_add_f32_dpp v20, v20, v20 row_mirror row_mask:0xf bank_mask:0xf bound_ctrl:1
	v_fma_mix_f32 v19, v34, v31, v19 op_sel:[0,1,0] op_sel_hi:[1,1,0]
	v_fma_mix_f32 v10, v20, v28, v16 op_sel:[0,0,0] op_sel_hi:[0,1,0]
	v_fma_mix_f32 v11, v20, v28, v17 op_sel:[0,1,0] op_sel_hi:[0,1,0]
	v_fma_mix_f32 v12, v20, v29, v18 op_sel:[0,0,0] op_sel_hi:[0,1,0]
	v_fma_mix_f32 v13, v20, v29, v19 op_sel:[0,1,0] op_sel_hi:[0,1,0]
	s_waitcnt lgkmcnt(4)
	ds_read_b128 v[100:103], v9
	ds_read_b64 v[84:85], v6 offset:24
	ds_read_b128 v[86:89], v6 offset:272
	ds_read_b128 v[90:93], v6 offset:528
	ds_read_u16 v94, v7 offset:16
	v_fma_mix_f32 v14, v10, v38, 0 op_sel:[0,0,0] op_sel_hi:[0,1,0]
	v_fma_mix_f32 v60, v10, v32, 0 op_sel:[0,0,0] op_sel_hi:[0,1,0]
	v_fma_mix_f32 v14, v11, v38, v14 op_sel:[0,1,0] op_sel_hi:[0,1,0]
	v_fma_mix_f32 v60, v11, v32, v60 op_sel:[0,1,0] op_sel_hi:[0,1,0]
	v_fma_mix_f32 v14, v12, v39, v14 op_sel:[0,0,0] op_sel_hi:[0,1,0]
	v_fma_mix_f32 v60, v12, v33, v60 op_sel:[0,0,0] op_sel_hi:[0,1,0]
	v_fma_mix_f32 v14, v13, v39, v14 op_sel:[0,1,0] op_sel_hi:[0,1,0]
	v_fma_mix_f32 v16, v10, v36, 0 op_sel:[0,0,0] op_sel_hi:[0,1,0]
	v_fma_mix_f32 v17, v11, v36, 0 op_sel:[0,1,0] op_sel_hi:[0,1,0]
	v_add_f32_dpp v20, v14, v14 quad_perm:[1,0,3,2] row_mask:0xf bank_mask:0xf bound_ctrl:1
	v_fma_mix_f32 v60, v13, v33, v60 op_sel:[0,1,0] op_sel_hi:[0,1,0]
	v_fma_mix_f32 v18, v12, v37, 0 op_sel:[0,0,0] op_sel_hi:[0,1,0]
	v_add_f32_dpp v20, v20, v20 quad_perm:[2,3,0,1] row_mask:0xf bank_mask:0xf bound_ctrl:1
	v_fma_mix_f32 v19, v13, v37, 0 op_sel:[0,1,0] op_sel_hi:[0,1,0]
	v_fma_mix_f32 v16, v46, v42, v16 op_sel:[0,0,0] op_sel_hi:[1,1,0]
	v_add_f32_dpp v20, v20, v20 row_half_mirror row_mask:0xf bank_mask:0xf bound_ctrl:1
	v_fma_mix_f32 v17, v46, v42, v17 op_sel:[0,1,0] op_sel_hi:[1,1,0]
	v_fma_mix_f32 v18, v46, v43, v18 op_sel:[0,0,0] op_sel_hi:[1,1,0]
	v_add_f32_dpp v20, v20, v20 row_mirror row_mask:0xf bank_mask:0xf bound_ctrl:1
	v_fma_mix_f32 v19, v46, v43, v19 op_sel:[0,1,0] op_sel_hi:[1,1,0]
	v_fma_mix_f32 v10, v20, v40, v16 op_sel:[0,0,0] op_sel_hi:[0,1,0]
	v_fma_mix_f32 v11, v20, v40, v17 op_sel:[0,1,0] op_sel_hi:[0,1,0]
	v_fma_mix_f32 v12, v20, v41, v18 op_sel:[0,0,0] op_sel_hi:[0,1,0]
	v_fma_mix_f32 v13, v20, v41, v19 op_sel:[0,1,0] op_sel_hi:[0,1,0]
	s_waitcnt lgkmcnt(4)
	v_add_u32_e32 v6, 0xffffc000, v6
	v_add_u32_e32 v7, 0xffffc000, v7
	v_and_b32_e32 v6, 0x1ffff, v6
	v_and_b32_e32 v7, 0x1ffff, v7
	ds_read_b64 v[24:25], v6 offset:15384
	ds_read_b128 v[26:29], v6 offset:15632
	ds_read_b128 v[30:33], v6 offset:15888
	ds_read_u16 v34, v7 offset:15376
	v_fma_mix_f32 v14, v10, v74, 0 op_sel:[0,0,0] op_sel_hi:[0,1,0]
	v_fma_mix_f32 v61, v10, v44, 0 op_sel:[0,0,0] op_sel_hi:[0,1,0]
	v_fma_mix_f32 v14, v11, v74, v14 op_sel:[0,1,0] op_sel_hi:[0,1,0]
	v_fma_mix_f32 v61, v11, v44, v61 op_sel:[0,1,0] op_sel_hi:[0,1,0]
	v_fma_mix_f32 v14, v12, v75, v14 op_sel:[0,0,0] op_sel_hi:[0,1,0]
	v_fma_mix_f32 v61, v12, v45, v61 op_sel:[0,0,0] op_sel_hi:[0,1,0]
	v_fma_mix_f32 v14, v13, v75, v14 op_sel:[0,1,0] op_sel_hi:[0,1,0]
	v_fma_mix_f32 v16, v10, v72, 0 op_sel:[0,0,0] op_sel_hi:[0,1,0]
	v_fma_mix_f32 v17, v11, v72, 0 op_sel:[0,1,0] op_sel_hi:[0,1,0]
	v_add_f32_dpp v20, v14, v14 quad_perm:[1,0,3,2] row_mask:0xf bank_mask:0xf bound_ctrl:1
	v_fma_mix_f32 v61, v13, v45, v61 op_sel:[0,1,0] op_sel_hi:[0,1,0]
	v_fma_mix_f32 v18, v12, v73, 0 op_sel:[0,0,0] op_sel_hi:[0,1,0]
	v_add_f32_dpp v20, v20, v20 quad_perm:[2,3,0,1] row_mask:0xf bank_mask:0xf bound_ctrl:1
	v_fma_mix_f32 v19, v13, v73, 0 op_sel:[0,1,0] op_sel_hi:[0,1,0]
	v_fma_mix_f32 v16, v82, v78, v16 op_sel:[0,0,0] op_sel_hi:[1,1,0]
	v_add_f32_dpp v20, v20, v20 row_half_mirror row_mask:0xf bank_mask:0xf bound_ctrl:1
	v_fma_mix_f32 v17, v82, v78, v17 op_sel:[0,1,0] op_sel_hi:[1,1,0]
	v_fma_mix_f32 v18, v82, v79, v18 op_sel:[0,0,0] op_sel_hi:[1,1,0]
	v_add_f32_dpp v20, v20, v20 row_mirror row_mask:0xf bank_mask:0xf bound_ctrl:1
	v_fma_mix_f32 v19, v82, v79, v19 op_sel:[0,1,0] op_sel_hi:[1,1,0]
	v_fma_mix_f32 v10, v20, v76, v16 op_sel:[0,0,0] op_sel_hi:[0,1,0]
	v_fma_mix_f32 v11, v20, v76, v17 op_sel:[0,1,0] op_sel_hi:[0,1,0]
	v_fma_mix_f32 v12, v20, v77, v18 op_sel:[0,0,0] op_sel_hi:[0,1,0]
	v_fma_mix_f32 v13, v20, v77, v19 op_sel:[0,1,0] op_sel_hi:[0,1,0]
	s_waitcnt lgkmcnt(4)
	ds_read_b64 v[36:37], v6 offset:14360
	ds_read_b128 v[38:41], v6 offset:14608
	ds_read_b128 v[42:45], v6 offset:14864
	ds_read_u16 v46, v7 offset:14352
	v_fma_mix_f32 v14, v10, v86, 0 op_sel:[0,0,0] op_sel_hi:[0,1,0]
	v_fma_mix_f32 v62, v10, v80, 0 op_sel:[0,0,0] op_sel_hi:[0,1,0]
	v_fma_mix_f32 v14, v11, v86, v14 op_sel:[0,1,0] op_sel_hi:[0,1,0]
	v_fma_mix_f32 v62, v11, v80, v62 op_sel:[0,1,0] op_sel_hi:[0,1,0]
	v_fma_mix_f32 v14, v12, v87, v14 op_sel:[0,0,0] op_sel_hi:[0,1,0]
	v_fma_mix_f32 v62, v12, v81, v62 op_sel:[0,0,0] op_sel_hi:[0,1,0]
	v_fma_mix_f32 v14, v13, v87, v14 op_sel:[0,1,0] op_sel_hi:[0,1,0]
	v_fma_mix_f32 v16, v10, v84, 0 op_sel:[0,0,0] op_sel_hi:[0,1,0]
	v_fma_mix_f32 v17, v11, v84, 0 op_sel:[0,1,0] op_sel_hi:[0,1,0]
	v_add_f32_dpp v20, v14, v14 quad_perm:[1,0,3,2] row_mask:0xf bank_mask:0xf bound_ctrl:1
	v_fma_mix_f32 v62, v13, v81, v62 op_sel:[0,1,0] op_sel_hi:[0,1,0]
	v_fma_mix_f32 v18, v12, v85, 0 op_sel:[0,0,0] op_sel_hi:[0,1,0]
	v_add_f32_dpp v20, v20, v20 quad_perm:[2,3,0,1] row_mask:0xf bank_mask:0xf bound_ctrl:1
	v_fma_mix_f32 v19, v13, v85, 0 op_sel:[0,1,0] op_sel_hi:[0,1,0]
	v_fma_mix_f32 v16, v94, v90, v16 op_sel:[0,0,0] op_sel_hi:[1,1,0]
	v_add_f32_dpp v20, v20, v20 row_half_mirror row_mask:0xf bank_mask:0xf bound_ctrl:1
	v_fma_mix_f32 v17, v94, v90, v17 op_sel:[0,1,0] op_sel_hi:[1,1,0]
	v_fma_mix_f32 v18, v94, v91, v18 op_sel:[0,0,0] op_sel_hi:[1,1,0]
	v_add_f32_dpp v20, v20, v20 row_mirror row_mask:0xf bank_mask:0xf bound_ctrl:1
	v_fma_mix_f32 v19, v94, v91, v19 op_sel:[0,1,0] op_sel_hi:[1,1,0]
	v_fma_mix_f32 v10, v20, v88, v16 op_sel:[0,0,0] op_sel_hi:[0,1,0]
	v_fma_mix_f32 v11, v20, v88, v17 op_sel:[0,1,0] op_sel_hi:[0,1,0]
	v_fma_mix_f32 v12, v20, v89, v18 op_sel:[0,0,0] op_sel_hi:[0,1,0]
	v_fma_mix_f32 v13, v20, v89, v19 op_sel:[0,1,0] op_sel_hi:[0,1,0]
	s_waitcnt lgkmcnt(4)
	s_add_u32 s43, s43, 1

; DEVINL u16 f2bf(float a) { return (u16)(pk2(a, 0.f) & 0xffffu); }
; #define RW_STEP2(B) RW_STEP(B, WvA, XA, KrA, vhA, WvB, XB, KrB, vhB); RW_STEP((B) + 1, WvB, XB, KrB, vhB, WvA, XA, KrA, vhA)
; #define RW_STEP4(B) RW_STEP2(B); RW_STEP2((B) + 2)
; template <int DIR>
; DEVINL void rwkv_scan_dir(const Params& p, int task, int lane, int wave) {
;     ...
;   for (int st = 0; st < 4096; st += 32) {
;     RW_STEP(0, WvA, XA, KrA, vhA, WvB, XB, KrB, vhB);
;     if (st > 0) { const int q0 = st - 16 + seg; yo[(long)(DIR ? (4095 - q0) : q0) * 1024] = f2bf(ykeep); }
;     RW_STEP(1, WvB, XB, KrB, vhB, WvA, XA, KrA, vhA);
;     RW_STEP2(2); RW_STEP4(4); RW_STEP4(8); RW_STEP4(12);
;     RW_STEP(16, WvA, XA, KrA, vhA, WvB, XB, KrB, vhB);
;     { const int q0 = st + seg; yo[(long)(DIR ? (4095 - q0) : q0) * 1024] = f2bf(ykeep); }
.Lrw_ready_d1:
	s_add_u32 m0, s41, 16
	s_nop 0
	global_load_lds_dwordx4 v5, s[10:11] offset:0
	global_load_lds_dwordx4 v5, s[10:11] offset:1024
	global_load_lds_dwordx4 v5, s[10:11] offset:2048
	global_load_lds_dwordx4 v5, s[10:11] offset:3072
	s_sub_u32 s10, s10, 0x4000
	s_subb_u32 s11, s11, 0
	s_sub_u32 s41, s41, 0x4000
	s_and_b32 s41, s41, 0x1ffff
	ds_read_b64 v[72:73], v6 offset:13336
	ds_read_b128 v[74:77], v6 offset:13584
	ds_read_b128 v[78:81], v6 offset:13840
	ds_read_u16 v82, v7 offset:13328
	v_fma_mix_f32 v14, v10, v26, 0 op_sel:[0,0,0] op_sel_hi:[0,1,0]
	v_fma_mix_f32 v63, v10, v92, 0 op_sel:[0,0,0] op_sel_hi:[0,1,0]
	v_fma_mix_f32 v14, v11, v26, v14 op_sel:[0,1,0] op_sel_hi:[0,1,0]
	v_fma_mix_f32 v63, v11, v92, v63 op_sel:[0,1,0] op_sel_hi:[0,1,0]
	v_fma_mix_f32 v14, v12, v27, v14 op_sel:[0,0,0] op_sel_hi:[0,1,0]
	v_fma_mix_f32 v63, v12, v93, v63 op_sel:[0,0,0] op_sel_hi:[0,1,0]
	v_fma_mix_f32 v14, v13, v27, v14 op_sel:[0,1,0] op_sel_hi:[0,1,0]
	v_fma_mix_f32 v16, v10, v24, 0 op_sel:[0,0,0] op_sel_hi:[0,1,0]
	v_fma_mix_f32 v17, v11, v24, 0 op_sel:[0,1,0] op_sel_hi:[0,1,0]
	v_add_f32_dpp v20, v14, v14 quad_perm:[1,0,3,2] row_mask:0xf bank_mask:0xf bound_ctrl:1
	v_fma_mix_f32 v63, v13, v93, v63 op_sel:[0,1,0] op_sel_hi:[0,1,0]
	v_fma_mix_f32 v18, v12, v25, 0 op_sel:[0,0,0] op_sel_hi:[0,1,0]
	v_add_f32_dpp v20, v20, v20 quad_perm:[2,3,0,1] row_mask:0xf bank_mask:0xf bound_ctrl:1
	v_fma_mix_f32 v19, v13, v25, 0 op_sel:[0,1,0] op_sel_hi:[0,1,0]
	v_fma_mix_f32 v16, v34, v30, v16 op_sel:[0,0,0] op_sel_hi:[1,1,0]
	v_add_f32_dpp v20, v20, v20 row_half_mirror row_mask:0xf bank_mask:0xf bound_ctrl:1
	v_fma_mix_f32 v17, v34, v30, v17 op_sel:[0,1,0] op_sel_hi:[1,1,0]
	v_fma_mix_f32 v18, v34, v31, v18 op_sel:[0,0,0] op_sel_hi:[1,1,0]
	v_add_f32_dpp v20, v20, v20 row_mirror row_mask:0xf bank_mask:0xf bound_ctrl:1
	v_fma_mix_f32 v19, v34, v31, v19 op_sel:[0,1,0] op_sel_hi:[1,1,0]
	v_fma_mix_f32 v10, v20, v28, v16 op_sel:[0,0,0] op_sel_hi:[0,1,0]
	v_fma_mix_f32 v11, v20, v28, v17 op_sel:[0,1,0] op_sel_hi:[0,1,0]
	v_fma_mix_f32 v12, v20, v29, v18 op_sel:[0,0,0] op_sel_hi:[0,1,0]
	v_fma_mix_f32 v13, v20, v29, v19 op_sel:[0,1,0] op_sel_hi:[0,1,0]
	s_waitcnt lgkmcnt(4)
	v_add_f32_dpp v48, v48, v48 row_ror:8 row_mask:0xf bank_mask:0x3
	v_add_f32_dpp v49, v49, v49 row_ror:8 row_mask:0xf bank_mask:0x3
	v_add_f32_dpp v50, v50, v50 row_ror:8 row_mask:0xf bank_mask:0x3
	v_add_f32_dpp v51, v51, v51 row_ror:8 row_mask:0xf bank_mask:0x3
	v_add_f32_dpp v52, v52, v52 row_ror:8 row_mask:0xf bank_mask:0x3
	v_add_f32_dpp v53, v53, v53 row_ror:8 row_mask:0xf bank_mask:0x3
	v_add_f32_dpp v54, v54, v54 row_ror:8 row_mask:0xf bank_mask:0x3
	v_add_f32_dpp v55, v55, v55 row_ror:8 row_mask:0xf bank_mask:0x3
	v_add_f32_dpp v48, v56, v56 row_ror:8 row_mask:0xf bank_mask:0xc
	v_add_f32_dpp v49, v57, v57 row_ror:8 row_mask:0xf bank_mask:0xc
	v_add_f32_dpp v50, v58, v58 row_ror:8 row_mask:0xf bank_mask:0xc
	v_add_f32_dpp v51, v59, v59 row_ror:8 row_mask:0xf bank_mask:0xc
	v_add_f32_dpp v52, v60, v60 row_ror:8 row_mask:0xf bank_mask:0xc
	v_add_f32_dpp v53, v61, v61 row_ror:8 row_mask:0xf bank_mask:0xc
	v_add_f32_dpp v54, v62, v62 row_ror:8 row_mask:0xf bank_mask:0xc
	v_add_f32_dpp v55, v63, v63 row_ror:8 row_mask:0xf bank_mask:0xc
	v_add_f32_dpp v48, v48, v48 row_ror:12 row_mask:0xf bank_mask:0x5
	v_add_f32_dpp v49, v49, v49 row_ror:12 row_mask:0xf bank_mask:0x5
	v_add_f32_dpp v50, v50, v50 row_ror:12 row_mask:0xf bank_mask:0x5
	v_add_f32_dpp v51, v51, v51 row_ror:12 row_mask:0xf bank_mask:0x5
	v_add_f32_dpp v48, v52, v52 row_ror:4 row_mask:0xf bank_mask:0xa
	v_add_f32_dpp v49, v53, v53 row_ror:4 row_mask:0xf bank_mask:0xa
	v_add_f32_dpp v50, v54, v54 row_ror:4 row_mask:0xf bank_mask:0xa
	v_add_f32_dpp v51, v55, v55 row_ror:4 row_mask:0xf bank_mask:0xa
	v_add_f32_dpp v64, v48, v48 quad_perm:[2,3,0,1] row_mask:0xf bank_mask:0xf bound_ctrl:1
	v_add_f32_dpp v65, v50, v50 quad_perm:[2,3,0,1] row_mask:0xf bank_mask:0xf bound_ctrl:1
	v_cndmask_b32_e64 v56, v64, v65, s[50:51]
	v_add_f32_dpp v64, v49, v49 quad_perm:[2,3,0,1] row_mask:0xf bank_mask:0xf bound_ctrl:1
	v_add_f32_dpp v65, v51, v51 quad_perm:[2,3,0,1] row_mask:0xf bank_mask:0xf bound_ctrl:1
	v_cndmask_b32_e64 v57, v64, v65, s[50:51]
	v_add_f32_dpp v64, v56, v56 quad_perm:[1,0,3,2] row_mask:0xf bank_mask:0xf bound_ctrl:1
	s_nop 0
	v_add_f32_dpp v65, v57, v57 quad_perm:[1,0,3,2] row_mask:0xf bank_mask:0xf bound_ctrl:1
	v_cndmask_b32_e64 v66, v64, v65, s[48:49]
	v_cvt_pk_bf16_f32 v66, v66, v66
	global_store_short v8, v66, s[12:13]
	s_sub_u32 s12, s12, 0x8000
	s_subb_u32 s13, s13, 0
	ds_read_b64 v[84:85], v6 offset:12312
	ds_read_b128 v[86:89], v6 offset:12560
	ds_read_b128 v[90:93], v6 offset:12816
	ds_read_u16 v94, v7 offset:12304
	v_fma_mix_f32 v14, v10, v38, 0 op_sel:[0,0,0] op_sel_hi:[0,1,0]
	v_fma_mix_f32 v48, v10, v32, 0 op_sel:[0,0,0] op_sel_hi:[0,1,0]
	v_fma_mix_f32 v14, v11, v38, v14 op_sel:[0,1,0] op_sel_hi:[0,1,0]
	v_fma_mix_f32 v48, v11, v32, v48 op_sel:[0,1,0] op_sel_hi:[0,1,0]
	v_fma_mix_f32 v14, v12, v39, v14 op_sel:[0,0,0] op_sel_hi:[0,1,0]
	v_fma_mix_f32 v48, v12, v33, v48 op_sel:[0,0,0] op_sel_hi:[0,1,0]
	v_fma_mix_f32 v14, v13, v39, v14 op_sel:[0,1,0] op_sel_hi:[0,1,0]
	v_fma_mix_f32 v16, v10, v36, 0 op_sel:[0,0,0] op_sel_hi:[0,1,0]
	v_fma_mix_f32 v17, v11, v36, 0 op_sel:[0,1,0] op_sel_hi:[0,1,0]
	v_add_f32_dpp v20, v14, v14 quad_perm:[1,0,3,2] row_mask:0xf bank_mask:0xf bound_ctrl:1
	v_fma_mix_f32 v48, v13, v33, v48 op_sel:[0,1,0] op_sel_hi:[0,1,0]
	v_fma_mix_f32 v18, v12, v37, 0 op_sel:[0,0,0] op_sel_hi:[0,1,0]
	v_add_f32_dpp v20, v20, v20 quad_perm:[2,3,0,1] row_mask:0xf bank_mask:0xf bound_ctrl:1
	v_fma_mix_f32 v19, v13, v37, 0 op_sel:[0,1,0] op_sel_hi:[0,1,0]
	v_fma_mix_f32 v16, v46, v42, v16 op_sel:[0,0,0] op_sel_hi:[1,1,0]
	v_add_f32_dpp v20, v20, v20 row_half_mirror row_mask:0xf bank_mask:0xf bound_ctrl:1
	v_fma_mix_f32 v17, v46, v42, v17 op_sel:[0,1,0] op_sel_hi:[1,1,0]
	v_fma_mix_f32 v18, v46, v43, v18 op_sel:[0,0,0] op_sel_hi:[1,1,0]
	v_add_f32_dpp v20, v20, v20 row_mirror row_mask:0xf bank_mask:0xf bound_ctrl:1
	v_fma_mix_f32 v19, v46, v43, v19 op_sel:[0,1,0] op_sel_hi:[1,1,0]
	v_fma_mix_f32 v10, v20, v40, v16 op_sel:[0,0,0] op_sel_hi:[0,1,0]
	v_fma_mix_f32 v11, v20, v40, v17 op_sel:[0,1,0] op_sel_hi:[0,1,0]
	v_fma_mix_f32 v12, v20, v41, v18 op_sel:[0,0,0] op_sel_hi:[0,1,0]
	v_fma_mix_f32 v13, v20, v41, v19 op_sel:[0,1,0] op_sel_hi:[0,1,0]
	s_waitcnt lgkmcnt(4)
	ds_read_b64 v[24:25], v6 offset:11288
	ds_read_b128 v[26:29], v6 offset:11536
	ds_read_b128 v[30:33], v6 offset:11792
	ds_read_u16 v34, v7 offset:11280
	v_fma_mix_f32 v14, v10, v74, 0 op_sel:[0,0,0] op_sel_hi:[0,1,0]
	v_fma_mix_f32 v49, v10, v44, 0 op_sel:[0,0,0] op_sel_hi:[0,1,0]
	v_fma_mix_f32 v14, v11, v74, v14 op_sel:[0,1,0] op_sel_hi:[0,1,0]
	v_fma_mix_f32 v49, v11, v44, v49 op_sel:[0,1,0] op_sel_hi:[0,1,0]
	v_fma_mix_f32 v14, v12, v75, v14 op_sel:[0,0,0] op_sel_hi:[0,1,0]
	v_fma_mix_f32 v49, v12, v45, v49 op_sel:[0,0,0] op_sel_hi:[0,1,0]
	v_fma_mix_f32 v14, v13, v75, v14 op_sel:[0,1,0] op_sel_hi:[0,1,0]
	v_fma_mix_f32 v16, v10, v72, 0 op_sel:[0,0,0] op_sel_hi:[0,1,0]
	v_fma_mix_f32 v17, v11, v72, 0 op_sel:[0,1,0] op_sel_hi:[0,1,0]
	v_add_f32_dpp v20, v14, v14 quad_perm:[1,0,3,2] row_mask:0xf bank_mask:0xf bound_ctrl:1
	v_fma_mix_f32 v49, v13, v45, v49 op_sel:[0,1,0] op_sel_hi:[0,1,0]
	v_fma_mix_f32 v18, v12, v73, 0 op_sel:[0,0,0] op_sel_hi:[0,1,0]
	v_add_f32_dpp v20, v20, v20 quad_perm:[2,3,0,1] row_mask:0xf bank_mask:0xf bound_ctrl:1
	v_fma_mix_f32 v19, v13, v73, 0 op_sel:[0,1,0] op_sel_hi:[0,1,0]
	v_fma_mix_f32 v16, v82, v78, v16 op_sel:[0,0,0] op_sel_hi:[1,1,0]
	v_add_f32_dpp v20, v20, v20 row_half_mirror row_mask:0xf bank_mask:0xf bound_ctrl:1
	v_fma_mix_f32 v17, v82, v78, v17 op_sel:[0,1,0] op_sel_hi:[1,1,0]
	v_fma_mix_f32 v18, v82, v79, v18 op_sel:[0,0,0] op_sel_hi:[1,1,0]
	v_add_f32_dpp v20, v20, v20 row_mirror row_mask:0xf bank_mask:0xf bound_ctrl:1
	v_fma_mix_f32 v19, v82, v79, v19 op_sel:[0,1,0] op_sel_hi:[1,1,0]
	v_fma_mix_f32 v10, v20, v76, v16 op_sel:[0,0,0] op_sel_hi:[0,1,0]
	v_fma_mix_f32 v11, v20, v76, v17 op_sel:[0,1,0] op_sel_hi:[0,1,0]
	v_fma_mix_f32 v12, v20, v77, v18 op_sel:[0,0,0] op_sel_hi:[0,1,0]
	v_fma_mix_f32 v13, v20, v77, v19 op_sel:[0,1,0] op_sel_hi:[0,1,0]
	s_waitcnt lgkmcnt(4)
	ds_read_b64 v[36:37], v6 offset:10264
	ds_read_b128 v[38:41], v6 offset:10512
	ds_read_b128 v[42:45], v6 offset:10768
	ds_read_u16 v46, v7 offset:10256
	v_fma_mix_f32 v14, v10, v86, 0 op_sel:[0,0,0] op_sel_hi:[0,1,0]
	v_fma_mix_f32 v50, v10, v80, 0 op_sel:[0,0,0] op_sel_hi:[0,1,0]
	v_fma_mix_f32 v14, v11, v86, v14 op_sel:[0,1,0] op_sel_hi:[0,1,0]
	v_fma_mix_f32 v50, v11, v80, v50 op_sel:[0,1,0] op_sel_hi:[0,1,0]
	v_fma_mix_f32 v14, v12, v87, v14 op_sel:[0,0,0] op_sel_hi:[0,1,0]
	v_fma_mix_f32 v50, v12, v81, v50 op_sel:[0,0,0] op_sel_hi:[0,1,0]
	v_fma_mix_f32 v14, v13, v87, v14 op_sel:[0,1,0] op_sel_hi:[0,1,0]
	v_fma_mix_f32 v16, v10, v84, 0 op_sel:[0,0,0] op_sel_hi:[0,1,0]
	v_fma_mix_f32 v17, v11, v84, 0 op_sel:[0,1,0] op_sel_hi:[0,1,0]
	v_add_f32_dpp v20, v14, v14 quad_perm:[1,0,3,2] row_mask:0xf bank_mask:0xf bound_ctrl:1
	v_fma_mix_f32 v50, v13, v81, v50 op_sel:[0,1,0] op_sel_hi:[0,1,0]
	v_fma_mix_f32 v18, v12, v85, 0 op_sel:[0,0,0] op_sel_hi:[0,1,0]
	v_add_f32_dpp v20, v20, v20 quad_perm:[2,3,0,1] row_mask:0xf bank_mask:0xf bound_ctrl:1
	v_fma_mix_f32 v19, v13, v85, 0 op_sel:[0,1,0] op_sel_hi:[0,1,0]
	v_fma_mix_f32 v16, v94, v90, v16 op_sel:[0,0,0] op_sel_hi:[1,1,0]
	v_add_f32_dpp v20, v20, v20 row_half_mirror row_mask:0xf bank_mask:0xf bound_ctrl:1
	v_fma_mix_f32 v17, v94, v90, v17 op_sel:[0,1,0] op_sel_hi:[1,1,0]
	v_fma_mix_f32 v18, v94, v91, v18 op_sel:[0,0,0] op_sel_hi:[1,1,0]
	v_add_f32_dpp v20, v20, v20 row_mirror row_mask:0xf bank_mask:0xf bound_ctrl:1
	v_fma_mix_f32 v19, v94, v91, v19 op_sel:[0,1,0] op_sel_hi:[1,1,0]
	v_fma_mix_f32 v10, v20, v88, v16 op_sel:[0,0,0] op_sel_hi:[0,1,0]
	v_fma_mix_f32 v11, v20, v88, v17 op_sel:[0,1,0] op_sel_hi:[0,1,0]
	v_fma_mix_f32 v12, v20, v89, v18 op_sel:[0,0,0] op_sel_hi:[0,1,0]
	v_fma_mix_f32 v13, v20, v89, v19 op_sel:[0,1,0] op_sel_hi:[0,1,0]
	s_waitcnt lgkmcnt(4)
	ds_read_b64 v[72:73], v6 offset:9240
	ds_read_b128 v[74:77], v6 offset:9488
	ds_read_b128 v[78:81], v6 offset:9744
	ds_read_u16 v82, v7 offset:9232
	v_fma_mix_f32 v14, v10, v26, 0 op_sel:[0,0,0] op_sel_hi:[0,1,0]
	v_fma_mix_f32 v51, v10, v92, 0 op_sel:[0,0,0] op_sel_hi:[0,1,0]
	v_fma_mix_f32 v14, v11, v26, v14 op_sel:[0,1,0] op_sel_hi:[0,1,0]
	v_fma_mix_f32 v51, v11, v92, v51 op_sel:[0,1,0] op_sel_hi:[0,1,0]
	v_fma_mix_f32 v14, v12, v27, v14 op_sel:[0,0,0] op_sel_hi:[0,1,0]
	v_fma_mix_f32 v51, v12, v93, v51 op_sel:[0,0,0] op_sel_hi:[0,1,0]
	v_fma_mix_f32 v14, v13, v27, v14 op_sel:[0,1,0] op_sel_hi:[0,1,0]
	v_fma_mix_f32 v16, v10, v24, 0 op_sel:[0,0,0] op_sel_hi:[0,1,0]
	v_fma_mix_f32 v17, v11, v24, 0 op_sel:[0,1,0] op_sel_hi:[0,1,0]
	v_add_f32_dpp v20, v14, v14 quad_perm:[1,0,3,2] row_mask:0xf bank_mask:0xf bound_ctrl:1
	v_fma_mix_f32 v51, v13, v93, v51 op_sel:[0,1,0] op_sel_hi:[0,1,0]
	v_fma_mix_f32 v18, v12, v25, 0 op_sel:[0,0,0] op_sel_hi:[0,1,0]
	v_add_f32_dpp v20, v20, v20 quad_perm:[2,3,0,1] row_mask:0xf bank_mask:0xf bound_ctrl:1
	v_fma_mix_f32 v19, v13, v25, 0 op_sel:[0,1,0] op_sel_hi:[0,1,0]
	v_fma_mix_f32 v16, v34, v30, v16 op_sel:[0,0,0] op_sel_hi:[1,1,0]
	v_add_f32_dpp v20, v20, v20 row_half_mirror row_mask:0xf bank_mask:0xf bound_ctrl:1
	v_fma_mix_f32 v17, v34, v30, v17 op_sel:[0,1,0] op_sel_hi:[1,1,0]
	v_fma_mix_f32 v18, v34, v31, v18 op_sel:[0,0,0] op_sel_hi:[1,1,0]
	v_add_f32_dpp v20, v20, v20 row_mirror row_mask:0xf bank_mask:0xf bound_ctrl:1
	v_fma_mix_f32 v19, v34, v31, v19 op_sel:[0,1,0] op_sel_hi:[1,1,0]
	v_fma_mix_f32 v10, v20, v28, v16 op_sel:[0,0,0] op_sel_hi:[0,1,0]
	v_fma_mix_f32 v11, v20, v28, v17 op_sel:[0,1,0] op_sel_hi:[0,1,0]
	v_fma_mix_f32 v12, v20, v29, v18 op_sel:[0,0,0] op_sel_hi:[0,1,0]
	v_fma_mix_f32 v13, v20, v29, v19 op_sel:[0,1,0] op_sel_hi:[0,1,0]
	s_waitcnt lgkmcnt(4)
	ds_read_b64 v[84:85], v6 offset:8216
	ds_read_b128 v[86:89], v6 offset:8464
	ds_read_b128 v[90:93], v6 offset:8720
	ds_read_u16 v94, v7 offset:8208
	v_fma_mix_f32 v14, v10, v38, 0 op_sel:[0,0,0] op_sel_hi:[0,1,0]
	v_fma_mix_f32 v52, v10, v32, 0 op_sel:[0,0,0] op_sel_hi:[0,1,0]
	v_fma_mix_f32 v14, v11, v38, v14 op_sel:[0,1,0] op_sel_hi:[0,1,0]
	v_fma_mix_f32 v52, v11, v32, v52 op_sel:[0,1,0] op_sel_hi:[0,1,0]
	v_fma_mix_f32 v14, v12, v39, v14 op_sel:[0,0,0] op_sel_hi:[0,1,0]
	v_fma_mix_f32 v52, v12, v33, v52 op_sel:[0,0,0] op_sel_hi:[0,1,0]
	v_fma_mix_f32 v14, v13, v39, v14 op_sel:[0,1,0] op_sel_hi:[0,1,0]
	v_fma_mix_f32 v16, v10, v36, 0 op_sel:[0,0,0] op_sel_hi:[0,1,0]
	v_fma_mix_f32 v17, v11, v36, 0 op_sel:[0,1,0] op_sel_hi:[0,1,0]
	v_add_f32_dpp v20, v14, v14 quad_perm:[1,0,3,2] row_mask:0xf bank_mask:0xf bound_ctrl:1
	v_fma_mix_f32 v52, v13, v33, v52 op_sel:[0,1,0] op_sel_hi:[0,1,0]
	v_fma_mix_f32 v18, v12, v37, 0 op_sel:[0,0,0] op_sel_hi:[0,1,0]
	v_add_f32_dpp v20, v20, v20 quad_perm:[2,3,0,1] row_mask:0xf bank_mask:0xf bound_ctrl:1
	v_fma_mix_f32 v19, v13, v37, 0 op_sel:[0,1,0] op_sel_hi:[0,1,0]
	v_fma_mix_f32 v16, v46, v42, v16 op_sel:[0,0,0] op_sel_hi:[1,1,0]
	v_add_f32_dpp v20, v20, v20 row_half_mirror row_mask:0xf bank_mask:0xf bound_ctrl:1
	v_fma_mix_f32 v17, v46, v42, v17 op_sel:[0,1,0] op_sel_hi:[1,1,0]
	v_fma_mix_f32 v18, v46, v43, v18 op_sel:[0,0,0] op_sel_hi:[1,1,0]
	v_add_f32_dpp v20, v20, v20 row_mirror row_mask:0xf bank_mask:0xf bound_ctrl:1
	v_fma_mix_f32 v19, v46, v43, v19 op_sel:[0,1,0] op_sel_hi:[1,1,0]
	v_fma_mix_f32 v10, v20, v40, v16 op_sel:[0,0,0] op_sel_hi:[0,1,0]
	v_fma_mix_f32 v11, v20, v40, v17 op_sel:[0,1,0] op_sel_hi:[0,1,0]
	v_fma_mix_f32 v12, v20, v41, v18 op_sel:[0,0,0] op_sel_hi:[0,1,0]
	v_fma_mix_f32 v13, v20, v41, v19 op_sel:[0,1,0] op_sel_hi:[0,1,0]
	s_waitcnt lgkmcnt(4)
	ds_read_b64 v[24:25], v6 offset:7192
	ds_read_b128 v[26:29], v6 offset:7440
	ds_read_b128 v[30:33], v6 offset:7696
	ds_read_u16 v34, v7 offset:7184
	v_fma_mix_f32 v14, v10, v74, 0 op_sel:[0,0,0] op_sel_hi:[0,1,0]
	v_fma_mix_f32 v53, v10, v44, 0 op_sel:[0,0,0] op_sel_hi:[0,1,0]
	v_fma_mix_f32 v14, v11, v74, v14 op_sel:[0,1,0] op_sel_hi:[0,1,0]
	v_fma_mix_f32 v53, v11, v44, v53 op_sel:[0,1,0] op_sel_hi:[0,1,0]
	v_fma_mix_f32 v14, v12, v75, v14 op_sel:[0,0,0] op_sel_hi:[0,1,0]
	v_fma_mix_f32 v53, v12, v45, v53 op_sel:[0,0,0] op_sel_hi:[0,1,0]
	v_fma_mix_f32 v14, v13, v75, v14 op_sel:[0,1,0] op_sel_hi:[0,1,0]
	v_fma_mix_f32 v16, v10, v72, 0 op_sel:[0,0,0] op_sel_hi:[0,1,0]
	v_fma_mix_f32 v17, v11, v72, 0 op_sel:[0,1,0] op_sel_hi:[0,1,0]
	v_add_f32_dpp v20, v14, v14 quad_perm:[1,0,3,2] row_mask:0xf bank_mask:0xf bound_ctrl:1
	v_fma_mix_f32 v53, v13, v45, v53 op_sel:[0,1,0] op_sel_hi:[0,1,0]
	v_fma_mix_f32 v18, v12, v73, 0 op_sel:[0,0,0] op_sel_hi:[0,1,0]
	v_add_f32_dpp v20, v20, v20 quad_perm:[2,3,0,1] row_mask:0xf bank_mask:0xf bound_ctrl:1
	v_fma_mix_f32 v19, v13, v73, 0 op_sel:[0,1,0] op_sel_hi:[0,1,0]
	v_fma_mix_f32 v16, v82, v78, v16 op_sel:[0,0,0] op_sel_hi:[1,1,0]
	v_add_f32_dpp v20, v20, v20 row_half_mirror row_mask:0xf bank_mask:0xf bound_ctrl:1
	v_fma_mix_f32 v17, v82, v78, v17 op_sel:[0,1,0] op_sel_hi:[1,1,0]
	v_fma_mix_f32 v18, v82, v79, v18 op_sel:[0,0,0] op_sel_hi:[1,1,0]
	v_add_f32_dpp v20, v20, v20 row_mirror row_mask:0xf bank_mask:0xf bound_ctrl:1
	v_fma_mix_f32 v19, v82, v79, v19 op_sel:[0,1,0] op_sel_hi:[1,1,0]
	v_fma_mix_f32 v10, v20, v76, v16 op_sel:[0,0,0] op_sel_hi:[0,1,0]
	v_fma_mix_f32 v11, v20, v76, v17 op_sel:[0,1,0] op_sel_hi:[0,1,0]
	v_fma_mix_f32 v12, v20, v77, v18 op_sel:[0,0,0] op_sel_hi:[0,1,0]
	v_fma_mix_f32 v13, v20, v77, v19 op_sel:[0,1,0] op_sel_hi:[0,1,0]
	s_waitcnt lgkmcnt(4)
	ds_read_b64 v[36:37], v6 offset:6168
	ds_read_b128 v[38:41], v6 offset:6416
	ds_read_b128 v[42:45], v6 offset:6672
	ds_read_u16 v46, v7 offset:6160
	v_fma_mix_f32 v14, v10, v86, 0 op_sel:[0,0,0] op_sel_hi:[0,1,0]
	v_fma_mix_f32 v54, v10, v80, 0 op_sel:[0,0,0] op_sel_hi:[0,1,0]
	v_fma_mix_f32 v14, v11, v86, v14 op_sel:[0,1,0] op_sel_hi:[0,1,0]
	v_fma_mix_f32 v54, v11, v80, v54 op_sel:[0,1,0] op_sel_hi:[0,1,0]
	v_fma_mix_f32 v14, v12, v87, v14 op_sel:[0,0,0] op_sel_hi:[0,1,0]
	v_fma_mix_f32 v54, v12, v81, v54 op_sel:[0,0,0] op_sel_hi:[0,1,0]
	v_fma_mix_f32 v14, v13, v87, v14 op_sel:[0,1,0] op_sel_hi:[0,1,0]
	v_fma_mix_f32 v16, v10, v84, 0 op_sel:[0,0,0] op_sel_hi:[0,1,0]
	v_fma_mix_f32 v17, v11, v84, 0 op_sel:[0,1,0] op_sel_hi:[0,1,0]
	v_add_f32_dpp v20, v14, v14 quad_perm:[1,0,3,2] row_mask:0xf bank_mask:0xf bound_ctrl:1
	v_fma_mix_f32 v54, v13, v81, v54 op_sel:[0,1,0] op_sel_hi:[0,1,0]
	v_fma_mix_f32 v18, v12, v85, 0 op_sel:[0,0,0] op_sel_hi:[0,1,0]
	v_add_f32_dpp v20, v20, v20 quad_perm:[2,3,0,1] row_mask:0xf bank_mask:0xf bound_ctrl:1
	v_fma_mix_f32 v19, v13, v85, 0 op_sel:[0,1,0] op_sel_hi:[0,1,0]
	v_fma_mix_f32 v16, v94, v90, v16 op_sel:[0,0,0] op_sel_hi:[1,1,0]
	v_add_f32_dpp v20, v20, v20 row_half_mirror row_mask:0xf bank_mask:0xf bound_ctrl:1
	v_fma_mix_f32 v17, v94, v90, v17 op_sel:[0,1,0] op_sel_hi:[1,1,0]
	v_fma_mix_f32 v18, v94, v91, v18 op_sel:[0,0,0] op_sel_hi:[1,1,0]
	v_add_f32_dpp v20, v20, v20 row_mirror row_mask:0xf bank_mask:0xf bound_ctrl:1
	v_fma_mix_f32 v19, v94, v91, v19 op_sel:[0,1,0] op_sel_hi:[1,1,0]
	v_fma_mix_f32 v10, v20, v88, v16 op_sel:[0,0,0] op_sel_hi:[0,1,0]
	v_fma_mix_f32 v11, v20, v88, v17 op_sel:[0,1,0] op_sel_hi:[0,1,0]
	v_fma_mix_f32 v12, v20, v89, v18 op_sel:[0,0,0] op_sel_hi:[0,1,0]
	v_fma_mix_f32 v13, v20, v89, v19 op_sel:[0,1,0] op_sel_hi:[0,1,0]
	s_waitcnt lgkmcnt(4)
	ds_read_b64 v[72:73], v6 offset:5144
	ds_read_b128 v[74:77], v6 offset:5392
	ds_read_b128 v[78:81], v6 offset:5648
	ds_read_u16 v82, v7 offset:5136
	v_fma_mix_f32 v14, v10, v26, 0 op_sel:[0,0,0] op_sel_hi:[0,1,0]
	v_fma_mix_f32 v55, v10, v92, 0 op_sel:[0,0,0] op_sel_hi:[0,1,0]
	v_fma_mix_f32 v14, v11, v26, v14 op_sel:[0,1,0] op_sel_hi:[0,1,0]
	v_fma_mix_f32 v55, v11, v92, v55 op_sel:[0,1,0] op_sel_hi:[0,1,0]
	v_fma_mix_f32 v14, v12, v27, v14 op_sel:[0,0,0] op_sel_hi:[0,1,0]
	v_fma_mix_f32 v55, v12, v93, v55 op_sel:[0,0,0] op_sel_hi:[0,1,0]
	v_fma_mix_f32 v14, v13, v27, v14 op_sel:[0,1,0] op_sel_hi:[0,1,0]
	v_fma_mix_f32 v16, v10, v24, 0 op_sel:[0,0,0] op_sel_hi:[0,1,0]
	v_fma_mix_f32 v17, v11, v24, 0 op_sel:[0,1,0] op_sel_hi:[0,1,0]
	v_add_f32_dpp v20, v14, v14 quad_perm:[1,0,3,2] row_mask:0xf bank_mask:0xf bound_ctrl:1
	v_fma_mix_f32 v55, v13, v93, v55 op_sel:[0,1,0] op_sel_hi:[0,1,0]
	v_fma_mix_f32 v18, v12, v25, 0 op_sel:[0,0,0] op_sel_hi:[0,1,0]
	v_add_f32_dpp v20, v20, v20 quad_perm:[2,3,0,1] row_mask:0xf bank_mask:0xf bound_ctrl:1
	v_fma_mix_f32 v19, v13, v25, 0 op_sel:[0,1,0] op_sel_hi:[0,1,0]
	v_fma_mix_f32 v16, v34, v30, v16 op_sel:[0,0,0] op_sel_hi:[1,1,0]
	v_add_f32_dpp v20, v20, v20 row_half_mirror row_mask:0xf bank_mask:0xf bound_ctrl:1
	v_fma_mix_f32 v17, v34, v30, v17 op_sel:[0,1,0] op_sel_hi:[1,1,0]
	v_fma_mix_f32 v18, v34, v31, v18 op_sel:[0,0,0] op_sel_hi:[1,1,0]
	v_add_f32_dpp v20, v20, v20 row_mirror row_mask:0xf bank_mask:0xf bound_ctrl:1
	v_fma_mix_f32 v19, v34, v31, v19 op_sel:[0,1,0] op_sel_hi:[1,1,0]
	v_fma_mix_f32 v10, v20, v28, v16 op_sel:[0,0,0] op_sel_hi:[0,1,0]
	v_fma_mix_f32 v11, v20, v28, v17 op_sel:[0,1,0] op_sel_hi:[0,1,0]
	v_fma_mix_f32 v12, v20, v29, v18 op_sel:[0,0,0] op_sel_hi:[0,1,0]
	v_fma_mix_f32 v13, v20, v29, v19 op_sel:[0,1,0] op_sel_hi:[0,1,0]
	s_waitcnt lgkmcnt(4)
	ds_read_b64 v[84:85], v6 offset:4120
	ds_read_b128 v[86:89], v6 offset:4368
	ds_read_b128 v[90:93], v6 offset:4624
	ds_read_u16 v94, v7 offset:4112
	v_fma_mix_f32 v14, v10, v38, 0 op_sel:[0,0,0] op_sel_hi:[0,1,0]
	v_fma_mix_f32 v56, v10, v32, 0 op_sel:[0,0,0] op_sel_hi:[0,1,0]
	v_fma_mix_f32 v14, v11, v38, v14 op_sel:[0,1,0] op_sel_hi:[0,1,0]
	v_fma_mix_f32 v56, v11, v32, v56 op_sel:[0,1,0] op_sel_hi:[0,1,0]
	v_fma_mix_f32 v14, v12, v39, v14 op_sel:[0,0,0] op_sel_hi:[0,1,0]
	v_fma_mix_f32 v56, v12, v33, v56 op_sel:[0,0,0] op_sel_hi:[0,1,0]
	v_fma_mix_f32 v14, v13, v39, v14 op_sel:[0,1,0] op_sel_hi:[0,1,0]
	v_fma_mix_f32 v16, v10, v36, 0 op_sel:[0,0,0] op_sel_hi:[0,1,0]
	v_fma_mix_f32 v17, v11, v36, 0 op_sel:[0,1,0] op_sel_hi:[0,1,0]
	v_add_f32_dpp v20, v14, v14 quad_perm:[1,0,3,2] row_mask:0xf bank_mask:0xf bound_ctrl:1
	v_fma_mix_f32 v56, v13, v33, v56 op_sel:[0,1,0] op_sel_hi:[0,1,0]
	v_fma_mix_f32 v18, v12, v37, 0 op_sel:[0,0,0] op_sel_hi:[0,1,0]
	v_add_f32_dpp v20, v20, v20 quad_perm:[2,3,0,1] row_mask:0xf bank_mask:0xf bound_ctrl:1
	v_fma_mix_f32 v19, v13, v37, 0 op_sel:[0,1,0] op_sel_hi:[0,1,0]
	v_fma_mix_f32 v16, v46, v42, v16 op_sel:[0,0,0] op_sel_hi:[1,1,0]
	v_add_f32_dpp v20, v20, v20 row_half_mirror row_mask:0xf bank_mask:0xf bound_ctrl:1
	v_fma_mix_f32 v17, v46, v42, v17 op_sel:[0,1,0] op_sel_hi:[1,1,0]
	v_fma_mix_f32 v18, v46, v43, v18 op_sel:[0,0,0] op_sel_hi:[1,1,0]
	v_add_f32_dpp v20, v20, v20 row_mirror row_mask:0xf bank_mask:0xf bound_ctrl:1
	v_fma_mix_f32 v19, v46, v43, v19 op_sel:[0,1,0] op_sel_hi:[1,1,0]
	v_fma_mix_f32 v10, v20, v40, v16 op_sel:[0,0,0] op_sel_hi:[0,1,0]
	v_fma_mix_f32 v11, v20, v40, v17 op_sel:[0,1,0] op_sel_hi:[0,1,0]
	v_fma_mix_f32 v12, v20, v41, v18 op_sel:[0,0,0] op_sel_hi:[0,1,0]
	v_fma_mix_f32 v13, v20, v41, v19 op_sel:[0,1,0] op_sel_hi:[0,1,0]
	s_waitcnt lgkmcnt(4)
	ds_read_b64 v[24:25], v6 offset:3096
	ds_read_b128 v[26:29], v6 offset:3344
	ds_read_b128 v[30:33], v6 offset:3600
	ds_read_u16 v34, v7 offset:3088
	v_fma_mix_f32 v14, v10, v74, 0 op_sel:[0,0,0] op_sel_hi:[0,1,0]
	v_fma_mix_f32 v57, v10, v44, 0 op_sel:[0,0,0] op_sel_hi:[0,1,0]
	v_fma_mix_f32 v14, v11, v74, v14 op_sel:[0,1,0] op_sel_hi:[0,1,0]
	v_fma_mix_f32 v57, v11, v44, v57 op_sel:[0,1,0] op_sel_hi:[0,1,0]
	v_fma_mix_f32 v14, v12, v75, v14 op_sel:[0,0,0] op_sel_hi:[0,1,0]
	v_fma_mix_f32 v57, v12, v45, v57 op_sel:[0,0,0] op_sel_hi:[0,1,0]
	v_fma_mix_f32 v14, v13, v75, v14 op_sel:[0,1,0] op_sel_hi:[0,1,0]
	v_fma_mix_f32 v16, v10, v72, 0 op_sel:[0,0,0] op_sel_hi:[0,1,0]
	v_fma_mix_f32 v17, v11, v72, 0 op_sel:[0,1,0] op_sel_hi:[0,1,0]
	v_add_f32_dpp v20, v14, v14 quad_perm:[1,0,3,2] row_mask:0xf bank_mask:0xf bound_ctrl:1
	v_fma_mix_f32 v57, v13, v45, v57 op_sel:[0,1,0] op_sel_hi:[0,1,0]
	v_fma_mix_f32 v18, v12, v73, 0 op_sel:[0,0,0] op_sel_hi:[0,1,0]
	v_add_f32_dpp v20, v20, v20 quad_perm:[2,3,0,1] row_mask:0xf bank_mask:0xf bound_ctrl:1
	v_fma_mix_f32 v19, v13, v73, 0 op_sel:[0,1,0] op_sel_hi:[0,1,0]
	v_fma_mix_f32 v16, v82, v78, v16 op_sel:[0,0,0] op_sel_hi:[1,1,0]
	v_add_f32_dpp v20, v20, v20 row_half_mirror row_mask:0xf bank_mask:0xf bound_ctrl:1
	v_fma_mix_f32 v17, v82, v78, v17 op_sel:[0,1,0] op_sel_hi:[1,1,0]
	v_fma_mix_f32 v18, v82, v79, v18 op_sel:[0,0,0] op_sel_hi:[1,1,0]
	v_add_f32_dpp v20, v20, v20 row_mirror row_mask:0xf bank_mask:0xf bound_ctrl:1
	v_fma_mix_f32 v19, v82, v79, v19 op_sel:[0,1,0] op_sel_hi:[1,1,0]
	v_fma_mix_f32 v10, v20, v76, v16 op_sel:[0,0,0] op_sel_hi:[0,1,0]
	v_fma_mix_f32 v11, v20, v76, v17 op_sel:[0,1,0] op_sel_hi:[0,1,0]
	v_fma_mix_f32 v12, v20, v77, v18 op_sel:[0,0,0] op_sel_hi:[0,1,0]
	v_fma_mix_f32 v13, v20, v77, v19 op_sel:[0,1,0] op_sel_hi:[0,1,0]
	s_waitcnt lgkmcnt(4)
	ds_read_b64 v[36:37], v6 offset:2072
	ds_read_b128 v[38:41], v6 offset:2320
	ds_read_b128 v[42:45], v6 offset:2576
	ds_read_u16 v46, v7 offset:2064
	v_fma_mix_f32 v14, v10, v86, 0 op_sel:[0,0,0] op_sel_hi:[0,1,0]
	v_fma_mix_f32 v58, v10, v80, 0 op_sel:[0,0,0] op_sel_hi:[0,1,0]
	v_fma_mix_f32 v14, v11, v86, v14 op_sel:[0,1,0] op_sel_hi:[0,1,0]
	v_fma_mix_f32 v58, v11, v80, v58 op_sel:[0,1,0] op_sel_hi:[0,1,0]
	v_fma_mix_f32 v14, v12, v87, v14 op_sel:[0,0,0] op_sel_hi:[0,1,0]
	v_fma_mix_f32 v58, v12, v81, v58 op_sel:[0,0,0] op_sel_hi:[0,1,0]
	v_fma_mix_f32 v14, v13, v87, v14 op_sel:[0,1,0] op_sel_hi:[0,1,0]
	v_fma_mix_f32 v16, v10, v84, 0 op_sel:[0,0,0] op_sel_hi:[0,1,0]
	v_fma_mix_f32 v17, v11, v84, 0 op_sel:[0,1,0] op_sel_hi:[0,1,0]
	v_add_f32_dpp v20, v14, v14 quad_perm:[1,0,3,2] row_mask:0xf bank_mask:0xf bound_ctrl:1
	v_fma_mix_f32 v58, v13, v81, v58 op_sel:[0,1,0] op_sel_hi:[0,1,0]
	v_fma_mix_f32 v18, v12, v85, 0 op_sel:[0,0,0] op_sel_hi:[0,1,0]
	v_add_f32_dpp v20, v20, v20 quad_perm:[2,3,0,1] row_mask:0xf bank_mask:0xf bound_ctrl:1
	v_fma_mix_f32 v19, v13, v85, 0 op_sel:[0,1,0] op_sel_hi:[0,1,0]
	v_fma_mix_f32 v16, v94, v90, v16 op_sel:[0,0,0] op_sel_hi:[1,1,0]
	v_add_f32_dpp v20, v20, v20 row_half_mirror row_mask:0xf bank_mask:0xf bound_ctrl:1
	v_fma_mix_f32 v17, v94, v90, v17 op_sel:[0,1,0] op_sel_hi:[1,1,0]
	v_fma_mix_f32 v18, v94, v91, v18 op_sel:[0,0,0] op_sel_hi:[1,1,0]
	v_add_f32_dpp v20, v20, v20 row_mirror row_mask:0xf bank_mask:0xf bound_ctrl:1
	v_fma_mix_f32 v19, v94, v91, v19 op_sel:[0,1,0] op_sel_hi:[1,1,0]
	v_fma_mix_f32 v10, v20, v88, v16 op_sel:[0,0,0] op_sel_hi:[0,1,0]
	v_fma_mix_f32 v11, v20, v88, v17 op_sel:[0,1,0] op_sel_hi:[0,1,0]
	v_fma_mix_f32 v12, v20, v89, v18 op_sel:[0,0,0] op_sel_hi:[0,1,0]
	v_fma_mix_f32 v13, v20, v89, v19 op_sel:[0,1,0] op_sel_hi:[0,1,0]
	s_waitcnt lgkmcnt(4)
	ds_read_b64 v[72:73], v6 offset:1048
	ds_read_b128 v[74:77], v6 offset:1296
	ds_read_b128 v[78:81], v6 offset:1552
	ds_read_u16 v82, v7 offset:1040
	v_fma_mix_f32 v14, v10, v26, 0 op_sel:[0,0,0] op_sel_hi:[0,1,0]
	v_fma_mix_f32 v59, v10, v92, 0 op_sel:[0,0,0] op_sel_hi:[0,1,0]
	v_fma_mix_f32 v14, v11, v26, v14 op_sel:[0,1,0] op_sel_hi:[0,1,0]
	v_fma_mix_f32 v59, v11, v92, v59 op_sel:[0,1,0] op_sel_hi:[0,1,0]
	v_fma_mix_f32 v14, v12, v27, v14 op_sel:[0,0,0] op_sel_hi:[0,1,0]
	v_fma_mix_f32 v59, v12, v93, v59 op_sel:[0,0,0] op_sel_hi:[0,1,0]
	v_fma_mix_f32 v14, v13, v27, v14 op_sel:[0,1,0] op_sel_hi:[0,1,0]
	v_fma_mix_f32 v16, v10, v24, 0 op_sel:[0,0,0] op_sel_hi:[0,1,0]
	v_fma_mix_f32 v17, v11, v24, 0 op_sel:[0,1,0] op_sel_hi:[0,1,0]
	v_add_f32_dpp v20, v14, v14 quad_perm:[1,0,3,2] row_mask:0xf bank_mask:0xf bound_ctrl:1
	v_fma_mix_f32 v59, v13, v93, v59 op_sel:[0,1,0] op_sel_hi:[0,1,0]
	v_fma_mix_f32 v18, v12, v25, 0 op_sel:[0,0,0] op_sel_hi:[0,1,0]
	v_add_f32_dpp v20, v20, v20 quad_perm:[2,3,0,1] row_mask:0xf bank_mask:0xf bound_ctrl:1
	v_fma_mix_f32 v19, v13, v25, 0 op_sel:[0,1,0] op_sel_hi:[0,1,0]
	v_fma_mix_f32 v16, v34, v30, v16 op_sel:[0,0,0] op_sel_hi:[1,1,0]
	v_add_f32_dpp v20, v20, v20 row_half_mirror row_mask:0xf bank_mask:0xf bound_ctrl:1
	v_fma_mix_f32 v17, v34, v30, v17 op_sel:[0,1,0] op_sel_hi:[1,1,0]
	v_fma_mix_f32 v18, v34, v31, v18 op_sel:[0,0,0] op_sel_hi:[1,1,0]
	v_add_f32_dpp v20, v20, v20 row_mirror row_mask:0xf bank_mask:0xf bound_ctrl:1
	v_fma_mix_f32 v19, v34, v31, v19 op_sel:[0,1,0] op_sel_hi:[1,1,0]
	v_fma_mix_f32 v10, v20, v28, v16 op_sel:[0,0,0] op_sel_hi:[0,1,0]
	v_fma_mix_f32 v11, v20, v28, v17 op_sel:[0,1,0] op_sel_hi:[0,1,0]
	v_fma_mix_f32 v12, v20, v29, v18 op_sel:[0,0,0] op_sel_hi:[0,1,0]
	v_fma_mix_f32 v13, v20, v29, v19 op_sel:[0,1,0] op_sel_hi:[0,1,0]
	s_waitcnt lgkmcnt(4)
	ds_read_b128 v[100:103], v9
	ds_read_b64 v[84:85], v6 offset:24
	ds_read_b128 v[86:89], v6 offset:272
	ds_read_b128 v[90:93], v6 offset:528
	ds_read_u16 v94, v7 offset:16
	v_fma_mix_f32 v14, v10, v38, 0 op_sel:[0,0,0] op_sel_hi:[0,1,0]
	v_fma_mix_f32 v60, v10, v32, 0 op_sel:[0,0,0] op_sel_hi:[0,1,0]
	v_fma_mix_f32 v14, v11, v38, v14 op_sel:[0,1,0] op_sel_hi:[0,1,0]
	v_fma_mix_f32 v60, v11, v32, v60 op_sel:[0,1,0] op_sel_hi:[0,1,0]
	v_fma_mix_f32 v14, v12, v39, v14 op_sel:[0,0,0] op_sel_hi:[0,1,0]
	v_fma_mix_f32 v60, v12, v33, v60 op_sel:[0,0,0] op_sel_hi:[0,1,0]
	v_fma_mix_f32 v14, v13, v39, v14 op_sel:[0,1,0] op_sel_hi:[0,1,0]
	v_fma_mix_f32 v16, v10, v36, 0 op_sel:[0,0,0] op_sel_hi:[0,1,0]
	v_fma_mix_f32 v17, v11, v36, 0 op_sel:[0,1,0] op_sel_hi:[0,1,0]
	v_add_f32_dpp v20, v14, v14 quad_perm:[1,0,3,2] row_mask:0xf bank_mask:0xf bound_ctrl:1
	v_fma_mix_f32 v60, v13, v33, v60 op_sel:[0,1,0] op_sel_hi:[0,1,0]
	v_fma_mix_f32 v18, v12, v37, 0 op_sel:[0,0,0] op_sel_hi:[0,1,0]
	v_add_f32_dpp v20, v20, v20 quad_perm:[2,3,0,1] row_mask:0xf bank_mask:0xf bound_ctrl:1
	v_fma_mix_f32 v19, v13, v37, 0 op_sel:[0,1,0] op_sel_hi:[0,1,0]
	v_fma_mix_f32 v16, v46, v42, v16 op_sel:[0,0,0] op_sel_hi:[1,1,0]
	v_add_f32_dpp v20, v20, v20 row_half_mirror row_mask:0xf bank_mask:0xf bound_ctrl:1
	v_fma_mix_f32 v17, v46, v42, v17 op_sel:[0,1,0] op_sel_hi:[1,1,0]
	v_fma_mix_f32 v18, v46, v43, v18 op_sel:[0,0,0] op_sel_hi:[1,1,0]
	v_add_f32_dpp v20, v20, v20 row_mirror row_mask:0xf bank_mask:0xf bound_ctrl:1
	v_fma_mix_f32 v19, v46, v43, v19 op_sel:[0,1,0] op_sel_hi:[1,1,0]
	v_fma_mix_f32 v10, v20, v40, v16 op_sel:[0,0,0] op_sel_hi:[0,1,0]
	v_fma_mix_f32 v11, v20, v40, v17 op_sel:[0,1,0] op_sel_hi:[0,1,0]
	v_fma_mix_f32 v12, v20, v41, v18 op_sel:[0,0,0] op_sel_hi:[0,1,0]
	v_fma_mix_f32 v13, v20, v41, v19 op_sel:[0,1,0] op_sel_hi:[0,1,0]
	s_waitcnt lgkmcnt(4)
; DEVINL u16 f2bf(float a) { return (u16)(pk2(a, 0.f) & 0xffffu); }
; #define RW_STEP2(B) RW_STEP(B, WvA, XA, KrA, vhA, WvB, XB, KrB, vhB); RW_STEP((B) + 1, WvB, XB, KrB, vhB, WvA, XA, KrA, vhA)
; #define RW_STEP4(B) RW_STEP2(B); RW_STEP2((B) + 2)
; template <int DIR>
; DEVINL void rwkv_scan_dir(const Params& p, int task, int lane, int wave) {
;     ...
;   for (int st = 0; st < 4096; st += 32) {
;     RW_STEP(0, WvA, XA, KrA, vhA, WvB, XB, KrB, vhB);
;     if (st > 0) { const int q0 = st - 16 + seg; yo[(long)(DIR ? (4095 - q0) : q0) * 1024] = f2bf(ykeep); }
;     RW_STEP(1, WvB, XB, KrB, vhB, WvA, XA, KrA, vhA);
;     RW_STEP2(2); RW_STEP4(4); RW_STEP4(8); RW_STEP4(12);
;     RW_STEP(16, WvA, XA, KrA, vhA, WvB, XB, KrB, vhB);
;     { const int q0 = st + seg; yo[(long)(DIR ? (4095 - q0) : q0) * 1024] = f2bf(ykeep); }
;     RW_STEP(17, WvB, XB, KrB, vhB, WvA, XA, KrA, vhA);
;     RW_STEP2(18); RW_STEP4(20); RW_STEP4(24); RW_STEP4(28);
;   }
;   {
;     const float ylast = allred16(ypart);
;     ykeep = (seg == 15) ? ylast : ykeep;
;     const int q0 = 4096 - 16 + seg; yo[(long)(DIR ? (4095 - q0) : q0) * 1024] = f2bf(ykeep);
	v_add_u32_e32 v6, 0xffffc000, v6
	v_add_u32_e32 v7, 0xffffc000, v7
	v_and_b32_e32 v6, 0x1ffff, v6
	v_and_b32_e32 v7, 0x1ffff, v7
	ds_read_b64 v[24:25], v6 offset:15384
	ds_read_b128 v[26:29], v6 offset:15632
	ds_read_b128 v[30:33], v6 offset:15888
	ds_read_u16 v34, v7 offset:15376
	v_fma_mix_f32 v14, v10, v74, 0 op_sel:[0,0,0] op_sel_hi:[0,1,0]
	v_fma_mix_f32 v61, v10, v44, 0 op_sel:[0,0,0] op_sel_hi:[0,1,0]
	v_fma_mix_f32 v14, v11, v74, v14 op_sel:[0,1,0] op_sel_hi:[0,1,0]
	v_fma_mix_f32 v61, v11, v44, v61 op_sel:[0,1,0] op_sel_hi:[0,1,0]
	v_fma_mix_f32 v14, v12, v75, v14 op_sel:[0,0,0] op_sel_hi:[0,1,0]
	v_fma_mix_f32 v61, v12, v45, v61 op_sel:[0,0,0] op_sel_hi:[0,1,0]
	v_fma_mix_f32 v14, v13, v75, v14 op_sel:[0,1,0] op_sel_hi:[0,1,0]
	v_fma_mix_f32 v16, v10, v72, 0 op_sel:[0,0,0] op_sel_hi:[0,1,0]
	v_fma_mix_f32 v17, v11, v72, 0 op_sel:[0,1,0] op_sel_hi:[0,1,0]
	v_add_f32_dpp v20, v14, v14 quad_perm:[1,0,3,2] row_mask:0xf bank_mask:0xf bound_ctrl:1
	v_fma_mix_f32 v61, v13, v45, v61 op_sel:[0,1,0] op_sel_hi:[0,1,0]
	v_fma_mix_f32 v18, v12, v73, 0 op_sel:[0,0,0] op_sel_hi:[0,1,0]
	v_add_f32_dpp v20, v20, v20 quad_perm:[2,3,0,1] row_mask:0xf bank_mask:0xf bound_ctrl:1
	v_fma_mix_f32 v19, v13, v73, 0 op_sel:[0,1,0] op_sel_hi:[0,1,0]
	v_fma_mix_f32 v16, v82, v78, v16 op_sel:[0,0,0] op_sel_hi:[1,1,0]
	v_add_f32_dpp v20, v20, v20 row_half_mirror row_mask:0xf bank_mask:0xf bound_ctrl:1
	v_fma_mix_f32 v17, v82, v78, v17 op_sel:[0,1,0] op_sel_hi:[1,1,0]
	v_fma_mix_f32 v18, v82, v79, v18 op_sel:[0,0,0] op_sel_hi:[1,1,0]
	v_add_f32_dpp v20, v20, v20 row_mirror row_mask:0xf bank_mask:0xf bound_ctrl:1
	v_fma_mix_f32 v19, v82, v79, v19 op_sel:[0,1,0] op_sel_hi:[1,1,0]
	v_fma_mix_f32 v10, v20, v76, v16 op_sel:[0,0,0] op_sel_hi:[0,1,0]
	v_fma_mix_f32 v11, v20, v76, v17 op_sel:[0,1,0] op_sel_hi:[0,1,0]
	v_fma_mix_f32 v12, v20, v77, v18 op_sel:[0,0,0] op_sel_hi:[0,1,0]
	v_fma_mix_f32 v13, v20, v77, v19 op_sel:[0,1,0] op_sel_hi:[0,1,0]
	s_waitcnt lgkmcnt(4)
	ds_read_b64 v[36:37], v6 offset:14360
	ds_read_b128 v[38:41], v6 offset:14608
	ds_read_b128 v[42:45], v6 offset:14864
	ds_read_u16 v46, v7 offset:14352
	v_fma_mix_f32 v14, v10, v86, 0 op_sel:[0,0,0] op_sel_hi:[0,1,0]
	v_fma_mix_f32 v62, v10, v80, 0 op_sel:[0,0,0] op_sel_hi:[0,1,0]
	v_fma_mix_f32 v14, v11, v86, v14 op_sel:[0,1,0] op_sel_hi:[0,1,0]
	v_fma_mix_f32 v62, v11, v80, v62 op_sel:[0,1,0] op_sel_hi:[0,1,0]
	v_fma_mix_f32 v14, v12, v87, v14 op_sel:[0,0,0] op_sel_hi:[0,1,0]
	v_fma_mix_f32 v62, v12, v81, v62 op_sel:[0,0,0] op_sel_hi:[0,1,0]
	v_fma_mix_f32 v14, v13, v87, v14 op_sel:[0,1,0] op_sel_hi:[0,1,0]
	v_fma_mix_f32 v16, v10, v84, 0 op_sel:[0,0,0] op_sel_hi:[0,1,0]
	v_fma_mix_f32 v17, v11, v84, 0 op_sel:[0,1,0] op_sel_hi:[0,1,0]
	v_add_f32_dpp v20, v14, v14 quad_perm:[1,0,3,2] row_mask:0xf bank_mask:0xf bound_ctrl:1
	v_fma_mix_f32 v62, v13, v81, v62 op_sel:[0,1,0] op_sel_hi:[0,1,0]
	v_fma_mix_f32 v18, v12, v85, 0 op_sel:[0,0,0] op_sel_hi:[0,1,0]
	v_add_f32_dpp v20, v20, v20 quad_perm:[2,3,0,1] row_mask:0xf bank_mask:0xf bound_ctrl:1
	v_fma_mix_f32 v19, v13, v85, 0 op_sel:[0,1,0] op_sel_hi:[0,1,0]
	v_fma_mix_f32 v16, v94, v90, v16 op_sel:[0,0,0] op_sel_hi:[1,1,0]
	v_add_f32_dpp v20, v20, v20 row_half_mirror row_mask:0xf bank_mask:0xf bound_ctrl:1
	v_fma_mix_f32 v17, v94, v90, v17 op_sel:[0,1,0] op_sel_hi:[1,1,0]
	v_fma_mix_f32 v18, v94, v91, v18 op_sel:[0,0,0] op_sel_hi:[1,1,0]
	v_add_f32_dpp v20, v20, v20 row_mirror row_mask:0xf bank_mask:0xf bound_ctrl:1
	v_fma_mix_f32 v19, v94, v91, v19 op_sel:[0,1,0] op_sel_hi:[1,1,0]
	v_fma_mix_f32 v10, v20, v88, v16 op_sel:[0,0,0] op_sel_hi:[0,1,0]
	v_fma_mix_f32 v11, v20, v88, v17 op_sel:[0,1,0] op_sel_hi:[0,1,0]
	v_fma_mix_f32 v12, v20, v89, v18 op_sel:[0,0,0] op_sel_hi:[0,1,0]
	v_fma_mix_f32 v13, v20, v89, v19 op_sel:[0,1,0] op_sel_hi:[0,1,0]
	s_waitcnt lgkmcnt(4)
	s_add_u32 s43, s43, 1
	s_cmp_lg_u32 s43, s45
	s_cbranch_scc1 .Lrw_blk_d1
	s_sub_u32 s15, s43, 2
	v_fma_mix_f32 v21, v10, v92, 0 op_sel:[0,0,0] op_sel_hi:[0,1,0]
	v_fma_mix_f32 v22, v12, v93, 0 op_sel:[0,0,0] op_sel_hi:[0,1,0]
	v_fma_mix_f32 v21, v11, v92, v21 op_sel:[0,1,0] op_sel_hi:[0,1,0]
	v_fma_mix_f32 v22, v13, v93, v22 op_sel:[0,1,0] op_sel_hi:[0,1,0]
	v_add_f32_e32 v63, v21, v22
	s_nop 1
	v_add_f32_dpp v48, v48, v48 row_ror:8 row_mask:0xf bank_mask:0x3
	v_add_f32_dpp v49, v49, v49 row_ror:8 row_mask:0xf bank_mask:0x3
	v_add_f32_dpp v50, v50, v50 row_ror:8 row_mask:0xf bank_mask:0x3
	v_add_f32_dpp v51, v51, v51 row_ror:8 row_mask:0xf bank_mask:0x3
	v_add_f32_dpp v52, v52, v52 row_ror:8 row_mask:0xf bank_mask:0x3
	v_add_f32_dpp v53, v53, v53 row_ror:8 row_mask:0xf bank_mask:0x3
	v_add_f32_dpp v54, v54, v54 row_ror:8 row_mask:0xf bank_mask:0x3
	v_add_f32_dpp v55, v55, v55 row_ror:8 row_mask:0xf bank_mask:0x3
	v_add_f32_dpp v48, v56, v56 row_ror:8 row_mask:0xf bank_mask:0xc
	v_add_f32_dpp v49, v57, v57 row_ror:8 row_mask:0xf bank_mask:0xc
	v_add_f32_dpp v50, v58, v58 row_ror:8 row_mask:0xf bank_mask:0xc
	v_add_f32_dpp v51, v59, v59 row_ror:8 row_mask:0xf bank_mask:0xc
	v_add_f32_dpp v52, v60, v60 row_ror:8 row_mask:0xf bank_mask:0xc
	v_add_f32_dpp v53, v61, v61 row_ror:8 row_mask:0xf bank_mask:0xc
	v_add_f32_dpp v54, v62, v62 row_ror:8 row_mask:0xf bank_mask:0xc
	v_add_f32_dpp v55, v63, v63 row_ror:8 row_mask:0xf bank_mask:0xc
	v_add_f32_dpp v48, v48, v48 row_ror:12 row_mask:0xf bank_mask:0x5
	v_add_f32_dpp v49, v49, v49 row_ror:12 row_mask:0xf bank_mask:0x5
	v_add_f32_dpp v50, v50, v50 row_ror:12 row_mask:0xf bank_mask:0x5
	v_add_f32_dpp v51, v51, v51 row_ror:12 row_mask:0xf bank_mask:0x5
	v_add_f32_dpp v48, v52, v52 row_ror:4 row_mask:0xf bank_mask:0xa
	v_add_f32_dpp v49, v53, v53 row_ror:4 row_mask:0xf bank_mask:0xa
	v_add_f32_dpp v50, v54, v54 row_ror:4 row_mask:0xf bank_mask:0xa
	v_add_f32_dpp v51, v55, v55 row_ror:4 row_mask:0xf bank_mask:0xa
	v_add_f32_dpp v64, v48, v48 quad_perm:[2,3,0,1] row_mask:0xf bank_mask:0xf bound_ctrl:1
	v_add_f32_dpp v65, v50, v50 quad_perm:[2,3,0,1] row_mask:0xf bank_mask:0xf bound_ctrl:1
	v_cndmask_b32_e64 v56, v64, v65, s[50:51]
	v_add_f32_dpp v64, v49, v49 quad_perm:[2,3,0,1] row_mask:0xf bank_mask:0xf bound_ctrl:1
	v_add_f32_dpp v65, v51, v51 quad_perm:[2,3,0,1] row_mask:0xf bank_mask:0xf bound_ctrl:1
	v_cndmask_b32_e64 v57, v64, v65, s[50:51]
	v_add_f32_dpp v64, v56, v56 quad_perm:[1,0,3,2] row_mask:0xf bank_mask:0xf bound_ctrl:1
	s_nop 0
	v_add_f32_dpp v65, v57, v57 quad_perm:[1,0,3,2] row_mask:0xf bank_mask:0xf bound_ctrl:1
	v_cndmask_b32_e64 v66, v64, v65, s[48:49]
	v_cvt_pk_bf16_f32 v66, v66, v66
	global_store_short v8, v66, s[12:13]
	s_sub_u32 s12, s12, 0x8000
	s_subb_u32 s13, s13, 0
